# norm phases: streaming stores (residual stream, H, final output) marked nt
# baseline (speedup 1.0000x reference)
.LBB0_425:
	v_and_b32_e32 v4, 64, v161
	v_add_u32_e32 v94, 64, v4
	v_mul_f32_e32 v4, v85, v85
	v_pk_fma_f32 v[88:89], v[84:85], v[84:85], v[4:5] op_sel_hi:[1,1,0]
	v_pk_mul_f32 v[80:81], v[80:81], v[80:81]
	v_mul_f32_e32 v4, v91, v91
	v_pk_fma_f32 v[80:81], v[86:87], v[86:87], v[80:81]
	v_pk_fma_f32 v[86:87], v[90:91], v[90:91], v[4:5] op_sel_hi:[1,1,0]
	v_mov_b32_e32 v92, v88
	v_mov_b32_e32 v78, v86
	v_mov_b32_e32 v93, v79
	v_pk_add_f32 v[86:87], v[86:87], v[88:89]
	v_pk_mul_f32 v[78:79], v[78:79], v[92:93]
	v_mul_f32_e32 v48, v33, v33
	v_mov_b32_e32 v87, v79
	v_pk_add_f32 v[78:79], v[80:81], v[80:81] op_sel:[0,1] op_sel_hi:[1,0]
	v_mul_f32_e32 v4, v35, v35
	v_mov_b32_e32 v79, v48
	v_pk_fma_f32 v[80:81], v[34:35], v[34:35], v[4:5] op_sel_hi:[1,1,0]
	v_mul_f32_e32 v4, v31, v31
	v_pk_add_f32 v[78:79], v[86:87], v[78:79]
	v_pk_fma_f32 v[86:87], v[30:31], v[30:31], v[4:5] op_sel_hi:[1,1,0]
	v_xor_b32_e32 v4, 32, v161
	v_cmp_lt_i32_e32 vcc, v4, v94
	v_mul_f32_e32 v60, v28, v28
	v_mul_f32_e32 v95, v29, v29
	v_cndmask_b32_e32 v4, v161, v4, vcc
	v_lshlrev_b32_e32 v88, 2, v4
	v_xor_b32_e32 v4, 16, v161
	v_cmp_lt_i32_e32 vcc, v4, v94
	v_mov_b32_e32 v81, v60
	v_mov_b32_e32 v87, v95
	v_cndmask_b32_e32 v4, v161, v4, vcc
	v_pk_add_f32 v[80:81], v[80:81], v[86:87]
	v_lshlrev_b32_e32 v89, 2, v4
	v_mul_f32_e32 v4, v69, v69
	v_pk_add_f32 v[78:79], v[78:79], v[80:81]
	v_pk_fma_f32 v[80:81], v[68:69], v[68:69], v[4:5] op_sel_hi:[1,1,0]
	v_pk_mul_f32 v[70:71], v[70:71], v[70:71]
	v_mul_f32_e32 v4, v75, v75
	v_pk_fma_f32 v[70:71], v[72:73], v[72:73], v[70:71]
	v_pk_fma_f32 v[72:73], v[74:75], v[74:75], v[4:5] op_sel_hi:[1,1,0]
	v_mov_b32_e32 v86, v80
	v_mov_b32_e32 v60, v72
	v_mov_b32_e32 v87, v61
	v_pk_add_f32 v[72:73], v[72:73], v[80:81]
	v_pk_mul_f32 v[60:61], v[60:61], v[86:87]
	v_xor_b32_e32 v48, 8, v161
	v_mul_f32_e32 v92, v25, v25
	v_mov_b32_e32 v73, v61
	v_pk_add_f32 v[60:61], v[70:71], v[70:71] op_sel:[0,1] op_sel_hi:[1,0]
	v_mul_f32_e32 v4, v27, v27
	v_mov_b32_e32 v61, v92
	v_pk_fma_f32 v[70:71], v[26:27], v[26:27], v[4:5] op_sel_hi:[1,1,0]
	v_mul_f32_e32 v4, v23, v23
	v_cmp_lt_i32_e32 vcc, v48, v94
	v_pk_add_f32 v[60:61], v[72:73], v[60:61]
	v_pk_fma_f32 v[72:73], v[22:23], v[22:23], v[4:5] op_sel_hi:[1,1,0]
	v_cndmask_b32_e32 v4, v161, v48, vcc
	v_lshlrev_b32_e32 v80, 2, v4
	v_xor_b32_e32 v4, 4, v161
	v_cmp_lt_i32_e32 vcc, v4, v94
	v_mul_f32_e32 v93, v18, v18
	v_mul_f32_e32 v95, v19, v19
	v_cndmask_b32_e32 v4, v161, v4, vcc
	v_lshlrev_b32_e32 v81, 2, v4
	v_xor_b32_e32 v4, 2, v161
	v_cmp_lt_i32_e32 vcc, v4, v94
	v_mov_b32_e32 v71, v93
	v_mov_b32_e32 v73, v95
	v_cndmask_b32_e32 v4, v161, v4, vcc
	v_pk_add_f32 v[70:71], v[70:71], v[72:73]
	v_lshlrev_b32_e32 v86, 2, v4
	v_mul_f32_e32 v4, v51, v51
	v_pk_add_f32 v[60:61], v[60:61], v[70:71]
	v_pk_fma_f32 v[72:73], v[50:51], v[50:51], v[4:5] op_sel_hi:[1,1,0]
	v_pk_mul_f32 v[56:57], v[56:57], v[56:57]
	v_mul_f32_e32 v4, v63, v63
	v_mov_b32_e32 v70, v60
	v_mov_b32_e32 v71, v78
	v_mov_b32_e32 v78, v61
	v_pk_fma_f32 v[56:57], v[58:59], v[58:59], v[56:57]
	v_pk_fma_f32 v[58:59], v[62:63], v[62:63], v[4:5] op_sel_hi:[1,1,0]
	v_pk_add_f32 v[60:61], v[70:71], v[78:79]
	v_mov_b32_e32 v48, v58
	v_mov_b32_e32 v78, v72
	v_mov_b32_e32 v79, v49
	v_pk_add_f32 v[58:59], v[58:59], v[72:73]
	v_pk_mul_f32 v[48:49], v[48:49], v[78:79]
	v_mul_f32_e32 v92, v17, v17
	v_mov_b32_e32 v59, v49
	v_pk_add_f32 v[48:49], v[56:57], v[56:57] op_sel:[0,1] op_sel_hi:[1,0]
	v_mul_f32_e32 v4, v21, v21
	v_mov_b32_e32 v49, v92
	v_pk_fma_f32 v[56:57], v[20:21], v[20:21], v[4:5] op_sel_hi:[1,1,0]
	v_mul_f32_e32 v4, v15, v15
	v_mul_f32_e32 v93, v10, v10
	v_mul_f32_e32 v95, v11, v11
	v_pk_add_f32 v[48:49], v[58:59], v[48:49]
	v_pk_fma_f32 v[58:59], v[14:15], v[14:15], v[4:5] op_sel_hi:[1,1,0]
	v_mov_b32_e32 v57, v93
	v_mov_b32_e32 v59, v95
	v_pk_add_f32 v[56:57], v[56:57], v[58:59]
	v_mul_f32_e32 v4, v41, v41
	v_pk_add_f32 v[48:49], v[48:49], v[56:57]
	v_pk_fma_f32 v[56:57], v[40:41], v[40:41], v[4:5] op_sel_hi:[1,1,0]
	v_pk_mul_f32 v[52:53], v[52:53], v[52:53]
	v_mul_f32_e32 v4, v43, v43
	v_pk_fma_f32 v[52:53], v[54:55], v[54:55], v[52:53]
	v_pk_fma_f32 v[54:55], v[42:43], v[42:43], v[4:5] op_sel_hi:[1,1,0]
	v_mov_b32_e32 v58, v56
	v_mov_b32_e32 v4, v54
	v_mov_b32_e32 v59, v5
	v_pk_add_f32 v[54:55], v[54:55], v[56:57]
	v_pk_mul_f32 v[4:5], v[4:5], v[58:59]
	v_mul_f32_e32 v72, v9, v9
	v_mov_b32_e32 v55, v5
	v_pk_add_f32 v[4:5], v[52:53], v[52:53] op_sel:[0,1] op_sel_hi:[1,0]
	ds_bpermute_b32 v71, v88, v61
	v_mov_b32_e32 v5, v72
	ds_bpermute_b32 v70, v88, v60
	v_pk_add_f32 v[4:5], v[54:55], v[4:5]
	v_mul_f32_e32 v52, v13, v13
	v_mul_f32_e32 v54, v7, v7
	v_mul_f32_e32 v73, v2, v2
	v_mul_f32_e32 v78, v3, v3
	v_pk_fma_f32 v[52:53], v[12:13], v[12:13], v[52:53] op_sel_hi:[1,1,0]
	v_pk_fma_f32 v[54:55], v[6:7], v[6:7], v[54:55] op_sel_hi:[1,1,0]
	v_mov_b32_e32 v53, v73
	v_mov_b32_e32 v55, v78
	v_pk_add_f32 v[52:53], v[52:53], v[54:55]
	s_waitcnt lgkmcnt(0)
	v_pk_add_f32 v[60:61], v[60:61], v[70:71]
	v_pk_add_f32 v[4:5], v[4:5], v[52:53]
	v_mov_b32_e32 v53, v48
	v_mov_b32_e32 v52, v4
	v_mov_b32_e32 v48, v5
	ds_bpermute_b32 v71, v89, v61
	ds_bpermute_b32 v70, v89, v60
	v_pk_add_f32 v[4:5], v[52:53], v[48:49]
	ds_bpermute_b32 v49, v88, v5
	ds_bpermute_b32 v48, v88, v4
	v_xor_b32_e32 v87, 1, v161
	s_waitcnt lgkmcnt(2)
	v_pk_add_f32 v[60:61], v[60:61], v[70:71]
	ds_bpermute_b32 v71, v80, v61
	ds_bpermute_b32 v70, v80, v60
	s_waitcnt lgkmcnt(2)
	v_pk_add_f32 v[4:5], v[4:5], v[48:49]
	ds_bpermute_b32 v49, v89, v5
	ds_bpermute_b32 v48, v89, v4
	v_cmp_lt_i32_e32 vcc, v87, v94
	s_waitcnt lgkmcnt(2)
	v_pk_add_f32 v[60:61], v[60:61], v[70:71]
	ds_bpermute_b32 v71, v81, v61
	ds_bpermute_b32 v70, v81, v60
	s_waitcnt lgkmcnt(2)
	v_pk_add_f32 v[4:5], v[4:5], v[48:49]
	ds_bpermute_b32 v49, v80, v5
	ds_bpermute_b32 v48, v80, v4
	v_cndmask_b32_e32 v56, v161, v87, vcc
	s_waitcnt lgkmcnt(2)
	v_pk_add_f32 v[52:53], v[60:61], v[70:71]
	ds_bpermute_b32 v55, v86, v53
	ds_bpermute_b32 v54, v86, v52
	s_waitcnt lgkmcnt(2)
	v_pk_add_f32 v[4:5], v[4:5], v[48:49]
	ds_bpermute_b32 v49, v81, v5
	ds_bpermute_b32 v48, v81, v4
	v_lshlrev_b32_e32 v56, 2, v56
	s_waitcnt lgkmcnt(2)
	v_pk_add_f32 v[52:53], v[52:53], v[54:55]
	ds_bpermute_b32 v55, v56, v53
	ds_bpermute_b32 v54, v56, v52
	s_waitcnt lgkmcnt(2)
	v_pk_add_f32 v[4:5], v[4:5], v[48:49]
	ds_bpermute_b32 v49, v86, v5
	ds_bpermute_b32 v48, v86, v4
	s_waitcnt lgkmcnt(2)
	v_pk_add_f32 v[52:53], v[52:53], v[54:55]
	v_mov_b64_e32 v[54:55], s[48:49]
	v_pk_fma_f32 v[52:53], v[52:53], s[50:51], v[54:55] op_sel_hi:[1,0,0]
	s_waitcnt lgkmcnt(0)
	v_pk_add_f32 v[4:5], v[4:5], v[48:49]
	v_mul_f32_e32 v57, 0x4b800000, v53
	v_cmp_gt_f32_e32 vcc, s77, v53
	ds_bpermute_b32 v49, v56, v5
	ds_bpermute_b32 v48, v56, v4
	v_cndmask_b32_e32 v53, v53, v57, vcc
	v_rsq_f32_e32 v53, v53
	v_mul_f32_e32 v57, 0x4b800000, v52
	v_cmp_gt_f32_e64 s[4:5], s77, v52
	s_waitcnt lgkmcnt(0)
	v_pk_add_f32 v[4:5], v[4:5], v[48:49]
	v_mul_f32_e32 v56, 0x45800000, v53
	v_pk_fma_f32 v[4:5], v[4:5], s[50:51], v[54:55] op_sel_hi:[1,0,0]
	v_cndmask_b32_e32 v58, v53, v56, vcc
	v_mul_f32_e32 v48, 0x4b800000, v5
	v_cmp_gt_f32_e32 vcc, s77, v5
	v_cndmask_b32_e64 v52, v52, v57, s[4:5]
	v_cmp_gt_f32_e64 s[6:7], s77, v4
	v_cndmask_b32_e32 v5, v5, v48, vcc
	v_mul_f32_e32 v48, 0x4b800000, v4
	v_rsq_f32_e32 v52, v52
	v_rsq_f32_e32 v5, v5
	v_cndmask_b32_e64 v4, v4, v48, s[6:7]
	v_rsq_f32_e32 v4, v4
	v_mul_f32_e32 v53, 0x45800000, v52
	v_mul_f32_e32 v48, 0x45800000, v5
	v_cndmask_b32_e64 v54, v52, v53, s[4:5]
	v_cndmask_b32_e32 v48, v5, v48, vcc
	v_mul_f32_e32 v5, 0x45800000, v4
	s_lshl_b64 s[4:5], s[62:63], 12
	v_cndmask_b32_e64 v4, v4, v5, s[6:7]
	s_add_u32 s6, s70, s4
	s_addc_u32 s7, s71, s5
	s_add_u32 s4, s6, 0x4000
	s_addc_u32 s5, s7, 0
	v_lshl_add_u64 v[52:53], s[6:7], 0, v[98:99]
	v_add_co_u32_e32 v56, vcc, s76, v52
	global_load_dwordx4 v[70:73], v98, s[4:5] offset:16
	global_load_dwordx4 v[78:81], v98, s[4:5]
	global_load_dwordx4 v[86:89], v[106:107], off offset:16
	global_load_dwordx4 v[92:95], v[106:107], off
	v_addc_co_u32_e32 v57, vcc, 0, v53, vcc
	v_lshl_add_u64 v[96:97], v[52:53], 0, s[44:45]
	global_load_dwordx4 v[118:121], v[56:57], off
	global_load_dwordx4 v[122:125], v[96:97], off offset:16
	v_pk_mul_f32 v[60:61], v[90:91], v[58:59] op_sel_hi:[1,0]
	v_pk_mul_f32 v[84:85], v[84:85], v[58:59] op_sel_hi:[1,0]
	v_pk_mul_f32 v[82:83], v[82:83], v[58:59] op_sel_hi:[1,0]
	v_pk_mul_f32 v[76:77], v[76:77], v[58:59] op_sel_hi:[1,0]
	v_pk_mul_f32 v[66:67], v[66:67], v[54:55] op_sel_hi:[1,0]
	v_pk_mul_f32 v[64:65], v[64:65], v[54:55] op_sel_hi:[1,0]
	v_pk_mul_f32 v[46:47], v[46:47], v[48:49] op_sel_hi:[1,0]
	v_pk_mul_f32 v[90:91], v[44:45], v[48:49] op_sel_hi:[1,0]
	v_pk_mul_f32 v[38:39], v[38:39], v[4:5] op_sel_hi:[1,0]
	v_pk_mul_f32 v[36:37], v[36:37], v[4:5] op_sel_hi:[1,0]
	v_lshl_add_u64 v[52:53], v[114:115], 0, s[60:61]
	v_pk_mul_f32 v[74:75], v[74:75], v[54:55] op_sel_hi:[1,0]
	v_pk_mul_f32 v[68:69], v[68:69], v[54:55] op_sel_hi:[1,0]
	v_lshl_add_u64 v[56:57], v[114:115], 0, s[64:65]
	v_pk_mul_f32 v[62:63], v[62:63], v[48:49] op_sel_hi:[1,0]
	v_pk_mul_f32 v[50:51], v[50:51], v[48:49] op_sel_hi:[1,0]
	v_lshl_add_u64 v[44:45], v[114:115], 0, s[66:67]
	v_pk_mul_f32 v[42:43], v[42:43], v[4:5] op_sel_hi:[1,0]
	v_pk_mul_f32 v[40:41], v[40:41], v[4:5] op_sel_hi:[1,0]
	v_lshl_add_u64 v[126:127], v[114:115], 0, s[68:69]
	v_pk_mul_f32 v[12:13], v[12:13], v[4:5] op_sel_hi:[1,0]
	v_pk_mul_f32 v[6:7], v[6:7], v[4:5] op_sel_hi:[1,0]
	v_pk_mul_f32 v[8:9], v[8:9], v[4:5] op_sel_hi:[1,0]
	v_pk_mul_f32 v[2:3], v[2:3], v[4:5] op_sel_hi:[1,0]
	v_pk_mul_f32 v[34:35], v[34:35], v[58:59] op_sel_hi:[1,0]
	v_pk_mul_f32 v[30:31], v[30:31], v[58:59] op_sel_hi:[1,0]
	v_pk_mul_f32 v[32:33], v[32:33], v[58:59] op_sel_hi:[1,0]
	v_pk_mul_f32 v[28:29], v[28:29], v[58:59] op_sel_hi:[1,0]
	v_pk_mul_f32 v[26:27], v[26:27], v[54:55] op_sel_hi:[1,0]
	v_pk_mul_f32 v[22:23], v[22:23], v[54:55] op_sel_hi:[1,0]
	v_pk_mul_f32 v[20:21], v[20:21], v[48:49] op_sel_hi:[1,0]
	v_pk_mul_f32 v[14:15], v[14:15], v[48:49] op_sel_hi:[1,0]
	v_pk_mul_f32 v[24:25], v[24:25], v[54:55] op_sel_hi:[1,0]
	v_pk_mul_f32 v[18:19], v[18:19], v[54:55] op_sel_hi:[1,0]
	v_pk_mul_f32 v[16:17], v[16:17], v[48:49] op_sel_hi:[1,0]
	v_pk_mul_f32 v[10:11], v[10:11], v[48:49] op_sel_hi:[1,0]
	s_add_i32 s49, s49, s72
	s_add_i32 s20, s20, s73
	s_cmpk_lt_i32 s49, 0x2200
	s_waitcnt vmcnt(5)
	v_pk_add_f32 v[72:73], v[72:73], 1.0 op_sel_hi:[1,0]
	s_waitcnt vmcnt(4)
	v_pk_add_f32 v[80:81], v[80:81], 1.0 op_sel_hi:[1,0]
	v_pk_add_f32 v[78:79], v[78:79], 1.0 op_sel_hi:[1,0]
	v_pk_add_f32 v[70:71], v[70:71], 1.0 op_sel_hi:[1,0]
	s_waitcnt vmcnt(2)
	v_pk_mul_f32 v[80:81], v[94:95], v[80:81]
	v_pk_mul_f32 v[78:79], v[92:93], v[78:79]
	v_pk_mul_f32 v[72:73], v[88:89], v[72:73]
	v_pk_mul_f32 v[70:71], v[86:87], v[70:71]
	s_waitcnt vmcnt(1)
	v_pk_fma_f32 v[84:85], v[84:85], v[80:81], v[120:121]
	v_pk_fma_f32 v[60:61], v[60:61], v[78:79], v[118:119]
	s_waitcnt vmcnt(0)
	v_pk_fma_f32 v[76:77], v[76:77], v[72:73], v[124:125]
	v_pk_fma_f32 v[82:83], v[82:83], v[70:71], v[122:123]
	v_pk_fma_f32 v[64:65], v[64:65], v[72:73], v[124:125]
	v_pk_fma_f32 v[66:67], v[66:67], v[70:71], v[122:123]
	v_pk_fma_f32 v[86:87], v[90:91], v[72:73], v[124:125]
	v_pk_fma_f32 v[46:47], v[46:47], v[70:71], v[122:123]
	v_pk_fma_f32 v[72:73], v[72:73], v[36:37], v[124:125]
	v_pk_fma_f32 v[70:71], v[70:71], v[38:39], v[122:123]
	v_cvt_pk_bf16_f32 v36, v60, v61
	v_cvt_pk_bf16_f32 v37, v84, v85
	v_cvt_pk_bf16_f32 v38, v82, v83
	v_cvt_pk_bf16_f32 v39, v76, v77
	v_pk_fma_f32 v[68:69], v[68:69], v[80:81], v[120:121]
	v_pk_fma_f32 v[74:75], v[74:75], v[78:79], v[118:119]
	global_store_dwordx4 v[52:53], v[36:39], off nt
	v_pk_fma_f32 v[50:51], v[80:81], v[50:51], v[120:121]
	v_pk_fma_f32 v[62:63], v[78:79], v[62:63], v[118:119]
	v_cvt_pk_bf16_f32 v36, v74, v75
	v_cvt_pk_bf16_f32 v37, v68, v69
	v_cvt_pk_bf16_f32 v38, v66, v67
	v_cvt_pk_bf16_f32 v39, v64, v65
	global_store_dwordx4 v[56:57], v[36:39], off nt
	v_pk_fma_f32 v[40:41], v[80:81], v[40:41], v[120:121]
	v_pk_fma_f32 v[42:43], v[78:79], v[42:43], v[118:119]
	v_cvt_pk_bf16_f32 v36, v62, v63
	v_cvt_pk_bf16_f32 v37, v50, v51
	v_cvt_pk_bf16_f32 v38, v46, v47
	v_cvt_pk_bf16_f32 v39, v86, v87
	global_store_dwordx4 v[44:45], v[36:39], off nt
	s_nop 1
	v_cvt_pk_bf16_f32 v36, v42, v43
	v_cvt_pk_bf16_f32 v37, v40, v41
	v_cvt_pk_bf16_f32 v38, v70, v71
	v_cvt_pk_bf16_f32 v39, v72, v73
	global_store_dwordx4 v[126:127], v[36:39], off nt
	global_load_dwordx4 v[36:39], v117, s[4:5]
	s_nop 0
	global_load_dwordx4 v[40:43], v117, s[4:5] offset:16
	global_load_dwordx4 v[60:63], v[108:109], off
	global_load_dwordx4 v[64:67], v[108:109], off offset:16
	global_load_dwordx4 v[68:71], v[96:97], off offset:2048
	global_load_dwordx4 v[72:75], v[96:97], off offset:2064
	s_waitcnt vmcnt(5)
	v_pk_add_f32 v[4:5], v[38:39], 1.0 op_sel_hi:[1,0]
	v_pk_add_f32 v[36:37], v[36:37], 1.0 op_sel_hi:[1,0]
	s_waitcnt vmcnt(4)
	v_pk_add_f32 v[38:39], v[42:43], 1.0 op_sel_hi:[1,0]
	v_pk_add_f32 v[40:41], v[40:41], 1.0 op_sel_hi:[1,0]
	s_waitcnt vmcnt(3)
	v_pk_mul_f32 v[4:5], v[62:63], v[4:5]
	v_pk_mul_f32 v[36:37], v[60:61], v[36:37]
	s_waitcnt vmcnt(2)
	v_pk_mul_f32 v[38:39], v[66:67], v[38:39]
	v_pk_mul_f32 v[40:41], v[64:65], v[40:41]
	s_waitcnt vmcnt(1)
	v_pk_fma_f32 v[30:31], v[30:31], v[4:5], v[70:71]
	v_pk_fma_f32 v[34:35], v[34:35], v[36:37], v[68:69]
	s_waitcnt vmcnt(0)
	v_pk_fma_f32 v[28:29], v[28:29], v[38:39], v[74:75]
	v_pk_fma_f32 v[32:33], v[32:33], v[40:41], v[72:73]
	v_pk_fma_f32 v[22:23], v[22:23], v[4:5], v[70:71]
	v_pk_fma_f32 v[26:27], v[26:27], v[36:37], v[68:69]
	v_pk_fma_f32 v[14:15], v[14:15], v[4:5], v[70:71]
	v_pk_fma_f32 v[20:21], v[20:21], v[36:37], v[68:69]
	v_pk_fma_f32 v[6:7], v[6:7], v[4:5], v[70:71]
	v_pk_fma_f32 v[12:13], v[12:13], v[36:37], v[68:69]
	v_pk_fma_f32 v[36:37], v[2:3], v[38:39], v[74:75]
	v_cvt_pk_bf16_f32 v2, v34, v35
	v_cvt_pk_bf16_f32 v3, v30, v31
	v_cvt_pk_bf16_f32 v4, v32, v33
	v_cvt_pk_bf16_f32 v5, v28, v29
	v_pk_fma_f32 v[18:19], v[18:19], v[38:39], v[74:75]
	v_pk_fma_f32 v[24:25], v[24:25], v[40:41], v[72:73]
	global_store_dwordx4 v[52:53], v[2:5], off offset:1024 nt
	v_pk_fma_f32 v[10:11], v[10:11], v[38:39], v[74:75]
	v_pk_fma_f32 v[16:17], v[16:17], v[40:41], v[72:73]
	v_cvt_pk_bf16_f32 v2, v26, v27
	v_cvt_pk_bf16_f32 v3, v22, v23
	v_cvt_pk_bf16_f32 v4, v24, v25
	v_cvt_pk_bf16_f32 v5, v18, v19
	global_store_dwordx4 v[56:57], v[2:5], off offset:1024 nt
	v_pk_fma_f32 v[8:9], v[8:9], v[40:41], v[72:73]
	s_nop 0
	v_cvt_pk_bf16_f32 v2, v20, v21
	v_cvt_pk_bf16_f32 v3, v14, v15
	v_cvt_pk_bf16_f32 v4, v16, v17
	v_cvt_pk_bf16_f32 v5, v10, v11
	global_store_dwordx4 v[44:45], v[2:5], off offset:1024 nt
	s_nop 1
	v_cvt_pk_bf16_f32 v2, v12, v13
	v_cvt_pk_bf16_f32 v3, v6, v7
	v_cvt_pk_bf16_f32 v4, v8, v9
	v_cvt_pk_bf16_f32 v5, v36, v37
	global_store_dwordx4 v[126:127], v[2:5], off offset:1024 nt
	s_cbranch_scc0 .LBB0_434

.LBB0_430:
	v_fmamk_f32 v121, v121, 0x3a800000, v116
	v_mul_f32_e32 v122, 0x4b800000, v121
	v_cmp_gt_f32_e32 vcc, s77, v121
	s_min_i32 s4, s49, 0x2000
	s_ashr_i32 s4, s4, 10
	v_cndmask_b32_e32 v121, v121, v122, vcc
	v_rsq_f32_e32 v121, v121
	v_mul_f32_e32 v124, 0.5, v120
	v_mul_f32_e32 v120, 0.5, v118
	v_mul_f32_e32 v122, 0x45800000, v121
	v_cndmask_b32_e32 v121, v121, v122, vcc
	v_mul_f32_e32 v122, 0.5, v119
	v_mul_f32_e32 v118, 0.5, v121
	s_mul_i32 s62, s4, 9
	s_ashr_i32 s63, s62, 31
	s_lshl_b64 s[4:5], s[62:63], 12
	s_add_u32 s4, s70, s4
	s_addc_u32 s5, s71, s5
	s_add_u32 s4, s4, 0x2000
	s_addc_u32 s5, s5, 0
	global_load_dwordx4 v[126:129], v[102:103], off
	global_load_dwordx4 v[130:133], v98, s[4:5]
	global_load_dwordx4 v[134:137], v98, s[4:5] offset:16
	global_load_dwordx4 v[138:141], v[102:103], off offset:16
	global_load_dwordx4 v[142:145], v117, s[4:5]
	global_load_dwordx4 v[146:149], v[104:105], off
	global_load_dwordx4 v[150:153], v[104:105], off offset:16
	global_load_dwordx4 v[154:157], v117, s[4:5] offset:16
	v_lshlrev_b32_e32 v162, 16, v68
	v_and_b32_e32 v163, 0xffff0000, v68
	v_lshlrev_b32_e32 v158, 16, v66
	v_and_b32_e32 v159, 0xffff0000, v66
	v_lshlrev_b32_e32 v66, 16, v67
	v_and_b32_e32 v67, 0xffff0000, v67
	v_lshlrev_b32_e32 v164, 16, v74
	v_and_b32_e32 v165, 0xffff0000, v74
	v_lshlrev_b32_e32 v74, 16, v75
	v_and_b32_e32 v75, 0xffff0000, v75
	v_lshlrev_b32_e32 v166, 16, v76
	v_and_b32_e32 v167, 0xffff0000, v76
	v_lshlrev_b32_e32 v76, 16, v77
	v_and_b32_e32 v77, 0xffff0000, v77
	v_lshlrev_b32_e32 v168, 16, v82
	v_and_b32_e32 v169, 0xffff0000, v82
	v_lshlrev_b32_e32 v82, 16, v83
	v_and_b32_e32 v83, 0xffff0000, v83
	v_lshlrev_b32_e32 v170, 16, v84
	v_and_b32_e32 v171, 0xffff0000, v84
	v_lshlrev_b32_e32 v84, 16, v85
	v_and_b32_e32 v85, 0xffff0000, v85
	v_lshlrev_b32_e32 v174, 16, v92
	v_and_b32_e32 v175, 0xffff0000, v92
	v_pk_mul_f32 v[162:163], v[124:125], v[162:163] op_sel_hi:[0,1]
	v_lshlrev_b32_e32 v176, 16, v70
	v_and_b32_e32 v177, 0xffff0000, v70
	v_pk_mul_f32 v[66:67], v[124:125], v[66:67] op_sel_hi:[0,1]
	v_pk_mul_f32 v[178:179], v[122:123], v[74:75] op_sel_hi:[0,1]
	v_pk_mul_f32 v[74:75], v[122:123], v[164:165] op_sel_hi:[0,1]
	v_pk_mul_f32 v[164:165], v[122:123], v[76:77] op_sel_hi:[0,1]
	v_pk_mul_f32 v[180:181], v[120:121], v[82:83] op_sel_hi:[0,1]
	v_pk_mul_f32 v[182:183], v[120:121], v[84:85] op_sel_hi:[0,1]
	v_pk_mul_f32 v[174:175], v[118:119], v[174:175] op_sel_hi:[0,1]
	v_lshlrev_b32_e32 v172, 16, v90
	v_and_b32_e32 v173, 0xffff0000, v90
	v_lshlrev_b32_e32 v90, 16, v91
	v_and_b32_e32 v91, 0xffff0000, v91
	v_pk_mul_f32 v[158:159], v[124:125], v[158:159] op_sel_hi:[0,1]
	v_pk_mul_f32 v[168:169], v[120:121], v[168:169] op_sel_hi:[0,1]
	v_pk_mul_f32 v[184:185], v[118:119], v[90:91] op_sel_hi:[0,1]
	v_lshlrev_b32_e32 v68, 16, v69
	v_and_b32_e32 v69, 0xffff0000, v69
	v_lshlrev_b32_e32 v92, 16, v93
	v_and_b32_e32 v93, 0xffff0000, v93
	v_pk_mul_f32 v[68:69], v[124:125], v[68:69] op_sel_hi:[0,1]
	v_pk_mul_f32 v[166:167], v[122:123], v[166:167] op_sel_hi:[0,1]
	v_pk_mul_f32 v[170:171], v[120:121], v[170:171] op_sel_hi:[0,1]
	v_pk_mul_f32 v[172:173], v[118:119], v[172:173] op_sel_hi:[0,1]
	v_pk_mul_f32 v[92:93], v[118:119], v[92:93] op_sel_hi:[0,1]
	s_mov_b64 s[4:5], -1
	s_and_b64 vcc, exec, s[60:61]
	s_waitcnt vmcnt(0)
	v_pk_mul_f32 v[128:129], v[132:133], v[128:129]
	v_pk_mul_f32 v[126:127], v[130:131], v[126:127]
	v_pk_mul_f32 v[132:133], v[134:135], v[138:139]
	v_pk_mul_f32 v[130:131], v[136:137], v[140:141]
	v_pk_fma_f32 v[82:83], v[162:163], v[132:133], v[34:35]
	v_lshlrev_b32_e32 v34, 16, v71
	v_and_b32_e32 v35, 0xffff0000, v71
	v_pk_mul_f32 v[134:135], v[144:145], v[148:149]
	v_pk_mul_f32 v[136:137], v[142:143], v[146:147]
	v_pk_fma_f32 v[84:85], v[128:129], v[66:67], v[64:65]
	v_pk_fma_f32 v[74:75], v[74:75], v[126:127], v[38:39]
	v_pk_fma_f32 v[64:65], v[164:165], v[130:131], v[44:45]
	v_pk_fma_f32 v[44:45], v[182:183], v[130:131], v[48:49]
	v_pk_fma_f32 v[38:39], v[174:175], v[132:133], v[54:55]
	v_lshlrev_b32_e32 v48, 16, v72
	v_and_b32_e32 v49, 0xffff0000, v72
	v_pk_mul_f32 v[54:55], v[124:125], v[34:35] op_sel_hi:[0,1]
	v_pk_mul_f32 v[34:35], v[124:125], v[176:177] op_sel_hi:[0,1]
	v_pk_mul_f32 v[140:141], v[154:155], v[150:151]
	v_pk_fma_f32 v[90:91], v[126:127], v[158:159], v[62:63]
	v_pk_fma_f32 v[62:63], v[168:169], v[126:127], v[50:51]
	v_pk_fma_f32 v[50:51], v[180:181], v[128:129], v[52:53]
	v_lshlrev_b32_e32 v52, 16, v73
	v_and_b32_e32 v53, 0xffff0000, v73
	v_pk_fma_f32 v[34:35], v[34:35], v[136:137], v[30:31]
	v_pk_fma_f32 v[30:31], v[54:55], v[134:135], v[32:33]
	v_pk_mul_f32 v[32:33], v[124:125], v[48:49] op_sel_hi:[0,1]
	v_pk_mul_f32 v[138:139], v[156:157], v[152:153]
	v_pk_mul_f32 v[52:53], v[124:125], v[52:53] op_sel_hi:[0,1]
	v_pk_fma_f32 v[32:33], v[32:33], v[140:141], v[26:27]
	v_lshlrev_b32_e32 v26, 16, v78
	v_and_b32_e32 v27, 0xffff0000, v78
	v_lshlrev_b32_e32 v48, 16, v79
	v_and_b32_e32 v49, 0xffff0000, v79
	v_pk_fma_f32 v[28:29], v[52:53], v[138:139], v[28:29]
	v_lshlrev_b32_e32 v52, 16, v80
	v_and_b32_e32 v53, 0xffff0000, v80
	v_lshlrev_b32_e32 v54, 16, v81
	v_and_b32_e32 v55, 0xffff0000, v81
	v_pk_mul_f32 v[48:49], v[122:123], v[48:49] op_sel_hi:[0,1]
	v_pk_mul_f32 v[26:27], v[122:123], v[26:27] op_sel_hi:[0,1]
	v_pk_fma_f32 v[26:27], v[26:27], v[136:137], v[22:23]
	v_pk_fma_f32 v[22:23], v[48:49], v[134:135], v[24:25]
	v_pk_mul_f32 v[48:49], v[122:123], v[54:55] op_sel_hi:[0,1]
	v_pk_mul_f32 v[24:25], v[122:123], v[52:53] op_sel_hi:[0,1]
	v_pk_fma_f32 v[24:25], v[24:25], v[140:141], v[18:19]
	v_pk_fma_f32 v[18:19], v[48:49], v[138:139], v[20:21]
	v_lshlrev_b32_e32 v20, 16, v86
	v_and_b32_e32 v21, 0xffff0000, v86
	v_lshlrev_b32_e32 v48, 16, v87
	v_and_b32_e32 v49, 0xffff0000, v87
	v_lshlrev_b32_e32 v52, 16, v88
	v_and_b32_e32 v53, 0xffff0000, v88
	v_lshlrev_b32_e32 v54, 16, v89
	v_and_b32_e32 v55, 0xffff0000, v89
	v_pk_mul_f32 v[48:49], v[120:121], v[48:49] op_sel_hi:[0,1]
	v_pk_mul_f32 v[20:21], v[120:121], v[20:21] op_sel_hi:[0,1]
	v_pk_fma_f32 v[20:21], v[20:21], v[136:137], v[14:15]
	v_pk_fma_f32 v[14:15], v[48:49], v[134:135], v[16:17]
	v_pk_mul_f32 v[48:49], v[120:121], v[54:55] op_sel_hi:[0,1]
	v_pk_mul_f32 v[16:17], v[120:121], v[52:53] op_sel_hi:[0,1]
	v_pk_fma_f32 v[16:17], v[16:17], v[140:141], v[10:11]
	v_pk_fma_f32 v[10:11], v[48:49], v[138:139], v[12:13]
	v_lshlrev_b32_e32 v12, 16, v94
	v_and_b32_e32 v13, 0xffff0000, v94
	v_lshlrev_b32_e32 v48, 16, v95
	v_and_b32_e32 v49, 0xffff0000, v95
	v_lshlrev_b32_e32 v52, 16, v96
	v_and_b32_e32 v53, 0xffff0000, v96
	v_pk_mul_f32 v[48:49], v[118:119], v[48:49] op_sel_hi:[0,1]
	v_pk_mul_f32 v[12:13], v[118:119], v[12:13] op_sel_hi:[0,1]
	v_lshlrev_b32_e32 v54, 16, v97
	v_and_b32_e32 v55, 0xffff0000, v97
	v_pk_fma_f32 v[12:13], v[12:13], v[136:137], v[6:7]
	v_pk_fma_f32 v[6:7], v[48:49], v[134:135], v[8:9]
	v_pk_mul_f32 v[8:9], v[118:119], v[52:53] op_sel_hi:[0,1]
	v_pk_mul_f32 v[48:49], v[118:119], v[54:55] op_sel_hi:[0,1]
	v_pk_fma_f32 v[8:9], v[8:9], v[140:141], v[2:3]
	v_pk_fma_f32 v[76:77], v[68:69], v[130:131], v[36:37]
	v_pk_fma_f32 v[68:69], v[178:179], v[128:129], v[40:41]
	v_pk_fma_f32 v[66:67], v[166:167], v[132:133], v[42:43]
	v_pk_fma_f32 v[46:47], v[170:171], v[132:133], v[46:47]
	v_pk_fma_f32 v[42:43], v[172:173], v[126:127], v[58:59]
	v_pk_fma_f32 v[40:41], v[184:185], v[128:129], v[60:61]
	v_pk_fma_f32 v[36:37], v[92:93], v[130:131], v[56:57]
	v_pk_fma_f32 v[2:3], v[48:49], v[138:139], v[4:5]
	v_mov_b32_e32 v79, v32
	v_mov_b32_e32 v61, v24
	v_mov_b32_e32 v49, v16
	v_mov_b32_e32 v5, v8
	s_cbranch_vccz .LBB0_432
	s_lshl_b64 s[60:61], s[58:59], 11
	s_add_i32 s4, s20, -2
	v_cvt_pk_bf16_f32 v52, v90, v91
	v_cvt_pk_bf16_f32 v53, v84, v85
	v_cvt_pk_bf16_f32 v54, v82, v83
	v_cvt_pk_bf16_f32 v55, v76, v77
	v_lshl_add_u64 v[4:5], v[112:113], 0, s[60:61]
	s_ashr_i32 s5, s4, 31
	global_store_dwordx4 v[4:5], v[52:55], off nt
	s_lshl_b64 s[64:65], s[4:5], 11
	s_add_i32 s4, s20, -1
	v_cvt_pk_bf16_f32 v52, v34, v35
	v_cvt_pk_bf16_f32 v53, v30, v31
	v_cvt_pk_bf16_f32 v54, v32, v33
	v_cvt_pk_bf16_f32 v55, v28, v29
	global_store_dwordx4 v[4:5], v[52:55], off offset:1024 nt
	v_lshl_add_u64 v[4:5], v[112:113], 0, s[64:65]
	s_ashr_i32 s5, s4, 31
	v_cvt_pk_bf16_f32 v52, v74, v75
	v_cvt_pk_bf16_f32 v53, v68, v69
	v_cvt_pk_bf16_f32 v54, v66, v67
	v_cvt_pk_bf16_f32 v55, v64, v65
	global_store_dwordx4 v[4:5], v[52:55], off nt
	s_lshl_b64 s[66:67], s[4:5], 11
	s_ashr_i32 s21, s20, 31
	v_cvt_pk_bf16_f32 v52, v26, v27
	v_cvt_pk_bf16_f32 v53, v22, v23
	v_cvt_pk_bf16_f32 v54, v24, v25
	v_cvt_pk_bf16_f32 v55, v18, v19
	global_store_dwordx4 v[4:5], v[52:55], off offset:1024 nt
	v_lshl_add_u64 v[4:5], v[112:113], 0, s[66:67]
	s_lshl_b64 s[68:69], s[20:21], 11
	v_cvt_pk_bf16_f32 v52, v62, v63
	v_cvt_pk_bf16_f32 v53, v50, v51
	v_cvt_pk_bf16_f32 v54, v46, v47
	v_cvt_pk_bf16_f32 v55, v44, v45
	global_store_dwordx4 v[4:5], v[52:55], off nt
	s_mov_b64 s[4:5], 0
	v_mov_b32_e32 v81, v77
	v_cvt_pk_bf16_f32 v52, v20, v21
	v_cvt_pk_bf16_f32 v53, v14, v15
	v_cvt_pk_bf16_f32 v54, v16, v17
	v_cvt_pk_bf16_f32 v55, v10, v11
	global_store_dwordx4 v[4:5], v[52:55], off offset:1024 nt
	v_lshl_add_u64 v[4:5], v[112:113], 0, s[68:69]
	v_mov_b32_e32 v80, v83
	v_cvt_pk_bf16_f32 v52, v42, v43
	v_cvt_pk_bf16_f32 v53, v40, v41
	v_cvt_pk_bf16_f32 v54, v38, v39
	v_cvt_pk_bf16_f32 v55, v36, v37
	global_store_dwordx4 v[4:5], v[52:55], off nt
	v_mov_b32_e32 v87, v76
	v_mov_b32_e32 v86, v82
	v_cvt_pk_bf16_f32 v52, v12, v13
	v_cvt_pk_bf16_f32 v53, v6, v7
	v_cvt_pk_bf16_f32 v54, v8, v9
	v_cvt_pk_bf16_f32 v55, v2, v3
	global_store_dwordx4 v[4:5], v[52:55], off offset:1024 nt
	v_mov_b32_e32 v71, v65
	v_mov_b32_e32 v70, v67
	v_mov_b32_e32 v73, v64
	v_mov_b32_e32 v72, v66
	v_mov_b32_e32 v57, v45
	v_mov_b32_e32 v56, v47
	v_mov_b32_e32 v59, v44
	v_mov_b32_e32 v58, v46
	v_mov_b32_e32 v53, v37
	v_mov_b32_e32 v52, v39
	v_mov_b32_e32 v55, v36
	v_mov_b32_e32 v54, v38
	v_mov_b32_e32 v79, v32
	v_mov_b32_e32 v61, v24
	v_mov_b32_e32 v49, v16
	v_mov_b32_e32 v5, v8

.LBB0_883:
	s_ashr_i32 s11, s10, 31
	s_lshl_b64 s[16:17], s[10:11], 11
	v_lshl_add_u64 v[54:55], v[38:39], 0, s[16:17]
	v_add_co_u32_e32 v30, vcc, s46, v54
	s_add_i32 s50, s10, 1
	s_nop 0
	v_addc_co_u32_e32 v31, vcc, 0, v55, vcc
	s_add_i32 s6, s10, 2
	s_add_i32 s4, s10, 3
	global_load_dwordx4 v[2:5], v[54:55], off
	global_load_dwordx4 v[6:9], v[54:55], off offset:1024
	global_load_dwordx4 v[10:13], v[54:55], off offset:2048
	global_load_dwordx4 v[14:17], v[54:55], off offset:3072
	global_load_dwordx4 v[18:21], v[30:31], off
	global_load_dwordx4 v[22:25], v[30:31], off offset:1024
	global_load_dwordx4 v[26:29], v[30:31], off offset:2048
	s_ashr_i32 s51, s50, 31
	s_ashr_i32 s7, s6, 31
	s_ashr_i32 s5, s4, 31
	s_ashr_i32 s24, s13, 10
	s_lshl_b64 s[56:57], s[10:11], 6
	s_lshl_b64 s[22:23], s[50:51], 11
	s_lshl_b64 s[20:21], s[6:7], 11
	s_lshl_b64 s[18:19], s[4:5], 11
	s_add_u32 s56, s28, s56
	s_addc_u32 s57, s29, s57
	global_load_dwordx4 v[32:35], v[30:31], off offset:3072
	global_load_dwordx4 v[72:75], v37, s[56:57] offset:48
	global_load_dwordx4 v[76:79], v37, s[56:57] offset:32
	global_load_dwordx4 v[84:87], v37, s[56:57] offset:16
	global_load_dwordx4 v[148:151], v37, s[56:57]
	s_lshl_b64 s[50:51], s[50:51], 6
	s_add_u32 s50, s28, s50
	s_addc_u32 s51, s29, s51
	global_load_dwordx4 v[152:155], v37, s[50:51] offset:48
	global_load_dwordx4 v[156:159], v37, s[50:51] offset:32
	global_load_dwordx4 v[160:163], v37, s[50:51] offset:16
	global_load_dwordx4 v[164:167], v37, s[50:51]
	s_lshl_b64 s[6:7], s[6:7], 6
	s_add_u32 s6, s28, s6
	s_addc_u32 s7, s29, s7
	global_load_dwordx4 v[168:171], v37, s[6:7] offset:16
	global_load_dwordx4 v[172:175], v37, s[6:7]
	s_lshl_b64 s[4:5], s[4:5], 6
	s_add_u32 s4, s28, s4
	s_addc_u32 s5, s29, s5
	s_waitcnt vmcnt(0)
	v_lshlrev_b32_e32 v56, 16, v2
	v_and_b32_e32 v57, 0xffff0000, v2
	v_lshlrev_b32_e32 v60, 16, v3
	v_and_b32_e32 v61, 0xffff0000, v3
	v_lshl_add_u64 v[2:3], v[40:41], 0, s[16:17]
	v_lshlrev_b32_e32 v102, 16, v14
	v_and_b32_e32 v103, 0xffff0000, v14
	v_lshlrev_b32_e32 v104, 16, v15
	v_and_b32_e32 v105, 0xffff0000, v15
	v_lshlrev_b32_e32 v98, 16, v16
	v_and_b32_e32 v99, 0xffff0000, v16
	v_lshlrev_b32_e32 v100, 16, v17
	v_and_b32_e32 v101, 0xffff0000, v17
	v_lshlrev_b32_e32 v126, 16, v26
	v_and_b32_e32 v127, 0xffff0000, v26
	v_lshlrev_b32_e32 v130, 16, v27
	v_and_b32_e32 v131, 0xffff0000, v27
	v_lshlrev_b32_e32 v128, 16, v28
	v_and_b32_e32 v129, 0xffff0000, v28
	v_lshlrev_b32_e32 v132, 16, v29
	v_and_b32_e32 v133, 0xffff0000, v29
	global_load_dwordx4 v[26:29], v[2:3], off
	global_load_dwordx4 v[14:17], v[2:3], off offset:1024
	v_lshl_add_u64 v[2:3], v[40:41], 0, s[22:23]
	v_lshlrev_b32_e32 v64, 16, v10
	v_and_b32_e32 v65, 0xffff0000, v10
	v_lshlrev_b32_e32 v68, 16, v11
	v_and_b32_e32 v69, 0xffff0000, v11
	v_lshlrev_b32_e32 v66, 16, v12
	v_and_b32_e32 v67, 0xffff0000, v12
	v_lshlrev_b32_e32 v70, 16, v13
	v_and_b32_e32 v71, 0xffff0000, v13
	v_lshlrev_b32_e32 v94, 16, v22
	v_and_b32_e32 v95, 0xffff0000, v22
	v_lshlrev_b32_e32 v96, 16, v23
	v_and_b32_e32 v97, 0xffff0000, v23
	v_lshlrev_b32_e32 v90, 16, v24
	v_and_b32_e32 v91, 0xffff0000, v24
	v_lshlrev_b32_e32 v92, 16, v25
	v_and_b32_e32 v93, 0xffff0000, v25
	global_load_dwordx4 v[176:179], v37, s[6:7] offset:48
	global_load_dwordx4 v[180:183], v37, s[6:7] offset:32
	global_load_dwordx4 v[22:25], v[2:3], off
	global_load_dwordx4 v[10:13], v[2:3], off offset:1024
	v_lshl_add_u64 v[2:3], v[40:41], 0, s[20:21]
	v_lshlrev_b32_e32 v58, 16, v4
	v_and_b32_e32 v59, 0xffff0000, v4
	v_lshlrev_b32_e32 v62, 16, v5
	v_and_b32_e32 v63, 0xffff0000, v5
	v_lshlrev_b32_e32 v118, 16, v18
	v_and_b32_e32 v119, 0xffff0000, v18
	v_lshlrev_b32_e32 v122, 16, v19
	v_and_b32_e32 v123, 0xffff0000, v19
	v_lshlrev_b32_e32 v120, 16, v20
	v_and_b32_e32 v121, 0xffff0000, v20
	v_lshlrev_b32_e32 v124, 16, v21
	v_and_b32_e32 v125, 0xffff0000, v21
	global_load_dwordx4 v[18:21], v[2:3], off
	s_nop 0
	global_load_dwordx4 v[2:5], v[2:3], off offset:1024
	s_nop 0
	global_load_dwordx4 v[184:187], v37, s[4:5] offset:16
	global_load_dwordx4 v[188:191], v37, s[4:5]
	v_lshlrev_b32_e32 v110, 16, v6
	v_and_b32_e32 v111, 0xffff0000, v6
	v_lshlrev_b32_e32 v114, 16, v7
	v_and_b32_e32 v115, 0xffff0000, v7
	v_lshl_add_u64 v[6:7], v[40:41], 0, s[18:19]
	v_mov_b32_e32 v80, v149
	v_mov_b32_e32 v81, v150
	v_mov_b32_e32 v149, v151
	v_lshlrev_b32_e32 v106, 16, v8
	v_and_b32_e32 v107, 0xffff0000, v8
	v_lshlrev_b32_e32 v108, 16, v9
	v_and_b32_e32 v109, 0xffff0000, v9
	v_lshlrev_b32_e32 v82, 16, v32
	v_and_b32_e32 v83, 0xffff0000, v32
	v_lshlrev_b32_e32 v88, 16, v33
	v_and_b32_e32 v89, 0xffff0000, v33
	global_load_dwordx4 v[30:33], v[6:7], off
	s_nop 0
	global_load_dwordx4 v[6:9], v[6:7], off offset:1024
	v_pk_add_f32 v[80:81], v[80:81], v[148:149]
	global_load_dwordx4 v[148:151], v37, s[4:5] offset:48
	global_load_dwordx4 v[192:195], v37, s[4:5] offset:32
	v_mov_b32_e32 v196, v85
	v_mov_b32_e32 v197, v86
	v_mov_b32_e32 v85, v87
	v_pk_add_f32 v[84:85], v[196:197], v[84:85]
	v_pk_add_f32 v[80:81], v[80:81], v[80:81] op_sel:[0,1] op_sel_hi:[1,0]
	v_pk_add_f32 v[84:85], v[84:85], v[84:85] op_sel:[0,1] op_sel_hi:[1,0]
	v_add_f32_e32 v76, v76, v77
	v_add_f32_e32 v78, v78, v79
	v_mov_b32_e32 v81, v72
	v_mov_b32_e32 v85, v73
	v_mov_b32_e32 v77, v74
	v_mov_b32_e32 v79, v75
	v_pk_add_f32 v[72:73], v[80:81], v[84:85]
	v_pk_add_f32 v[74:75], v[76:77], v[78:79]
	v_mov_b32_e32 v76, v161
	v_pk_add_f32 v[72:73], v[72:73], v[74:75]
	v_mov_b32_e32 v74, v165
	v_mov_b32_e32 v75, v166
	v_mov_b32_e32 v165, v167
	v_mov_b32_e32 v77, v162
	v_mov_b32_e32 v161, v163
	v_pk_add_f32 v[74:75], v[74:75], v[164:165]
	v_pk_add_f32 v[76:77], v[76:77], v[160:161]
	v_pk_add_f32 v[74:75], v[74:75], v[74:75] op_sel:[0,1] op_sel_hi:[1,0]
	v_pk_add_f32 v[76:77], v[76:77], v[76:77] op_sel:[0,1] op_sel_hi:[1,0]
	v_add_f32_e32 v78, v156, v157
	v_add_f32_e32 v80, v158, v159
	v_mov_b32_e32 v75, v152
	v_mov_b32_e32 v77, v153
	v_mov_b32_e32 v79, v154
	v_mov_b32_e32 v81, v155
	v_pk_add_f32 v[74:75], v[74:75], v[76:77]
	v_pk_add_f32 v[76:77], v[78:79], v[80:81]
	v_lshlrev_b32_e32 v112, 16, v34
	v_pk_add_f32 v[74:75], v[74:75], v[76:77]
	v_mov_b32_e32 v77, v72
	v_mov_b32_e32 v76, v74
	v_mov_b32_e32 v72, v75
	v_pk_add_f32 v[72:73], v[76:77], v[72:73]
	v_and_b32_e32 v113, 0xffff0000, v34
	v_pk_fma_f32 v[72:73], v[72:73], s[12:13], v[52:53] op_sel_hi:[1,0,0]
	v_lshlrev_b32_e32 v116, 16, v35
	v_mul_f32_e32 v34, 0x4b800000, v73
	v_cmp_gt_f32_e32 vcc, s47, v73
	v_cmp_gt_f32_e64 s[4:5], s47, v72
	v_and_b32_e32 v117, 0xffff0000, v35
	v_cndmask_b32_e32 v34, v73, v34, vcc
	v_rsq_f32_e32 v34, v34
	v_mul_f32_e32 v73, 0x4b800000, v72
	v_cndmask_b32_e64 v72, v72, v73, s[4:5]
	v_rsq_f32_e32 v80, v72
	v_mul_f32_e32 v35, 0x45800000, v34
	v_cndmask_b32_e32 v136, v34, v35, vcc
	v_mov_b32_e32 v34, v173
	v_mov_b32_e32 v35, v174
	v_mov_b32_e32 v173, v175
	v_mov_b32_e32 v72, v169
	v_mov_b32_e32 v73, v170
	v_mov_b32_e32 v169, v171
	v_pk_add_f32 v[34:35], v[34:35], v[172:173]
	v_pk_add_f32 v[72:73], v[72:73], v[168:169]
	v_pk_add_f32 v[34:35], v[34:35], v[34:35] op_sel:[0,1] op_sel_hi:[1,0]
	v_pk_add_f32 v[72:73], v[72:73], v[72:73] op_sel:[0,1] op_sel_hi:[1,0]
	s_waitcnt vmcnt(10)
	v_add_f32_e32 v74, v180, v181
	v_add_f32_e32 v76, v182, v183
	v_mov_b32_e32 v35, v176
	v_mov_b32_e32 v73, v177
	v_mov_b32_e32 v75, v178
	v_mov_b32_e32 v77, v179
	v_pk_add_f32 v[34:35], v[34:35], v[72:73]
	v_pk_add_f32 v[72:73], v[74:75], v[76:77]
	s_waitcnt vmcnt(5)
	v_mov_b32_e32 v74, v185
	v_pk_add_f32 v[34:35], v[34:35], v[72:73]
	s_waitcnt vmcnt(4)
	v_mov_b32_e32 v72, v189
	v_mov_b32_e32 v73, v190
	v_mov_b32_e32 v189, v191
	v_mov_b32_e32 v75, v186
	v_mov_b32_e32 v185, v187
	v_pk_add_f32 v[72:73], v[72:73], v[188:189]
	v_pk_add_f32 v[74:75], v[74:75], v[184:185]
	v_pk_add_f32 v[72:73], v[72:73], v[72:73] op_sel:[0,1] op_sel_hi:[1,0]
	v_pk_add_f32 v[74:75], v[74:75], v[74:75] op_sel:[0,1] op_sel_hi:[1,0]
	s_waitcnt vmcnt(0)
	v_add_f32_e32 v76, v192, v193
	v_add_f32_e32 v78, v194, v195
	v_mov_b32_e32 v73, v148
	v_mov_b32_e32 v75, v149
	v_mov_b32_e32 v77, v150
	v_mov_b32_e32 v79, v151
	v_pk_add_f32 v[72:73], v[72:73], v[74:75]
	v_pk_add_f32 v[74:75], v[76:77], v[78:79]
	v_mul_f32_e32 v81, 0x45800000, v80
	v_pk_add_f32 v[72:73], v[72:73], v[74:75]
	v_mov_b32_e32 v75, v34
	v_mov_b32_e32 v74, v72
	v_mov_b32_e32 v34, v73
	v_pk_add_f32 v[34:35], v[74:75], v[34:35]
	v_cndmask_b32_e64 v140, v80, v81, s[4:5]
	v_pk_fma_f32 v[34:35], v[34:35], s[12:13], v[52:53] op_sel_hi:[1,0,0]
	s_nop 0
	v_mul_f32_e32 v72, 0x4b800000, v35
	v_cmp_gt_f32_e32 vcc, s47, v35
	v_cmp_gt_f32_e64 s[6:7], s47, v34
	s_nop 0
	v_cndmask_b32_e32 v35, v35, v72, vcc
	v_mul_f32_e32 v72, 0x4b800000, v34
	v_rsq_f32_e32 v35, v35
	v_cndmask_b32_e64 v34, v34, v72, s[6:7]
	v_rsq_f32_e32 v34, v34
	v_mul_f32_e32 v72, 0x45800000, v35
	v_cndmask_b32_e32 v138, v35, v72, vcc
	v_mul_f32_e32 v35, 0x45800000, v34
	v_cndmask_b32_e64 v134, v34, v35, s[6:7]
	s_mul_i32 s4, s24, 9
	s_ashr_i32 s5, s4, 31
	s_lshl_b64 s[4:5], s[4:5], 12
	s_add_u32 s24, s70, s4
	s_addc_u32 s25, s71, s5
	s_add_u32 s4, s24, 0x5000
	s_addc_u32 s5, s25, 0
	global_load_dwordx4 v[72:75], v[42:43], off
	global_load_dwordx4 v[76:79], v36, s[4:5]
	global_load_dwordx4 v[84:87], v36, s[4:5] offset:16
	global_load_dwordx4 v[148:151], v[42:43], off offset:16
	global_load_dwordx4 v[152:155], v135, s[4:5]
	global_load_dwordx4 v[156:159], v[44:45], off
	global_load_dwordx4 v[160:163], v[44:45], off offset:16
	global_load_dwordx4 v[164:167], v135, s[4:5] offset:16
	v_lshlrev_b32_e32 v168, 16, v22
	v_and_b32_e32 v169, 0xffff0000, v22
	v_lshlrev_b32_e32 v172, 16, v18
	v_and_b32_e32 v173, 0xffff0000, v18
	v_lshlrev_b32_e32 v18, 16, v19
	v_and_b32_e32 v19, 0xffff0000, v19
	v_lshlrev_b32_e32 v80, 16, v28
	v_and_b32_e32 v81, 0xffff0000, v28
	v_lshlrev_b32_e32 v28, 16, v29
	v_and_b32_e32 v29, 0xffff0000, v29
	v_lshlrev_b32_e32 v22, 16, v23
	v_and_b32_e32 v23, 0xffff0000, v23
	v_lshlrev_b32_e32 v174, 16, v20
	v_and_b32_e32 v175, 0xffff0000, v20
	v_lshlrev_b32_e32 v20, 16, v21
	v_and_b32_e32 v21, 0xffff0000, v21
	v_pk_mul_f32 v[168:169], v[140:141], v[168:169] op_sel_hi:[0,1]
	v_pk_mul_f32 v[18:19], v[138:139], v[18:19] op_sel_hi:[0,1]
	v_lshlrev_b32_e32 v34, 16, v26
	v_and_b32_e32 v35, 0xffff0000, v26
	v_lshlrev_b32_e32 v26, 16, v27
	v_and_b32_e32 v27, 0xffff0000, v27
	v_pk_mul_f32 v[28:29], v[136:137], v[28:29] op_sel_hi:[0,1]
	v_pk_mul_f32 v[22:23], v[140:141], v[22:23] op_sel_hi:[0,1]
	v_pk_mul_f32 v[20:21], v[138:139], v[20:21] op_sel_hi:[0,1]
	v_lshlrev_b32_e32 v170, 16, v24
	v_and_b32_e32 v171, 0xffff0000, v24
	v_lshlrev_b32_e32 v24, 16, v25
	v_and_b32_e32 v25, 0xffff0000, v25
	v_lshlrev_b32_e32 v176, 16, v30
	v_and_b32_e32 v177, 0xffff0000, v30
	v_lshlrev_b32_e32 v30, 16, v31
	v_and_b32_e32 v31, 0xffff0000, v31
	v_pk_mul_f32 v[26:27], v[136:137], v[26:27] op_sel_hi:[0,1]
	v_pk_mul_f32 v[34:35], v[136:137], v[34:35] op_sel_hi:[0,1]
	v_pk_mul_f32 v[24:25], v[140:141], v[24:25] op_sel_hi:[0,1]
	v_pk_mul_f32 v[30:31], v[134:135], v[30:31] op_sel_hi:[0,1]
	v_lshlrev_b32_e32 v178, 16, v32
	v_and_b32_e32 v179, 0xffff0000, v32
	v_lshlrev_b32_e32 v32, 16, v33
	v_and_b32_e32 v33, 0xffff0000, v33
	v_lshlrev_b32_e32 v180, 16, v14
	v_and_b32_e32 v181, 0xffff0000, v14
	v_pk_mul_f32 v[80:81], v[136:137], v[80:81] op_sel_hi:[0,1]
	v_pk_mul_f32 v[32:33], v[134:135], v[32:33] op_sel_hi:[0,1]
	v_lshlrev_b32_e32 v14, 16, v15
	v_and_b32_e32 v15, 0xffff0000, v15
	v_pk_mul_f32 v[14:15], v[136:137], v[14:15] op_sel_hi:[0,1]
	v_pk_mul_f32 v[170:171], v[140:141], v[170:171] op_sel_hi:[0,1]
	v_pk_mul_f32 v[172:173], v[138:139], v[172:173] op_sel_hi:[0,1]
	v_pk_mul_f32 v[174:175], v[138:139], v[174:175] op_sel_hi:[0,1]
	v_pk_mul_f32 v[176:177], v[134:135], v[176:177] op_sel_hi:[0,1]
	v_pk_mul_f32 v[178:179], v[134:135], v[178:179] op_sel_hi:[0,1]
	s_waitcnt vmcnt(6)
	v_pk_mul_f32 v[182:183], v[78:79], v[74:75]
	v_pk_mul_f32 v[184:185], v[76:77], v[72:73]
	s_waitcnt vmcnt(4)
	v_pk_mul_f32 v[150:151], v[86:87], v[150:151]
	v_pk_fma_f32 v[76:77], v[184:185], v[168:169], v[64:65]
	v_pk_fma_f32 v[64:65], v[182:183], v[18:19], v[122:123]
	v_lshlrev_b32_e32 v18, 16, v16
	v_and_b32_e32 v19, 0xffff0000, v16
	s_waitcnt vmcnt(2)
	v_pk_mul_f32 v[154:155], v[154:155], v[158:159]
	s_waitcnt vmcnt(0)
	v_pk_mul_f32 v[158:159], v[164:165], v[160:161]
	v_pk_fma_f32 v[78:79], v[28:29], v[150:151], v[62:63]
	v_pk_fma_f32 v[72:73], v[182:183], v[22:23], v[68:69]
	v_pk_fma_f32 v[62:63], v[150:151], v[20:21], v[124:125]
	v_lshlrev_b32_e32 v20, 16, v17
	v_and_b32_e32 v21, 0xffff0000, v17
	v_pk_mul_f32 v[22:23], v[136:137], v[18:19] op_sel_hi:[0,1]
	v_pk_mul_f32 v[148:149], v[84:85], v[148:149]
	v_pk_fma_f32 v[84:85], v[26:27], v[182:183], v[60:61]
	v_pk_mul_f32 v[18:19], v[136:137], v[20:21] op_sel_hi:[0,1]
	v_pk_fma_f32 v[20:21], v[22:23], v[158:159], v[106:107]
	v_lshlrev_b32_e32 v22, 16, v10
	v_and_b32_e32 v23, 0xffff0000, v10
	v_lshlrev_b32_e32 v26, 16, v13
	v_and_b32_e32 v27, 0xffff0000, v13
	v_pk_fma_f32 v[86:87], v[34:35], v[184:185], v[56:57]
	v_pk_fma_f32 v[70:71], v[150:151], v[24:25], v[70:71]
	v_pk_fma_f32 v[56:57], v[182:183], v[30:31], v[130:131]
	v_lshlrev_b32_e32 v24, 16, v12
	v_and_b32_e32 v25, 0xffff0000, v12
	v_pk_mul_f32 v[12:13], v[140:141], v[22:23] op_sel_hi:[0,1]
	v_pk_mul_f32 v[22:23], v[140:141], v[26:27] op_sel_hi:[0,1]
	v_lshlrev_b32_e32 v26, 16, v2
	v_and_b32_e32 v27, 0xffff0000, v2
	v_lshlrev_b32_e32 v28, 16, v4
	v_and_b32_e32 v29, 0xffff0000, v4
	v_lshlrev_b32_e32 v30, 16, v5
	v_and_b32_e32 v31, 0xffff0000, v5
	v_pk_mul_f32 v[4:5], v[138:139], v[26:27] op_sel_hi:[0,1]
	v_pk_mul_f32 v[28:29], v[138:139], v[28:29] op_sel_hi:[0,1]
	v_pk_mul_f32 v[26:27], v[138:139], v[30:31] op_sel_hi:[0,1]
	v_lshlrev_b32_e32 v30, 16, v6
	v_and_b32_e32 v31, 0xffff0000, v6
	v_lshlrev_b32_e32 v6, 16, v7
	v_and_b32_e32 v7, 0xffff0000, v7
	v_pk_fma_f32 v[28:29], v[158:159], v[28:29], v[90:91]
	v_lshlrev_b32_e32 v90, 16, v9
	v_and_b32_e32 v91, 0xffff0000, v9
	v_pk_mul_f32 v[6:7], v[134:135], v[6:7] op_sel_hi:[0,1]
	v_pk_mul_f32 v[152:153], v[152:153], v[156:157]
	v_pk_mul_f32 v[156:157], v[166:167], v[162:163]
	v_pk_fma_f32 v[80:81], v[80:81], v[148:149], v[58:59]
	v_pk_fma_f32 v[34:35], v[150:151], v[32:33], v[132:133]
	v_pk_mul_f32 v[16:17], v[136:137], v[180:181] op_sel_hi:[0,1]
	v_lshlrev_b32_e32 v32, 16, v8
	v_and_b32_e32 v33, 0xffff0000, v8
	v_pk_mul_f32 v[8:9], v[134:135], v[30:31] op_sel_hi:[0,1]
	v_pk_fma_f32 v[6:7], v[154:155], v[6:7], v[88:89]
	v_pk_mul_f32 v[30:31], v[134:135], v[90:91] op_sel_hi:[0,1]
	v_cvt_pk_bf16_f32 v88, v86, v87
	v_cvt_pk_bf16_f32 v89, v84, v85
	v_cvt_pk_bf16_f32 v90, v80, v81
	v_cvt_pk_bf16_f32 v91, v78, v79
	v_pk_fma_f32 v[14:15], v[14:15], v[154:155], v[114:115]
	v_pk_fma_f32 v[16:17], v[16:17], v[152:153], v[110:111]
	v_pk_fma_f32 v[18:19], v[18:19], v[156:157], v[108:109]
	v_lshlrev_b32_e32 v10, 16, v11
	v_and_b32_e32 v11, 0xffff0000, v11
	global_store_dwordx4 v[54:55], v[88:91], off nt
	v_pk_fma_f32 v[74:75], v[148:149], v[170:171], v[66:67]
	v_pk_mul_f32 v[10:11], v[140:141], v[10:11] op_sel_hi:[0,1]
	v_cvt_pk_bf16_f32 v88, v16, v17
	v_cvt_pk_bf16_f32 v89, v14, v15
	v_cvt_pk_bf16_f32 v90, v20, v21
	v_cvt_pk_bf16_f32 v91, v18, v19
	v_pk_mul_f32 v[24:25], v[140:141], v[24:25] op_sel_hi:[0,1]
	global_store_dwordx4 v[54:55], v[88:91], off offset:1024 nt
	v_lshl_add_u64 v[54:55], v[38:39], 0, s[22:23]
	v_pk_fma_f32 v[10:11], v[10:11], v[154:155], v[104:105]
	v_cvt_pk_bf16_f32 v88, v76, v77
	v_cvt_pk_bf16_f32 v89, v72, v73
	v_cvt_pk_bf16_f32 v90, v74, v75
	v_cvt_pk_bf16_f32 v91, v70, v71
	v_pk_fma_f32 v[12:13], v[12:13], v[152:153], v[102:103]
	v_pk_fma_f32 v[22:23], v[22:23], v[156:157], v[100:101]
	v_pk_fma_f32 v[24:25], v[24:25], v[158:159], v[98:99]
	v_lshlrev_b32_e32 v2, 16, v3
	v_and_b32_e32 v3, 0xffff0000, v3
	global_store_dwordx4 v[54:55], v[88:91], off nt
	v_pk_fma_f32 v[68:69], v[184:185], v[172:173], v[118:119]
	v_pk_fma_f32 v[66:67], v[148:149], v[174:175], v[120:121]
	v_cvt_pk_bf16_f32 v88, v12, v13
	v_cvt_pk_bf16_f32 v89, v10, v11
	v_cvt_pk_bf16_f32 v90, v24, v25
	v_cvt_pk_bf16_f32 v91, v22, v23
	v_pk_mul_f32 v[2:3], v[138:139], v[2:3] op_sel_hi:[0,1]
	global_store_dwordx4 v[54:55], v[88:91], off offset:1024 nt
	v_lshl_add_u64 v[54:55], v[38:39], 0, s[20:21]
	v_pk_fma_f32 v[2:3], v[154:155], v[2:3], v[96:97]
	v_cvt_pk_bf16_f32 v88, v68, v69
	v_cvt_pk_bf16_f32 v89, v64, v65
	v_cvt_pk_bf16_f32 v90, v66, v67
	v_cvt_pk_bf16_f32 v91, v62, v63
	v_pk_fma_f32 v[4:5], v[152:153], v[4:5], v[94:95]
	v_pk_fma_f32 v[26:27], v[156:157], v[26:27], v[92:93]
	global_store_dwordx4 v[54:55], v[88:91], off nt
	v_pk_fma_f32 v[60:61], v[184:185], v[176:177], v[126:127]
	v_pk_fma_f32 v[58:59], v[148:149], v[178:179], v[128:129]
	v_cvt_pk_bf16_f32 v88, v4, v5
	v_cvt_pk_bf16_f32 v89, v2, v3
	v_cvt_pk_bf16_f32 v90, v28, v29
	v_cvt_pk_bf16_f32 v91, v26, v27
	v_pk_mul_f32 v[32:33], v[134:135], v[32:33] op_sel_hi:[0,1]
	global_store_dwordx4 v[54:55], v[88:91], off offset:1024 nt
	v_lshl_add_u64 v[54:55], v[38:39], 0, s[18:19]
	v_pk_fma_f32 v[8:9], v[152:153], v[8:9], v[82:83]
	v_cvt_pk_bf16_f32 v88, v60, v61
	v_cvt_pk_bf16_f32 v89, v56, v57
	v_cvt_pk_bf16_f32 v90, v58, v59
	v_cvt_pk_bf16_f32 v91, v34, v35
	v_pk_fma_f32 v[30:31], v[156:157], v[30:31], v[116:117]
	v_pk_fma_f32 v[32:33], v[158:159], v[32:33], v[112:113]
	global_store_dwordx4 v[54:55], v[88:91], off nt
	s_nop 1
	v_cvt_pk_bf16_f32 v88, v8, v9
	v_cvt_pk_bf16_f32 v89, v6, v7
	v_cvt_pk_bf16_f32 v90, v32, v33
	v_cvt_pk_bf16_f32 v91, v30, v31
	global_store_dwordx4 v[54:55], v[88:91], off offset:1024 nt
	v_pk_mul_f32 v[54:55], v[84:85], v[84:85]
	v_pk_mul_f32 v[82:83], v[86:87], v[86:87]
	v_cmp_lt_i32_e32 vcc, v141, v139
	v_pk_mov_b32 v[88:89], v[82:83], v[54:55] op_sel:[1,0]
	v_mov_b32_e32 v83, v55
	v_pk_add_f32 v[54:55], v[88:89], v[82:83]
	v_pk_mul_f32 v[82:83], v[78:79], v[78:79]
	v_pk_mul_f32 v[88:89], v[80:81], v[80:81]
	v_pk_add_f32 v[54:55], v[54:55], v[54:55] op_sel:[0,1] op_sel_hi:[1,0]
	v_pk_mov_b32 v[90:91], v[88:89], v[82:83] op_sel:[1,0]
	v_mov_b32_e32 v89, v83
	v_pk_add_f32 v[82:83], v[90:91], v[88:89]
	v_mul_f32_e32 v88, v20, v20
	v_mul_f32_e32 v89, v21, v21
	v_pk_add_f32 v[82:83], v[82:83], v[82:83] op_sel:[0,1] op_sel_hi:[1,0]
	v_mov_b32_e32 v55, v88
	v_mov_b32_e32 v83, v89
	v_pk_add_f32 v[54:55], v[54:55], v[82:83]
	v_mul_f32_e32 v82, v17, v17
	v_mul_f32_e32 v88, v15, v15
	v_mul_f32_e32 v90, v18, v18
	v_mul_f32_e32 v91, v19, v19
	v_pk_fma_f32 v[82:83], v[16:17], v[16:17], v[82:83] op_sel_hi:[1,1,0]
	v_pk_fma_f32 v[88:89], v[14:15], v[14:15], v[88:89] op_sel_hi:[1,1,0]
	v_mov_b32_e32 v83, v90
	v_mov_b32_e32 v89, v91
	v_pk_add_f32 v[82:83], v[82:83], v[88:89]
	v_pk_mul_f32 v[88:89], v[76:77], v[76:77]
	v_pk_add_f32 v[54:55], v[54:55], v[82:83]
	v_cndmask_b32_e32 v82, v137, v141, vcc
	v_lshlrev_b32_e32 v98, 2, v82
	v_pk_mul_f32 v[82:83], v[72:73], v[72:73]
	v_cmp_lt_i32_e32 vcc, v142, v139
	v_pk_mov_b32 v[90:91], v[88:89], v[82:83] op_sel:[1,0]
	v_mov_b32_e32 v89, v83
	v_pk_add_f32 v[82:83], v[90:91], v[88:89]
	v_pk_mul_f32 v[88:89], v[70:71], v[70:71]
	v_pk_mul_f32 v[90:91], v[74:75], v[74:75]
	v_pk_add_f32 v[82:83], v[82:83], v[82:83] op_sel:[0,1] op_sel_hi:[1,0]
	v_pk_mov_b32 v[92:93], v[90:91], v[88:89] op_sel:[1,0]
	v_mov_b32_e32 v91, v89
	v_pk_add_f32 v[88:89], v[92:93], v[90:91]
	v_mul_f32_e32 v90, v24, v24
	v_mul_f32_e32 v91, v25, v25
	v_pk_add_f32 v[88:89], v[88:89], v[88:89] op_sel:[0,1] op_sel_hi:[1,0]
	v_mov_b32_e32 v83, v90
	v_mov_b32_e32 v89, v91
	v_pk_add_f32 v[82:83], v[82:83], v[88:89]
	v_mul_f32_e32 v88, v13, v13
	v_mul_f32_e32 v90, v11, v11
	v_mul_f32_e32 v92, v22, v22
	v_mul_f32_e32 v93, v23, v23
	v_pk_fma_f32 v[88:89], v[12:13], v[12:13], v[88:89] op_sel_hi:[1,1,0]
	v_pk_fma_f32 v[90:91], v[10:11], v[10:11], v[90:91] op_sel_hi:[1,1,0]
	v_mov_b32_e32 v89, v92
	v_mov_b32_e32 v91, v93
	v_pk_add_f32 v[88:89], v[88:89], v[90:91]
	v_pk_mul_f32 v[90:91], v[68:69], v[68:69]
	v_pk_add_f32 v[82:83], v[82:83], v[88:89]
	v_mov_b32_e32 v89, v54
	v_mov_b32_e32 v88, v82
	v_mov_b32_e32 v54, v83
	v_pk_add_f32 v[54:55], v[88:89], v[54:55]
	v_cndmask_b32_e32 v88, v137, v142, vcc
	v_cmp_lt_i32_e32 vcc, v143, v139
	v_lshlrev_b32_e32 v99, 2, v88
	ds_bpermute_b32 v83, v98, v55
	v_cndmask_b32_e32 v88, v137, v143, vcc
	v_cmp_lt_i32_e32 vcc, v144, v139
	v_lshlrev_b32_e32 v100, 2, v88
	ds_bpermute_b32 v82, v98, v54
	v_cndmask_b32_e32 v88, v137, v144, vcc
	v_cmp_lt_i32_e32 vcc, v145, v139
	v_lshlrev_b32_e32 v101, 2, v88
	s_waitcnt lgkmcnt(0)
	v_pk_add_f32 v[54:55], v[54:55], v[82:83]
	v_cndmask_b32_e32 v88, v137, v145, vcc
	v_lshlrev_b32_e32 v102, 2, v88
	v_pk_mul_f32 v[88:89], v[64:65], v[64:65]
	ds_bpermute_b32 v83, v99, v55
	v_pk_mov_b32 v[92:93], v[90:91], v[88:89] op_sel:[1,0]
	v_mov_b32_e32 v91, v89
	v_pk_add_f32 v[88:89], v[92:93], v[90:91]
	v_pk_mul_f32 v[90:91], v[62:63], v[62:63]
	v_pk_add_f32 v[88:89], v[88:89], v[88:89] op_sel_hi:[0,1]
	v_pk_mul_f32 v[92:93], v[66:67], v[66:67]
	v_mul_f32_e32 v88, v4, v4
	v_pk_mov_b32 v[94:95], v[92:93], v[90:91] op_sel:[1,0]
	v_mov_b32_e32 v93, v91
	v_pk_add_f32 v[90:91], v[94:95], v[92:93]
	v_pk_fma_f32 v[92:93], v[4:5], v[4:5], v[88:89] op_sel_hi:[1,1,0]
	v_mul_f32_e32 v88, v2, v2
	v_pk_add_f32 v[90:91], v[90:91], v[90:91] op_sel_hi:[0,1]
	v_pk_fma_f32 v[94:95], v[2:3], v[2:3], v[88:89] op_sel_hi:[1,1,0]
	v_mul_f32_e32 v92, v28, v28
	v_mul_f32_e32 v94, v29, v29
	v_mul_f32_e32 v88, v26, v26
	v_mul_f32_e32 v90, v27, v27
	v_pk_add_f32 v[92:93], v[92:93], v[94:95]
	v_pk_add_f32 v[88:89], v[88:89], v[90:91]
	ds_bpermute_b32 v82, v99, v54
	v_pk_add_f32 v[88:89], v[92:93], v[88:89]
	v_pk_mul_f32 v[90:91], v[56:57], v[56:57]
	v_pk_mul_f32 v[92:93], v[60:61], v[60:61]
	v_cmp_lt_i32_e32 vcc, v146, v139
	v_pk_mov_b32 v[94:95], v[92:93], v[90:91] op_sel:[1,0]
	v_mov_b32_e32 v93, v91
	v_pk_add_f32 v[90:91], v[94:95], v[92:93]
	v_pk_mul_f32 v[92:93], v[34:35], v[34:35]
	v_pk_add_f32 v[90:91], v[90:91], v[90:91] op_sel_hi:[0,1]
	v_pk_mul_f32 v[94:95], v[58:59], v[58:59]
	v_mul_f32_e32 v90, v8, v8
	v_pk_mov_b32 v[96:97], v[94:95], v[92:93] op_sel:[1,0]
	v_mov_b32_e32 v95, v93
	s_waitcnt lgkmcnt(0)
	v_pk_add_f32 v[54:55], v[54:55], v[82:83]
	v_pk_add_f32 v[92:93], v[96:97], v[94:95]
	v_pk_fma_f32 v[94:95], v[8:9], v[8:9], v[90:91] op_sel_hi:[1,1,0]
	v_mul_f32_e32 v90, v6, v6
	ds_bpermute_b32 v83, v100, v55
	ds_bpermute_b32 v82, v100, v54
	v_pk_add_f32 v[92:93], v[92:93], v[92:93] op_sel_hi:[0,1]
	v_pk_fma_f32 v[96:97], v[6:7], v[6:7], v[90:91] op_sel_hi:[1,1,0]
	v_mul_f32_e32 v94, v32, v32
	v_mul_f32_e32 v96, v33, v33
	v_mul_f32_e32 v90, v30, v30
	v_mul_f32_e32 v92, v31, v31
	v_pk_add_f32 v[94:95], v[94:95], v[96:97]
	v_pk_add_f32 v[90:91], v[90:91], v[92:93]
	v_mov_b32_e32 v93, v88
	v_pk_add_f32 v[90:91], v[94:95], v[90:91]
	s_waitcnt lgkmcnt(0)
	v_pk_add_f32 v[54:55], v[54:55], v[82:83]
	v_mov_b32_e32 v92, v90
	v_mov_b32_e32 v88, v91
	v_pk_add_f32 v[88:89], v[92:93], v[88:89]
	ds_bpermute_b32 v83, v101, v55
	ds_bpermute_b32 v82, v101, v54
	ds_bpermute_b32 v91, v98, v89
	ds_bpermute_b32 v90, v98, v88
	v_cndmask_b32_e32 v92, v137, v146, vcc
	v_lshlrev_b32_e32 v92, 2, v92
	s_waitcnt lgkmcnt(2)
	v_pk_add_f32 v[54:55], v[54:55], v[82:83]
	ds_bpermute_b32 v83, v102, v55
	s_waitcnt lgkmcnt(1)
	v_pk_add_f32 v[88:89], v[88:89], v[90:91]
	ds_bpermute_b32 v82, v102, v54
	ds_bpermute_b32 v91, v99, v89
	ds_bpermute_b32 v90, v99, v88
	s_waitcnt lgkmcnt(2)
	v_pk_add_f32 v[54:55], v[54:55], v[82:83]
	ds_bpermute_b32 v83, v92, v55
	s_waitcnt lgkmcnt(1)
	v_pk_add_f32 v[88:89], v[88:89], v[90:91]
	ds_bpermute_b32 v82, v92, v54
	ds_bpermute_b32 v91, v100, v89
	ds_bpermute_b32 v90, v100, v88
	s_waitcnt lgkmcnt(2)
	v_pk_add_f32 v[54:55], v[54:55], v[82:83]
	s_nop 0
	v_pk_fma_f32 v[54:55], v[54:55], s[12:13], v[52:53] op_sel_hi:[1,0,0]
	s_waitcnt lgkmcnt(0)
	v_pk_add_f32 v[82:83], v[88:89], v[90:91]
	ds_bpermute_b32 v89, v101, v83
	ds_bpermute_b32 v88, v101, v82
	v_mul_f32_e32 v90, 0x4b800000, v55
	v_cmp_gt_f32_e32 vcc, s47, v55
	v_cmp_gt_f32_e64 s[4:5], s47, v54
	s_waitcnt lgkmcnt(0)
	v_pk_add_f32 v[82:83], v[82:83], v[88:89]
	ds_bpermute_b32 v89, v102, v83
	ds_bpermute_b32 v88, v102, v82
	v_cndmask_b32_e32 v55, v55, v90, vcc
	v_rsq_f32_e32 v90, v55
	v_mul_f32_e32 v55, 0x4b800000, v54
	v_cndmask_b32_e64 v54, v54, v55, s[4:5]
	v_rsq_f32_e32 v91, v54
	s_waitcnt lgkmcnt(0)
	v_pk_add_f32 v[54:55], v[82:83], v[88:89]
	ds_bpermute_b32 v83, v92, v55
	ds_bpermute_b32 v82, v92, v54
	v_mul_f32_e32 v88, 0x45800000, v90
	v_cndmask_b32_e32 v114, v90, v88, vcc
	v_mul_f32_e32 v88, 0x45800000, v91
	v_cndmask_b32_e64 v88, v91, v88, s[4:5]
	s_waitcnt lgkmcnt(0)
	v_pk_add_f32 v[54:55], v[54:55], v[82:83]
	s_add_u32 s4, s24, 0x7000
	v_pk_fma_f32 v[54:55], v[54:55], s[12:13], v[52:53] op_sel_hi:[1,0,0]
	s_addc_u32 s5, s25, 0
	v_mul_f32_e32 v82, 0x4b800000, v55
	v_cmp_gt_f32_e32 vcc, s47, v55
	v_cmp_gt_f32_e64 s[6:7], s47, v54
	s_nop 0
	v_cndmask_b32_e32 v55, v55, v82, vcc
	v_mul_f32_e32 v82, 0x4b800000, v54
	v_rsq_f32_e32 v55, v55
	v_cndmask_b32_e64 v54, v54, v82, s[6:7]
	v_rsq_f32_e32 v54, v54
	v_mul_f32_e32 v82, 0x45800000, v55
	v_cndmask_b32_e32 v82, v55, v82, vcc
	v_mul_f32_e32 v55, 0x45800000, v54
	v_cndmask_b32_e64 v54, v54, v55, s[6:7]
	v_lshl_add_u64 v[110:111], s[24:25], 0, v[36:37]
	v_add_co_u32_e32 v106, vcc, s48, v110
	global_load_dwordx4 v[90:93], v36, s[4:5] offset:16
	global_load_dwordx4 v[94:97], v36, s[4:5]
	global_load_dwordx4 v[98:101], v[46:47], off offset:16
	global_load_dwordx4 v[102:105], v[46:47], off
	v_addc_co_u32_e32 v107, vcc, 0, v111, vcc
	v_lshl_add_u64 v[116:117], v[110:111], 0, s[14:15]
	global_load_dwordx4 v[106:109], v[106:107], off
	v_pk_mul_f32 v[86:87], v[86:87], v[114:115] op_sel_hi:[1,0]
	global_load_dwordx4 v[110:113], v[116:117], off offset:16
	v_pk_mul_f32 v[84:85], v[84:85], v[114:115] op_sel_hi:[1,0]
	v_pk_mul_f32 v[80:81], v[80:81], v[114:115] op_sel_hi:[1,0]
	v_pk_mul_f32 v[118:119], v[78:79], v[114:115] op_sel_hi:[1,0]
	v_pk_mul_f32 v[72:73], v[72:73], v[88:89] op_sel_hi:[1,0]
	v_pk_mul_f32 v[74:75], v[74:75], v[88:89] op_sel_hi:[1,0]
	v_pk_mul_f32 v[64:65], v[64:65], v[82:83] op_sel_hi:[1,0]
	v_pk_mul_f32 v[66:67], v[66:67], v[82:83] op_sel_hi:[1,0]
	v_pk_mul_f32 v[56:57], v[56:57], v[54:55] op_sel_hi:[1,0]
	v_pk_mul_f32 v[58:59], v[58:59], v[54:55] op_sel_hi:[1,0]
	v_lshl_add_u64 v[78:79], v[50:51], 0, s[16:17]
	v_pk_mul_f32 v[76:77], v[76:77], v[88:89] op_sel_hi:[1,0]
	v_pk_mul_f32 v[120:121], v[70:71], v[88:89] op_sel_hi:[1,0]
	v_lshl_add_u64 v[70:71], v[50:51], 0, s[22:23]
	v_pk_mul_f32 v[68:69], v[68:69], v[82:83] op_sel_hi:[1,0]
	v_pk_mul_f32 v[62:63], v[62:63], v[82:83] op_sel_hi:[1,0]
	v_lshl_add_u64 v[122:123], v[50:51], 0, s[20:21]
	v_pk_mul_f32 v[60:61], v[60:61], v[54:55] op_sel_hi:[1,0]
	v_pk_mul_f32 v[34:35], v[34:35], v[54:55] op_sel_hi:[1,0]
	v_lshl_add_u64 v[124:125], v[50:51], 0, s[18:19]
	v_pk_mul_f32 v[8:9], v[8:9], v[54:55] op_sel_hi:[1,0]
	v_pk_mul_f32 v[6:7], v[6:7], v[54:55] op_sel_hi:[1,0]
	v_pk_mul_f32 v[32:33], v[32:33], v[54:55] op_sel_hi:[1,0]
	v_pk_mul_f32 v[30:31], v[30:31], v[54:55] op_sel_hi:[1,0]
	v_pk_mul_f32 v[16:17], v[16:17], v[114:115] op_sel_hi:[1,0]
	v_pk_mul_f32 v[14:15], v[14:15], v[114:115] op_sel_hi:[1,0]
	v_pk_mul_f32 v[20:21], v[20:21], v[114:115] op_sel_hi:[1,0]
	v_pk_mul_f32 v[18:19], v[18:19], v[114:115] op_sel_hi:[1,0]
	v_pk_mul_f32 v[4:5], v[4:5], v[82:83] op_sel_hi:[1,0]
	v_pk_mul_f32 v[2:3], v[2:3], v[82:83] op_sel_hi:[1,0]
	v_pk_mul_f32 v[12:13], v[12:13], v[88:89] op_sel_hi:[1,0]
	v_pk_mul_f32 v[10:11], v[10:11], v[88:89] op_sel_hi:[1,0]
	v_pk_mul_f32 v[24:25], v[24:25], v[88:89] op_sel_hi:[1,0]
	v_pk_mul_f32 v[22:23], v[22:23], v[88:89] op_sel_hi:[1,0]
	v_pk_mul_f32 v[28:29], v[28:29], v[82:83] op_sel_hi:[1,0]
	v_pk_mul_f32 v[26:27], v[26:27], v[82:83] op_sel_hi:[1,0]
	s_add_i32 s13, s13, s44
	s_add_i32 s10, s10, s45
	s_cmpk_lt_i32 s13, 0x2000
	s_waitcnt vmcnt(5)
	v_pk_add_f32 v[92:93], v[92:93], 1.0 op_sel_hi:[1,0]
	s_waitcnt vmcnt(4)
	v_pk_add_f32 v[96:97], v[96:97], 1.0 op_sel_hi:[1,0]
	v_pk_add_f32 v[94:95], v[94:95], 1.0 op_sel_hi:[1,0]
	v_pk_add_f32 v[90:91], v[90:91], 1.0 op_sel_hi:[1,0]
	s_waitcnt vmcnt(2)
	v_pk_mul_f32 v[96:97], v[104:105], v[96:97]
	v_pk_mul_f32 v[94:95], v[102:103], v[94:95]
	v_pk_mul_f32 v[92:93], v[100:101], v[92:93]
	v_pk_mul_f32 v[90:91], v[98:99], v[90:91]
	s_waitcnt vmcnt(1)
	v_pk_fma_f32 v[84:85], v[84:85], v[96:97], v[108:109]
	v_pk_fma_f32 v[86:87], v[86:87], v[94:95], v[106:107]
	s_waitcnt vmcnt(0)
	v_pk_fma_f32 v[98:99], v[118:119], v[92:93], v[112:113]
	v_pk_fma_f32 v[80:81], v[80:81], v[90:91], v[110:111]
	v_pk_fma_f32 v[72:73], v[72:73], v[96:97], v[108:109]
	v_pk_fma_f32 v[74:75], v[74:75], v[90:91], v[110:111]
	v_pk_fma_f32 v[64:65], v[96:97], v[64:65], v[108:109]
	v_pk_fma_f32 v[66:67], v[66:67], v[90:91], v[110:111]
	v_pk_fma_f32 v[96:97], v[96:97], v[56:57], v[108:109]
	v_pk_fma_f32 v[90:91], v[90:91], v[58:59], v[110:111]
	v_cvt_pk_bf16_f32 v56, v86, v87
	v_cvt_pk_bf16_f32 v57, v84, v85
	v_cvt_pk_bf16_f32 v58, v80, v81
	v_cvt_pk_bf16_f32 v59, v98, v99
	v_pk_fma_f32 v[76:77], v[76:77], v[94:95], v[106:107]
	v_pk_fma_f32 v[100:101], v[120:121], v[92:93], v[112:113]
	global_store_dwordx4 v[78:79], v[56:59], off nt
	v_pk_fma_f32 v[68:69], v[94:95], v[68:69], v[106:107]
	v_pk_fma_f32 v[62:63], v[62:63], v[92:93], v[112:113]
	v_cvt_pk_bf16_f32 v56, v76, v77
	v_cvt_pk_bf16_f32 v57, v72, v73
	v_cvt_pk_bf16_f32 v58, v74, v75
	v_cvt_pk_bf16_f32 v59, v100, v101
	global_store_dwordx4 v[70:71], v[56:59], off nt
	v_pk_fma_f32 v[60:61], v[94:95], v[60:61], v[106:107]
	v_pk_fma_f32 v[34:35], v[92:93], v[34:35], v[112:113]
	v_cvt_pk_bf16_f32 v56, v68, v69
	v_cvt_pk_bf16_f32 v57, v64, v65
	v_cvt_pk_bf16_f32 v58, v66, v67
	v_cvt_pk_bf16_f32 v59, v62, v63
	global_store_dwordx4 v[122:123], v[56:59], off nt
	s_nop 1
	v_cvt_pk_bf16_f32 v56, v60, v61
	v_cvt_pk_bf16_f32 v57, v96, v97
	v_cvt_pk_bf16_f32 v58, v90, v91
	v_cvt_pk_bf16_f32 v59, v34, v35
	global_store_dwordx4 v[124:125], v[56:59], off nt
	global_load_dwordx4 v[56:59], v135, s[4:5]
	s_nop 0
	global_load_dwordx4 v[60:63], v135, s[4:5] offset:16
	global_load_dwordx4 v[64:67], v[48:49], off
	global_load_dwordx4 v[72:75], v[48:49], off offset:16
	global_load_dwordx4 v[84:87], v[116:117], off offset:2048
	global_load_dwordx4 v[90:93], v[116:117], off offset:2064
	s_waitcnt vmcnt(5)
	v_pk_add_f32 v[34:35], v[58:59], 1.0 op_sel_hi:[1,0]
	v_pk_add_f32 v[54:55], v[56:57], 1.0 op_sel_hi:[1,0]
	s_waitcnt vmcnt(4)
	v_pk_add_f32 v[56:57], v[62:63], 1.0 op_sel_hi:[1,0]
	v_pk_add_f32 v[58:59], v[60:61], 1.0 op_sel_hi:[1,0]
	s_waitcnt vmcnt(3)
	v_pk_mul_f32 v[34:35], v[66:67], v[34:35]
	v_pk_mul_f32 v[54:55], v[64:65], v[54:55]
	s_waitcnt vmcnt(2)
	v_pk_mul_f32 v[56:57], v[74:75], v[56:57]
	v_pk_mul_f32 v[58:59], v[72:73], v[58:59]
	s_waitcnt vmcnt(1)
	v_pk_fma_f32 v[14:15], v[14:15], v[34:35], v[86:87]
	v_pk_fma_f32 v[16:17], v[16:17], v[54:55], v[84:85]
	s_waitcnt vmcnt(0)
	v_pk_fma_f32 v[18:19], v[18:19], v[56:57], v[92:93]
	v_pk_fma_f32 v[20:21], v[20:21], v[58:59], v[90:91]
	v_pk_fma_f32 v[60:61], v[2:3], v[34:35], v[86:87]
	v_pk_fma_f32 v[62:63], v[4:5], v[54:55], v[84:85]
	v_cvt_pk_bf16_f32 v2, v16, v17
	v_cvt_pk_bf16_f32 v3, v14, v15
	v_cvt_pk_bf16_f32 v4, v20, v21
	v_cvt_pk_bf16_f32 v5, v18, v19
	v_pk_fma_f32 v[10:11], v[10:11], v[34:35], v[86:87]
	v_pk_fma_f32 v[12:13], v[12:13], v[54:55], v[84:85]
	v_pk_fma_f32 v[22:23], v[22:23], v[56:57], v[92:93]
	v_pk_fma_f32 v[24:25], v[24:25], v[58:59], v[90:91]
	global_store_dwordx4 v[78:79], v[2:5], off offset:1024 nt
	v_pk_fma_f32 v[26:27], v[26:27], v[56:57], v[92:93]
	v_pk_fma_f32 v[28:29], v[28:29], v[58:59], v[90:91]
	v_cvt_pk_bf16_f32 v2, v12, v13
	v_cvt_pk_bf16_f32 v3, v10, v11
	v_cvt_pk_bf16_f32 v4, v24, v25
	v_cvt_pk_bf16_f32 v5, v22, v23
	global_store_dwordx4 v[70:71], v[2:5], off offset:1024 nt
	v_pk_fma_f32 v[6:7], v[6:7], v[34:35], v[86:87]
	v_pk_fma_f32 v[8:9], v[8:9], v[54:55], v[84:85]
	v_cvt_pk_bf16_f32 v2, v62, v63
	v_cvt_pk_bf16_f32 v3, v60, v61
	v_cvt_pk_bf16_f32 v4, v28, v29
	v_cvt_pk_bf16_f32 v5, v26, v27
	v_pk_fma_f32 v[30:31], v[30:31], v[56:57], v[92:93]
	v_pk_fma_f32 v[32:33], v[32:33], v[58:59], v[90:91]
	global_store_dwordx4 v[122:123], v[2:5], off offset:1024 nt
	s_nop 1
	v_cvt_pk_bf16_f32 v2, v8, v9
	v_cvt_pk_bf16_f32 v3, v6, v7
	v_cvt_pk_bf16_f32 v4, v32, v33
	v_cvt_pk_bf16_f32 v5, v30, v31
	global_store_dwordx4 v[124:125], v[2:5], off offset:1024 nt
	s_cbranch_scc1 .LBB0_883

.LBB0_1195:
	s_ashr_i32 s11, s10, 31
	s_lshl_b64 s[14:15], s[10:11], 11
	v_lshl_add_u64 v[52:53], v[36:37], 0, s[14:15]
	v_add_co_u32_e32 v30, vcc, s44, v52
	s_add_i32 s46, s10, 1
	s_nop 0
	v_addc_co_u32_e32 v31, vcc, 0, v53, vcc
	s_add_i32 s6, s10, 2
	s_add_i32 s4, s10, 3
	global_load_dwordx4 v[2:5], v[52:53], off
	global_load_dwordx4 v[6:9], v[52:53], off offset:1024
	global_load_dwordx4 v[10:13], v[52:53], off offset:2048
	global_load_dwordx4 v[14:17], v[52:53], off offset:3072
	global_load_dwordx4 v[18:21], v[30:31], off
	global_load_dwordx4 v[22:25], v[30:31], off offset:1024
	global_load_dwordx4 v[26:29], v[30:31], off offset:2048
	s_ashr_i32 s47, s46, 31
	s_ashr_i32 s7, s6, 31
	s_ashr_i32 s5, s4, 31
	s_ashr_i32 s22, s13, 10
	s_lshl_b64 s[48:49], s[10:11], 6
	s_lshl_b64 s[20:21], s[46:47], 11
	s_lshl_b64 s[18:19], s[6:7], 11
	s_lshl_b64 s[16:17], s[4:5], 11
	s_add_u32 s48, s24, s48
	s_addc_u32 s49, s25, s49
	global_load_dwordx4 v[30:33], v[30:31], off offset:3072
	s_nop 0
	global_load_dwordx4 v[70:73], v35, s[48:49] offset:48
	global_load_dwordx4 v[74:77], v35, s[48:49] offset:32
	global_load_dwordx4 v[88:91], v35, s[48:49] offset:16
	global_load_dwordx4 v[148:151], v35, s[48:49]
	s_lshl_b64 s[46:47], s[46:47], 6
	s_add_u32 s46, s24, s46
	s_addc_u32 s47, s25, s47
	global_load_dwordx4 v[152:155], v35, s[46:47] offset:48
	global_load_dwordx4 v[156:159], v35, s[46:47] offset:32
	global_load_dwordx4 v[160:163], v35, s[46:47] offset:16
	global_load_dwordx4 v[164:167], v35, s[46:47]
	s_lshl_b64 s[6:7], s[6:7], 6
	s_add_u32 s6, s24, s6
	s_addc_u32 s7, s25, s7
	global_load_dwordx4 v[168:171], v35, s[6:7] offset:16
	global_load_dwordx4 v[172:175], v35, s[6:7]
	s_lshl_b64 s[4:5], s[4:5], 6
	s_add_u32 s4, s24, s4
	s_addc_u32 s5, s25, s5
	s_waitcnt vmcnt(0)
	v_lshlrev_b32_e32 v54, 16, v2
	v_and_b32_e32 v55, 0xffff0000, v2
	v_lshlrev_b32_e32 v58, 16, v3
	v_and_b32_e32 v59, 0xffff0000, v3
	v_lshl_add_u64 v[2:3], v[38:39], 0, s[14:15]
	v_lshlrev_b32_e32 v106, 16, v14
	v_and_b32_e32 v107, 0xffff0000, v14
	v_lshlrev_b32_e32 v108, 16, v15
	v_and_b32_e32 v109, 0xffff0000, v15
	v_lshlrev_b32_e32 v102, 16, v16
	v_and_b32_e32 v103, 0xffff0000, v16
	v_lshlrev_b32_e32 v104, 16, v17
	v_and_b32_e32 v105, 0xffff0000, v17
	v_lshlrev_b32_e32 v126, 16, v26
	v_and_b32_e32 v127, 0xffff0000, v26
	v_lshlrev_b32_e32 v130, 16, v27
	v_and_b32_e32 v131, 0xffff0000, v27
	v_lshlrev_b32_e32 v128, 16, v28
	v_and_b32_e32 v129, 0xffff0000, v28
	v_lshlrev_b32_e32 v132, 16, v29
	v_and_b32_e32 v133, 0xffff0000, v29
	global_load_dwordx4 v[26:29], v[2:3], off
	global_load_dwordx4 v[14:17], v[2:3], off offset:1024
	v_lshl_add_u64 v[2:3], v[38:39], 0, s[20:21]
	v_lshlrev_b32_e32 v62, 16, v10
	v_and_b32_e32 v63, 0xffff0000, v10
	v_lshlrev_b32_e32 v66, 16, v11
	v_and_b32_e32 v67, 0xffff0000, v11
	v_lshlrev_b32_e32 v64, 16, v12
	v_and_b32_e32 v65, 0xffff0000, v12
	v_lshlrev_b32_e32 v68, 16, v13
	v_and_b32_e32 v69, 0xffff0000, v13
	v_lshlrev_b32_e32 v98, 16, v22
	v_and_b32_e32 v99, 0xffff0000, v22
	v_lshlrev_b32_e32 v100, 16, v23
	v_and_b32_e32 v101, 0xffff0000, v23
	v_lshlrev_b32_e32 v92, 16, v24
	v_and_b32_e32 v93, 0xffff0000, v24
	v_lshlrev_b32_e32 v96, 16, v25
	v_and_b32_e32 v97, 0xffff0000, v25
	global_load_dwordx4 v[22:25], v[2:3], off
	global_load_dwordx4 v[10:13], v[2:3], off offset:1024
	v_lshl_add_u64 v[2:3], v[38:39], 0, s[18:19]
	v_lshlrev_b32_e32 v56, 16, v4
	v_and_b32_e32 v57, 0xffff0000, v4
	v_lshlrev_b32_e32 v60, 16, v5
	v_and_b32_e32 v61, 0xffff0000, v5
	v_lshlrev_b32_e32 v118, 16, v18
	v_and_b32_e32 v119, 0xffff0000, v18
	v_lshlrev_b32_e32 v122, 16, v19
	v_and_b32_e32 v123, 0xffff0000, v19
	v_lshlrev_b32_e32 v120, 16, v20
	v_and_b32_e32 v121, 0xffff0000, v20
	v_lshlrev_b32_e32 v124, 16, v21
	v_and_b32_e32 v125, 0xffff0000, v21
	global_load_dwordx4 v[176:179], v35, s[6:7] offset:48
	global_load_dwordx4 v[180:183], v35, s[6:7] offset:32
	global_load_dwordx4 v[18:21], v[2:3], off
	s_nop 0
	global_load_dwordx4 v[2:5], v[2:3], off offset:1024
	v_lshlrev_b32_e32 v114, 16, v6
	v_and_b32_e32 v115, 0xffff0000, v6
	v_lshlrev_b32_e32 v116, 16, v7
	v_and_b32_e32 v117, 0xffff0000, v7
	v_lshl_add_u64 v[6:7], v[38:39], 0, s[16:17]
	v_lshlrev_b32_e32 v110, 16, v8
	v_and_b32_e32 v111, 0xffff0000, v8
	v_lshlrev_b32_e32 v112, 16, v9
	v_and_b32_e32 v113, 0xffff0000, v9
	v_lshlrev_b32_e32 v82, 16, v30
	v_and_b32_e32 v83, 0xffff0000, v30
	v_lshlrev_b32_e32 v86, 16, v31
	v_and_b32_e32 v87, 0xffff0000, v31
	v_lshlrev_b32_e32 v78, 16, v32
	v_and_b32_e32 v79, 0xffff0000, v32
	v_lshlrev_b32_e32 v80, 16, v33
	v_and_b32_e32 v81, 0xffff0000, v33
	global_load_dwordx4 v[184:187], v35, s[4:5] offset:16
	global_load_dwordx4 v[188:191], v35, s[4:5]
	global_load_dwordx4 v[30:33], v[6:7], off
	s_nop 0
	global_load_dwordx4 v[6:9], v[6:7], off offset:1024
	v_mov_b32_e32 v84, v149
	v_mov_b32_e32 v85, v150
	v_mov_b32_e32 v149, v151
	v_pk_add_f32 v[84:85], v[84:85], v[148:149]
	global_load_dwordx4 v[148:151], v35, s[4:5] offset:48
	global_load_dwordx4 v[192:195], v35, s[4:5] offset:32
	v_mov_b32_e32 v94, v89
	v_mov_b32_e32 v95, v90
	v_mov_b32_e32 v89, v91
	v_pk_add_f32 v[88:89], v[94:95], v[88:89]
	v_pk_add_f32 v[84:85], v[84:85], v[84:85] op_sel:[0,1] op_sel_hi:[1,0]
	v_pk_add_f32 v[88:89], v[88:89], v[88:89] op_sel:[0,1] op_sel_hi:[1,0]
	v_add_f32_e32 v74, v74, v75
	v_add_f32_e32 v76, v76, v77
	v_mov_b32_e32 v85, v70
	v_mov_b32_e32 v89, v71
	v_mov_b32_e32 v75, v72
	v_mov_b32_e32 v77, v73
	v_pk_add_f32 v[70:71], v[84:85], v[88:89]
	v_pk_add_f32 v[72:73], v[74:75], v[76:77]
	v_mov_b32_e32 v74, v161
	v_pk_add_f32 v[70:71], v[70:71], v[72:73]
	v_mov_b32_e32 v72, v165
	v_mov_b32_e32 v73, v166
	v_mov_b32_e32 v165, v167
	v_mov_b32_e32 v75, v162
	v_mov_b32_e32 v161, v163
	v_pk_add_f32 v[72:73], v[72:73], v[164:165]
	v_pk_add_f32 v[74:75], v[74:75], v[160:161]
	v_pk_add_f32 v[72:73], v[72:73], v[72:73] op_sel:[0,1] op_sel_hi:[1,0]
	v_pk_add_f32 v[74:75], v[74:75], v[74:75] op_sel:[0,1] op_sel_hi:[1,0]
	v_add_f32_e32 v76, v156, v157
	v_add_f32_e32 v84, v158, v159
	v_mov_b32_e32 v73, v152
	v_mov_b32_e32 v75, v153
	v_mov_b32_e32 v77, v154
	v_mov_b32_e32 v85, v155
	v_pk_add_f32 v[72:73], v[72:73], v[74:75]
	v_pk_add_f32 v[74:75], v[76:77], v[84:85]
	s_waitcnt vmcnt(9)
	v_mov_b32_e32 v77, v179
	v_pk_add_f32 v[72:73], v[72:73], v[74:75]
	v_mov_b32_e32 v75, v70
	v_mov_b32_e32 v74, v72
	v_mov_b32_e32 v70, v73
	v_pk_add_f32 v[70:71], v[74:75], v[70:71]
	v_mov_b32_e32 v72, v169
	v_pk_fma_f32 v[70:71], v[70:71], s[12:13], v[50:51] op_sel_hi:[1,0,0]
	v_mov_b32_e32 v73, v170
	v_mul_f32_e32 v34, 0x4b800000, v71
	v_cmp_gt_f32_e32 vcc, s45, v71
	v_cmp_gt_f32_e64 s[4:5], s45, v70
	v_mov_b32_e32 v169, v171
	v_cndmask_b32_e32 v34, v71, v34, vcc
	v_rsq_f32_e32 v34, v34
	v_mul_f32_e32 v71, 0x4b800000, v70
	v_cndmask_b32_e64 v70, v70, v71, s[4:5]
	v_rsq_f32_e32 v70, v70
	v_mul_f32_e32 v71, 0x45800000, v34
	v_cndmask_b32_e32 v34, v34, v71, vcc
	v_mul_f32_e32 v136, 0.5, v34
	v_mul_f32_e32 v34, 0x45800000, v70
	v_cndmask_b32_e64 v34, v70, v34, s[4:5]
	v_mov_b32_e32 v70, v173
	v_mov_b32_e32 v71, v174
	v_mov_b32_e32 v173, v175
	v_pk_add_f32 v[70:71], v[70:71], v[172:173]
	v_pk_add_f32 v[72:73], v[72:73], v[168:169]
	v_pk_add_f32 v[70:71], v[70:71], v[70:71] op_sel:[0,1] op_sel_hi:[1,0]
	v_pk_add_f32 v[72:73], v[72:73], v[72:73] op_sel:[0,1] op_sel_hi:[1,0]
	s_waitcnt vmcnt(8)
	v_add_f32_e32 v74, v180, v181
	v_add_f32_e32 v76, v182, v183
	v_mov_b32_e32 v71, v176
	v_mov_b32_e32 v73, v177
	v_mov_b32_e32 v75, v178
	v_pk_add_f32 v[70:71], v[70:71], v[72:73]
	v_pk_add_f32 v[72:73], v[74:75], v[76:77]
	s_waitcnt vmcnt(5)
	v_mov_b32_e32 v74, v185
	v_pk_add_f32 v[70:71], v[70:71], v[72:73]
	s_waitcnt vmcnt(4)
	v_mov_b32_e32 v72, v189
	v_mov_b32_e32 v73, v190
	v_mov_b32_e32 v189, v191
	v_mov_b32_e32 v75, v186
	v_mov_b32_e32 v185, v187
	v_pk_add_f32 v[72:73], v[72:73], v[188:189]
	v_pk_add_f32 v[74:75], v[74:75], v[184:185]
	v_pk_add_f32 v[72:73], v[72:73], v[72:73] op_sel:[0,1] op_sel_hi:[1,0]
	v_pk_add_f32 v[74:75], v[74:75], v[74:75] op_sel:[0,1] op_sel_hi:[1,0]
	s_waitcnt vmcnt(0)
	v_add_f32_e32 v76, v192, v193
	v_add_f32_e32 v84, v194, v195
	v_mov_b32_e32 v73, v148
	v_mov_b32_e32 v75, v149
	v_mov_b32_e32 v77, v150
	v_mov_b32_e32 v85, v151
	v_pk_add_f32 v[72:73], v[72:73], v[74:75]
	v_pk_add_f32 v[74:75], v[76:77], v[84:85]
	v_mul_f32_e32 v34, 0.5, v34
	v_pk_add_f32 v[72:73], v[72:73], v[74:75]
	v_mov_b32_e32 v75, v70
	v_mov_b32_e32 v74, v72
	v_mov_b32_e32 v70, v73
	v_pk_add_f32 v[70:71], v[74:75], v[70:71]
	s_nop 0
	v_pk_fma_f32 v[70:71], v[70:71], s[12:13], v[50:51] op_sel_hi:[1,0,0]
	s_nop 0
	v_mul_f32_e32 v72, 0x4b800000, v71
	v_cmp_gt_f32_e32 vcc, s45, v71
	v_cmp_gt_f32_e64 s[4:5], s45, v70
	s_nop 0
	v_cndmask_b32_e32 v71, v71, v72, vcc
	v_rsq_f32_e32 v71, v71
	v_mul_f32_e32 v72, 0x4b800000, v70
	v_cndmask_b32_e64 v70, v70, v72, s[4:5]
	v_rsq_f32_e32 v70, v70
	v_mul_f32_e32 v72, 0x45800000, v71
	v_cndmask_b32_e32 v71, v71, v72, vcc
	v_mul_f32_e32 v138, 0.5, v71
	v_mul_f32_e32 v71, 0x45800000, v70
	v_cndmask_b32_e64 v70, v70, v71, s[4:5]
	v_mul_f32_e32 v134, 0.5, v70
	s_mul_i32 s4, s22, 9
	s_ashr_i32 s5, s4, 31
	s_lshl_b64 s[22:23], s[4:5], 12
	s_add_u32 s4, s70, s22
	s_addc_u32 s5, s71, s23
	s_add_u32 s4, s4, 0x8000
	s_addc_u32 s5, s5, 0
	global_load_dwordx4 v[70:73], v[40:41], off
	global_load_dwordx4 v[74:77], v135, s[4:5]
	global_load_dwordx4 v[88:91], v135, s[4:5] offset:16
	global_load_dwordx4 v[148:151], v[40:41], off offset:16
	global_load_dwordx4 v[152:155], v137, s[4:5]
	global_load_dwordx4 v[156:159], v[42:43], off
	global_load_dwordx4 v[160:163], v[42:43], off offset:16
	global_load_dwordx4 v[164:167], v137, s[4:5] offset:16
	v_lshlrev_b32_e32 v170, 16, v24
	v_and_b32_e32 v171, 0xffff0000, v24
	v_lshlrev_b32_e32 v172, 16, v18
	v_and_b32_e32 v173, 0xffff0000, v18
	v_lshlrev_b32_e32 v18, 16, v19
	v_and_b32_e32 v19, 0xffff0000, v19
	v_lshlrev_b32_e32 v168, 16, v22
	v_and_b32_e32 v169, 0xffff0000, v22
	v_lshlrev_b32_e32 v22, 16, v23
	v_and_b32_e32 v23, 0xffff0000, v23
	v_lshlrev_b32_e32 v174, 16, v20
	v_and_b32_e32 v175, 0xffff0000, v20
	v_lshlrev_b32_e32 v20, 16, v21
	v_and_b32_e32 v21, 0xffff0000, v21
	v_pk_mul_f32 v[170:171], v[34:35], v[170:171] op_sel_hi:[0,1]
	v_pk_mul_f32 v[18:19], v[138:139], v[18:19] op_sel_hi:[0,1]
	v_lshlrev_b32_e32 v84, 16, v26
	v_and_b32_e32 v85, 0xffff0000, v26
	v_lshlrev_b32_e32 v26, 16, v27
	v_and_b32_e32 v27, 0xffff0000, v27
	v_lshlrev_b32_e32 v94, 16, v28
	v_and_b32_e32 v95, 0xffff0000, v28
	v_lshlrev_b32_e32 v28, 16, v29
	v_and_b32_e32 v29, 0xffff0000, v29
	v_pk_mul_f32 v[168:169], v[34:35], v[168:169] op_sel_hi:[0,1]
	v_pk_mul_f32 v[22:23], v[34:35], v[22:23] op_sel_hi:[0,1]
	v_pk_mul_f32 v[20:21], v[138:139], v[20:21] op_sel_hi:[0,1]
	v_lshlrev_b32_e32 v24, 16, v25
	v_and_b32_e32 v25, 0xffff0000, v25
	v_lshlrev_b32_e32 v176, 16, v30
	v_and_b32_e32 v177, 0xffff0000, v30
	v_lshlrev_b32_e32 v30, 16, v31
	v_and_b32_e32 v31, 0xffff0000, v31
	v_pk_mul_f32 v[84:85], v[136:137], v[84:85] op_sel_hi:[0,1]
	v_pk_mul_f32 v[26:27], v[136:137], v[26:27] op_sel_hi:[0,1]
	v_pk_mul_f32 v[28:29], v[136:137], v[28:29] op_sel_hi:[0,1]
	v_lshlrev_b32_e32 v178, 16, v32
	v_and_b32_e32 v179, 0xffff0000, v32
	v_lshlrev_b32_e32 v32, 16, v33
	v_and_b32_e32 v33, 0xffff0000, v33
	v_pk_mul_f32 v[182:183], v[136:137], v[94:95] op_sel_hi:[0,1]
	v_pk_mul_f32 v[24:25], v[34:35], v[24:25] op_sel_hi:[0,1]
	v_pk_mul_f32 v[30:31], v[134:135], v[30:31] op_sel_hi:[0,1]
	v_pk_mul_f32 v[32:33], v[134:135], v[32:33] op_sel_hi:[0,1]
	v_lshlrev_b32_e32 v180, 16, v14
	v_and_b32_e32 v181, 0xffff0000, v14
	v_lshlrev_b32_e32 v14, 16, v15
	v_and_b32_e32 v15, 0xffff0000, v15
	v_pk_mul_f32 v[14:15], v[136:137], v[14:15] op_sel_hi:[0,1]
	v_pk_mul_f32 v[172:173], v[138:139], v[172:173] op_sel_hi:[0,1]
	v_pk_mul_f32 v[174:175], v[138:139], v[174:175] op_sel_hi:[0,1]
	v_pk_mul_f32 v[176:177], v[134:135], v[176:177] op_sel_hi:[0,1]
	v_pk_mul_f32 v[178:179], v[134:135], v[178:179] op_sel_hi:[0,1]
	s_waitcnt vmcnt(6)
	v_pk_mul_f32 v[184:185], v[76:77], v[72:73]
	v_pk_mul_f32 v[186:187], v[74:75], v[70:71]
	s_waitcnt vmcnt(4)
	v_pk_mul_f32 v[148:149], v[88:89], v[148:149]
	v_pk_mul_f32 v[150:151], v[90:91], v[150:151]
	v_pk_fma_f32 v[74:75], v[148:149], v[170:171], v[64:65]
	v_pk_fma_f32 v[64:65], v[184:185], v[18:19], v[122:123]
	v_lshlrev_b32_e32 v18, 16, v16
	v_and_b32_e32 v19, 0xffff0000, v16
	s_waitcnt vmcnt(2)
	v_pk_mul_f32 v[154:155], v[154:155], v[158:159]
	s_waitcnt vmcnt(0)
	v_pk_mul_f32 v[158:159], v[164:165], v[160:161]
	v_pk_fma_f32 v[72:73], v[184:185], v[22:23], v[66:67]
	v_pk_fma_f32 v[76:77], v[186:187], v[168:169], v[62:63]
	v_pk_fma_f32 v[62:63], v[150:151], v[20:21], v[124:125]
	v_lshlrev_b32_e32 v20, 16, v17
	v_and_b32_e32 v21, 0xffff0000, v17
	v_pk_mul_f32 v[22:23], v[136:137], v[18:19] op_sel_hi:[0,1]
	v_pk_fma_f32 v[90:91], v[184:185], v[26:27], v[58:59]
	v_pk_fma_f32 v[94:95], v[186:187], v[84:85], v[54:55]
	v_pk_fma_f32 v[84:85], v[28:29], v[150:151], v[60:61]
	v_pk_mul_f32 v[18:19], v[136:137], v[20:21] op_sel_hi:[0,1]
	v_pk_fma_f32 v[20:21], v[22:23], v[158:159], v[110:111]
	v_lshlrev_b32_e32 v22, 16, v10
	v_and_b32_e32 v23, 0xffff0000, v10
	v_lshlrev_b32_e32 v26, 16, v13
	v_and_b32_e32 v27, 0xffff0000, v13
	v_lshlrev_b32_e32 v28, 16, v4
	v_and_b32_e32 v29, 0xffff0000, v4
	v_pk_fma_f32 v[88:89], v[182:183], v[148:149], v[56:57]
	v_pk_fma_f32 v[70:71], v[150:151], v[24:25], v[68:69]
	v_pk_fma_f32 v[56:57], v[184:185], v[30:31], v[130:131]
	v_lshlrev_b32_e32 v24, 16, v12
	v_and_b32_e32 v25, 0xffff0000, v12
	v_pk_mul_f32 v[12:13], v[34:35], v[22:23] op_sel_hi:[0,1]
	v_pk_mul_f32 v[22:23], v[34:35], v[26:27] op_sel_hi:[0,1]
	v_lshlrev_b32_e32 v26, 16, v2
	v_and_b32_e32 v27, 0xffff0000, v2
	v_lshlrev_b32_e32 v30, 16, v5
	v_and_b32_e32 v31, 0xffff0000, v5
	v_pk_mul_f32 v[28:29], v[138:139], v[28:29] op_sel_hi:[0,1]
	v_pk_fma_f32 v[54:55], v[150:151], v[32:33], v[132:133]
	v_pk_mul_f32 v[4:5], v[138:139], v[26:27] op_sel_hi:[0,1]
	v_pk_mul_f32 v[26:27], v[138:139], v[30:31] op_sel_hi:[0,1]
	v_pk_fma_f32 v[28:29], v[158:159], v[28:29], v[92:93]
	v_lshlrev_b32_e32 v30, 16, v6
	v_and_b32_e32 v31, 0xffff0000, v6
	v_lshlrev_b32_e32 v32, 16, v8
	v_and_b32_e32 v33, 0xffff0000, v8
	v_lshlrev_b32_e32 v92, 16, v9
	v_and_b32_e32 v93, 0xffff0000, v9
	v_pk_mul_f32 v[152:153], v[152:153], v[156:157]
	v_pk_mul_f32 v[156:157], v[166:167], v[162:163]
	v_pk_mul_f32 v[8:9], v[134:135], v[30:31] op_sel_hi:[0,1]
	v_pk_mul_f32 v[32:33], v[134:135], v[32:33] op_sel_hi:[0,1]
	v_pk_mul_f32 v[30:31], v[134:135], v[92:93] op_sel_hi:[0,1]
	v_pk_mul_f32 v[16:17], v[136:137], v[180:181] op_sel_hi:[0,1]
	v_pk_fma_f32 v[30:31], v[156:157], v[30:31], v[80:81]
	v_pk_fma_f32 v[32:33], v[158:159], v[32:33], v[78:79]
	v_cvt_pk_bf16_f32 v78, v94, v95
	v_cvt_pk_bf16_f32 v79, v90, v91
	v_cvt_pk_bf16_f32 v80, v88, v89
	v_cvt_pk_bf16_f32 v81, v84, v85
	v_pk_fma_f32 v[14:15], v[14:15], v[154:155], v[116:117]
	v_pk_fma_f32 v[16:17], v[16:17], v[152:153], v[114:115]
	v_pk_fma_f32 v[18:19], v[18:19], v[156:157], v[112:113]
	v_lshlrev_b32_e32 v10, 16, v11
	v_and_b32_e32 v11, 0xffff0000, v11
	global_store_dwordx4 v[52:53], v[78:81], off nt
	v_pk_mul_f32 v[10:11], v[34:35], v[10:11] op_sel_hi:[0,1]
	v_pk_mul_f32 v[24:25], v[34:35], v[24:25] op_sel_hi:[0,1]
	v_cvt_pk_bf16_f32 v78, v16, v17
	v_cvt_pk_bf16_f32 v79, v14, v15
	v_cvt_pk_bf16_f32 v80, v20, v21
	v_cvt_pk_bf16_f32 v81, v18, v19
	global_store_dwordx4 v[52:53], v[78:81], off offset:1024 nt
	v_lshl_add_u64 v[52:53], v[36:37], 0, s[20:21]
	v_pk_fma_f32 v[10:11], v[154:155], v[10:11], v[108:109]
	v_cvt_pk_bf16_f32 v78, v76, v77
	v_cvt_pk_bf16_f32 v79, v72, v73
	v_cvt_pk_bf16_f32 v80, v74, v75
	v_cvt_pk_bf16_f32 v81, v70, v71
	v_pk_fma_f32 v[12:13], v[152:153], v[12:13], v[106:107]
	v_pk_fma_f32 v[22:23], v[22:23], v[156:157], v[104:105]
	v_pk_fma_f32 v[24:25], v[24:25], v[158:159], v[102:103]
	v_lshlrev_b32_e32 v2, 16, v3
	v_and_b32_e32 v3, 0xffff0000, v3
	global_store_dwordx4 v[52:53], v[78:81], off nt
	v_pk_fma_f32 v[68:69], v[186:187], v[172:173], v[118:119]
	v_pk_fma_f32 v[66:67], v[148:149], v[174:175], v[120:121]
	v_cvt_pk_bf16_f32 v78, v12, v13
	v_cvt_pk_bf16_f32 v79, v10, v11
	v_cvt_pk_bf16_f32 v80, v24, v25
	v_cvt_pk_bf16_f32 v81, v22, v23
	v_pk_mul_f32 v[2:3], v[138:139], v[2:3] op_sel_hi:[0,1]
	global_store_dwordx4 v[52:53], v[78:81], off offset:1024 nt
	v_lshl_add_u64 v[52:53], v[36:37], 0, s[18:19]
	v_pk_fma_f32 v[2:3], v[154:155], v[2:3], v[100:101]
	v_cvt_pk_bf16_f32 v78, v68, v69
	v_cvt_pk_bf16_f32 v79, v64, v65
	v_cvt_pk_bf16_f32 v80, v66, v67
	v_cvt_pk_bf16_f32 v81, v62, v63
	v_pk_fma_f32 v[4:5], v[152:153], v[4:5], v[98:99]
	v_pk_fma_f32 v[26:27], v[156:157], v[26:27], v[96:97]
	v_lshlrev_b32_e32 v6, 16, v7
	v_and_b32_e32 v7, 0xffff0000, v7
	global_store_dwordx4 v[52:53], v[78:81], off nt
	v_pk_fma_f32 v[60:61], v[186:187], v[176:177], v[126:127]
	v_pk_fma_f32 v[58:59], v[148:149], v[178:179], v[128:129]
	v_cvt_pk_bf16_f32 v78, v4, v5
	v_cvt_pk_bf16_f32 v79, v2, v3
	v_cvt_pk_bf16_f32 v80, v28, v29
	v_cvt_pk_bf16_f32 v81, v26, v27
	v_pk_mul_f32 v[6:7], v[134:135], v[6:7] op_sel_hi:[0,1]
	global_store_dwordx4 v[52:53], v[78:81], off offset:1024 nt
	v_lshl_add_u64 v[52:53], v[36:37], 0, s[16:17]
	v_pk_fma_f32 v[6:7], v[154:155], v[6:7], v[86:87]
	v_cvt_pk_bf16_f32 v78, v60, v61
	v_cvt_pk_bf16_f32 v79, v56, v57
	v_cvt_pk_bf16_f32 v80, v58, v59
	v_cvt_pk_bf16_f32 v81, v54, v55
	v_pk_fma_f32 v[8:9], v[152:153], v[8:9], v[82:83]
	global_store_dwordx4 v[52:53], v[78:81], off nt
	s_nop 1
	v_cvt_pk_bf16_f32 v78, v8, v9
	v_cvt_pk_bf16_f32 v79, v6, v7
	v_cvt_pk_bf16_f32 v80, v32, v33
	v_cvt_pk_bf16_f32 v81, v30, v31
	global_store_dwordx4 v[52:53], v[78:81], off offset:1024 nt
	v_pk_mul_f32 v[52:53], v[90:91], v[90:91]
	s_nop 0
	v_pk_mul_f32 v[78:79], v[94:95], v[94:95]
	v_mul_f32_e32 v34, v20, v20
	v_pk_mov_b32 v[80:81], v[78:79], v[52:53] op_sel:[1,0]
	v_mov_b32_e32 v79, v53
	v_pk_add_f32 v[52:53], v[80:81], v[78:79]
	v_pk_mul_f32 v[78:79], v[84:85], v[84:85]
	v_pk_mul_f32 v[80:81], v[88:89], v[88:89]
	v_pk_add_f32 v[52:53], v[52:53], v[52:53] op_sel:[0,1] op_sel_hi:[1,0]
	v_pk_mov_b32 v[82:83], v[80:81], v[78:79] op_sel:[1,0]
	v_mov_b32_e32 v81, v79
	v_pk_add_f32 v[78:79], v[82:83], v[80:81]
	v_mul_f32_e32 v80, v21, v21
	v_pk_add_f32 v[78:79], v[78:79], v[78:79] op_sel:[0,1] op_sel_hi:[1,0]
	v_mov_b32_e32 v53, v34
	v_mov_b32_e32 v79, v80
	v_mul_f32_e32 v34, v17, v17
	v_mul_f32_e32 v81, v18, v18
	v_pk_add_f32 v[52:53], v[52:53], v[78:79]
	v_pk_fma_f32 v[78:79], v[16:17], v[16:17], v[34:35] op_sel_hi:[1,1,0]
	v_mul_f32_e32 v34, v15, v15
	v_mul_f32_e32 v82, v19, v19
	v_mov_b32_e32 v79, v81
	v_pk_fma_f32 v[80:81], v[14:15], v[14:15], v[34:35] op_sel_hi:[1,1,0]
	v_cmp_lt_i32_e32 vcc, v141, v140
	v_mov_b32_e32 v81, v82
	v_pk_add_f32 v[78:79], v[78:79], v[80:81]
	v_pk_mul_f32 v[80:81], v[76:77], v[76:77]
	v_pk_add_f32 v[52:53], v[52:53], v[78:79]
	v_pk_mul_f32 v[78:79], v[72:73], v[72:73]
	v_cndmask_b32_e32 v34, v139, v141, vcc
	v_pk_mov_b32 v[82:83], v[80:81], v[78:79] op_sel:[1,0]
	v_mov_b32_e32 v81, v79
	v_pk_add_f32 v[78:79], v[82:83], v[80:81]
	v_pk_mul_f32 v[80:81], v[70:71], v[70:71]
	v_pk_mul_f32 v[82:83], v[74:75], v[74:75]
	v_lshlrev_b32_e32 v98, 2, v34
	v_pk_mov_b32 v[86:87], v[82:83], v[80:81] op_sel:[1,0]
	v_mov_b32_e32 v83, v81
	v_mul_f32_e32 v34, v13, v13
	v_pk_add_f32 v[80:81], v[86:87], v[82:83]
	v_mul_f32_e32 v86, v24, v24
	v_pk_fma_f32 v[82:83], v[12:13], v[12:13], v[34:35] op_sel_hi:[1,1,0]
	v_mul_f32_e32 v34, v11, v11
	v_mul_f32_e32 v92, v25, v25
	v_mul_f32_e32 v93, v22, v22
	v_mul_f32_e32 v96, v23, v23
	v_mov_b32_e32 v83, v86
	v_pk_fma_f32 v[86:87], v[10:11], v[10:11], v[34:35] op_sel_hi:[1,1,0]
	v_pk_add_f32 v[78:79], v[78:79], v[78:79] op_sel:[0,1] op_sel_hi:[1,0]
	v_pk_add_f32 v[80:81], v[80:81], v[80:81] op_sel:[0,1] op_sel_hi:[1,0]
	v_mov_b32_e32 v87, v92
	v_mov_b32_e32 v79, v93
	v_mov_b32_e32 v81, v96
	v_pk_add_f32 v[82:83], v[82:83], v[86:87]
	v_pk_add_f32 v[78:79], v[78:79], v[80:81]
	v_cmp_lt_i32_e32 vcc, v142, v140
	v_pk_add_f32 v[78:79], v[82:83], v[78:79]
	v_mov_b32_e32 v81, v52
	v_mov_b32_e32 v80, v78
	v_mov_b32_e32 v52, v79
	v_cndmask_b32_e32 v34, v139, v142, vcc
	v_cmp_lt_i32_e32 vcc, v143, v140
	v_pk_add_f32 v[52:53], v[80:81], v[52:53]
	v_lshlrev_b32_e32 v99, 2, v34
	v_cndmask_b32_e32 v34, v139, v143, vcc
	v_cmp_lt_i32_e32 vcc, v144, v140
	v_pk_mul_f32 v[80:81], v[64:65], v[64:65]
	v_pk_mul_f32 v[82:83], v[68:69], v[68:69]
	ds_bpermute_b32 v79, v98, v53
	ds_bpermute_b32 v78, v98, v52
	v_lshlrev_b32_e32 v100, 2, v34
	v_cndmask_b32_e32 v34, v139, v144, vcc
	v_cmp_lt_i32_e32 vcc, v145, v140
	v_pk_mov_b32 v[86:87], v[82:83], v[80:81] op_sel:[1,0]
	v_mov_b32_e32 v83, v81
	v_lshlrev_b32_e32 v101, 2, v34
	v_cndmask_b32_e32 v34, v139, v145, vcc
	v_pk_add_f32 v[80:81], v[86:87], v[82:83]
	v_pk_mul_f32 v[82:83], v[62:63], v[62:63]
	v_pk_mul_f32 v[86:87], v[66:67], v[66:67]
	v_lshlrev_b32_e32 v102, 2, v34
	v_pk_mov_b32 v[92:93], v[86:87], v[82:83] op_sel:[1,0]
	v_mov_b32_e32 v87, v83
	v_mul_f32_e32 v34, v4, v4
	v_pk_add_f32 v[82:83], v[92:93], v[86:87]
	v_pk_fma_f32 v[86:87], v[4:5], v[4:5], v[34:35] op_sel_hi:[1,1,0]
	v_mul_f32_e32 v34, v2, v2
	v_pk_add_f32 v[80:81], v[80:81], v[80:81] op_sel_hi:[0,1]
	v_pk_add_f32 v[82:83], v[82:83], v[82:83] op_sel_hi:[0,1]
	v_pk_fma_f32 v[92:93], v[2:3], v[2:3], v[34:35] op_sel_hi:[1,1,0]
	s_waitcnt lgkmcnt(0)
	v_pk_add_f32 v[52:53], v[52:53], v[78:79]
	v_mul_f32_e32 v86, v28, v28
	v_mul_f32_e32 v92, v29, v29
	v_mul_f32_e32 v80, v26, v26
	v_mul_f32_e32 v82, v27, v27
	ds_bpermute_b32 v79, v99, v53
	ds_bpermute_b32 v78, v99, v52
	v_pk_add_f32 v[86:87], v[86:87], v[92:93]
	v_pk_add_f32 v[80:81], v[80:81], v[82:83]
	v_pk_mul_f32 v[82:83], v[56:57], v[56:57]
	v_pk_add_f32 v[80:81], v[86:87], v[80:81]
	v_pk_mul_f32 v[86:87], v[60:61], v[60:61]
	v_mul_f32_e32 v34, v8, v8
	v_pk_mov_b32 v[92:93], v[86:87], v[82:83] op_sel:[1,0]
	v_mov_b32_e32 v87, v83
	v_pk_add_f32 v[82:83], v[92:93], v[86:87]
	v_pk_mul_f32 v[86:87], v[54:55], v[54:55]
	v_pk_mul_f32 v[92:93], v[58:59], v[58:59]
	s_waitcnt lgkmcnt(0)
	v_pk_add_f32 v[52:53], v[52:53], v[78:79]
	v_pk_mov_b32 v[96:97], v[92:93], v[86:87] op_sel:[1,0]
	v_mov_b32_e32 v93, v87
	v_pk_add_f32 v[86:87], v[96:97], v[92:93]
	v_pk_fma_f32 v[92:93], v[8:9], v[8:9], v[34:35] op_sel_hi:[1,1,0]
	v_mul_f32_e32 v34, v6, v6
	ds_bpermute_b32 v79, v100, v53
	ds_bpermute_b32 v78, v100, v52
	v_pk_add_f32 v[82:83], v[82:83], v[82:83] op_sel_hi:[0,1]
	v_pk_add_f32 v[86:87], v[86:87], v[86:87] op_sel_hi:[0,1]
	v_pk_fma_f32 v[96:97], v[6:7], v[6:7], v[34:35] op_sel_hi:[1,1,0]
	v_mul_f32_e32 v92, v32, v32
	v_mul_f32_e32 v96, v33, v33
	v_mul_f32_e32 v82, v30, v30
	v_mul_f32_e32 v86, v31, v31
	v_pk_add_f32 v[92:93], v[92:93], v[96:97]
	v_pk_add_f32 v[82:83], v[82:83], v[86:87]
	v_mov_b32_e32 v87, v80
	v_pk_add_f32 v[82:83], v[92:93], v[82:83]
	s_waitcnt lgkmcnt(0)
	v_pk_add_f32 v[52:53], v[52:53], v[78:79]
	v_mov_b32_e32 v86, v82
	v_mov_b32_e32 v80, v83
	v_pk_add_f32 v[80:81], v[86:87], v[80:81]
	ds_bpermute_b32 v79, v101, v53
	ds_bpermute_b32 v78, v101, v52
	ds_bpermute_b32 v83, v98, v81
	ds_bpermute_b32 v82, v98, v80
	v_cmp_lt_i32_e32 vcc, v146, v140
	s_waitcnt lgkmcnt(2)
	v_pk_add_f32 v[52:53], v[52:53], v[78:79]
	ds_bpermute_b32 v79, v102, v53
	s_waitcnt lgkmcnt(1)
	v_pk_add_f32 v[80:81], v[80:81], v[82:83]
	ds_bpermute_b32 v78, v102, v52
	ds_bpermute_b32 v83, v99, v81
	ds_bpermute_b32 v82, v99, v80
	v_cndmask_b32_e32 v34, v139, v146, vcc
	v_lshlrev_b32_e32 v34, 2, v34
	s_waitcnt lgkmcnt(2)
	v_pk_add_f32 v[52:53], v[52:53], v[78:79]
	ds_bpermute_b32 v79, v34, v53
	s_waitcnt lgkmcnt(1)
	v_pk_add_f32 v[80:81], v[80:81], v[82:83]
	ds_bpermute_b32 v78, v34, v52
	ds_bpermute_b32 v83, v100, v81
	ds_bpermute_b32 v82, v100, v80
	s_waitcnt lgkmcnt(2)
	v_pk_add_f32 v[52:53], v[52:53], v[78:79]
	s_nop 0
	v_pk_fma_f32 v[52:53], v[52:53], s[12:13], v[50:51] op_sel_hi:[1,0,0]
	s_waitcnt lgkmcnt(0)
	v_pk_add_f32 v[78:79], v[80:81], v[82:83]
	ds_bpermute_b32 v81, v101, v79
	ds_bpermute_b32 v80, v101, v78
	v_mul_f32_e32 v82, 0x4b800000, v53
	v_cmp_gt_f32_e32 vcc, s45, v53
	v_cmp_gt_f32_e64 s[4:5], s45, v52
	s_waitcnt lgkmcnt(0)
	v_pk_add_f32 v[78:79], v[78:79], v[80:81]
	ds_bpermute_b32 v81, v102, v79
	ds_bpermute_b32 v80, v102, v78
	v_cndmask_b32_e32 v53, v53, v82, vcc
	v_rsq_f32_e32 v82, v53
	v_mul_f32_e32 v53, 0x4b800000, v52
	v_cndmask_b32_e64 v52, v52, v53, s[4:5]
	v_rsq_f32_e32 v83, v52
	s_waitcnt lgkmcnt(0)
	v_pk_add_f32 v[52:53], v[78:79], v[80:81]
	ds_bpermute_b32 v79, v34, v53
	ds_bpermute_b32 v78, v34, v52
	v_mul_f32_e32 v34, 0x45800000, v82
	v_cndmask_b32_e32 v86, v82, v34, vcc
	v_mul_f32_e32 v34, 0x45800000, v83
	v_cndmask_b32_e64 v80, v83, v34, s[4:5]
	s_waitcnt lgkmcnt(0)
	v_pk_add_f32 v[52:53], v[52:53], v[78:79]
	s_add_u32 s4, s68, s22
	v_pk_fma_f32 v[52:53], v[52:53], s[12:13], v[50:51] op_sel_hi:[1,0,0]
	s_addc_u32 s5, s69, s23
	v_mul_f32_e32 v78, 0x4b800000, v53
	v_cmp_gt_f32_e32 vcc, s45, v53
	v_cmp_gt_f32_e64 s[6:7], s45, v52
	s_nop 0
	v_cndmask_b32_e32 v53, v53, v78, vcc
	v_mul_f32_e32 v78, 0x4b800000, v52
	v_rsq_f32_e32 v53, v53
	v_cndmask_b32_e64 v52, v52, v78, s[6:7]
	v_rsq_f32_e32 v52, v52
	v_mul_f32_e32 v34, 0x45800000, v53
	v_cndmask_b32_e32 v78, v53, v34, vcc
	v_mul_f32_e32 v34, 0x45800000, v52
	v_cndmask_b32_e64 v34, v52, v34, s[6:7]
	s_add_u32 s6, s4, 0x1000
	s_addc_u32 s7, s5, 0
	global_load_dwordx4 v[96:99], v135, s[6:7]
	global_load_dwordx4 v[100:103], v135, s[6:7] offset:16
	global_load_dwordx4 v[104:107], v[44:45], off
	global_load_dwordx4 v[108:111], v[44:45], off offset:16
	global_load_dwordx4 v[112:115], v135, s[4:5]
	global_load_dwordx4 v[116:119], v135, s[4:5] offset:16
	v_pk_mul_f32 v[82:83], v[94:95], v[86:87] op_sel_hi:[1,0]
	v_pk_mul_f32 v[90:91], v[90:91], v[86:87] op_sel_hi:[1,0]
	v_pk_mul_f32 v[88:89], v[88:89], v[86:87] op_sel_hi:[1,0]
	v_pk_mul_f32 v[84:85], v[84:85], v[86:87] op_sel_hi:[1,0]
	v_pk_mul_f32 v[76:77], v[76:77], v[80:81] op_sel_hi:[1,0]
	v_pk_mul_f32 v[72:73], v[72:73], v[80:81] op_sel_hi:[1,0]
	v_pk_mul_f32 v[68:69], v[68:69], v[78:79] op_sel_hi:[1,0]
	v_pk_mul_f32 v[64:65], v[64:65], v[78:79] op_sel_hi:[1,0]
	v_pk_mul_f32 v[60:61], v[60:61], v[34:35] op_sel_hi:[1,0]
	v_pk_mul_f32 v[56:57], v[56:57], v[34:35] op_sel_hi:[1,0]
	v_pk_mul_f32 v[54:55], v[54:55], v[34:35] op_sel_hi:[1,0]
	v_lshl_add_u64 v[52:53], v[48:49], 0, s[14:15]
	v_pk_mul_f32 v[74:75], v[74:75], v[80:81] op_sel_hi:[1,0]
	v_pk_mul_f32 v[92:93], v[70:71], v[80:81] op_sel_hi:[1,0]
	v_lshl_add_u64 v[70:71], v[48:49], 0, s[20:21]
	v_pk_mul_f32 v[66:67], v[66:67], v[78:79] op_sel_hi:[1,0]
	v_pk_mul_f32 v[62:63], v[62:63], v[78:79] op_sel_hi:[1,0]
	v_lshl_add_u64 v[94:95], v[48:49], 0, s[18:19]
	v_pk_mul_f32 v[58:59], v[58:59], v[34:35] op_sel_hi:[1,0]
	v_lshl_add_u64 v[120:121], v[48:49], 0, s[16:17]
	v_pk_mul_f32 v[16:17], v[16:17], v[86:87] op_sel_hi:[1,0]
	v_pk_mul_f32 v[14:15], v[14:15], v[86:87] op_sel_hi:[1,0]
	v_pk_mul_f32 v[20:21], v[20:21], v[86:87] op_sel_hi:[1,0]
	v_pk_mul_f32 v[18:19], v[18:19], v[86:87] op_sel_hi:[1,0]
	v_pk_mul_f32 v[4:5], v[4:5], v[78:79] op_sel_hi:[1,0]
	v_pk_mul_f32 v[2:3], v[2:3], v[78:79] op_sel_hi:[1,0]
	v_pk_mul_f32 v[12:13], v[12:13], v[80:81] op_sel_hi:[1,0]
	v_pk_mul_f32 v[10:11], v[10:11], v[80:81] op_sel_hi:[1,0]
	v_pk_mul_f32 v[24:25], v[24:25], v[80:81] op_sel_hi:[1,0]
	v_pk_mul_f32 v[22:23], v[22:23], v[80:81] op_sel_hi:[1,0]
	v_pk_mul_f32 v[28:29], v[28:29], v[78:79] op_sel_hi:[1,0]
	v_pk_mul_f32 v[26:27], v[26:27], v[78:79] op_sel_hi:[1,0]
	s_add_i32 s13, s13, s28
	s_add_i32 s10, s10, s29
	v_pk_mul_f32 v[8:9], v[8:9], v[34:35] op_sel_hi:[1,0]
	v_pk_mul_f32 v[6:7], v[6:7], v[34:35] op_sel_hi:[1,0]
	v_pk_mul_f32 v[32:33], v[32:33], v[34:35] op_sel_hi:[1,0]
	v_pk_mul_f32 v[30:31], v[30:31], v[34:35] op_sel_hi:[1,0]
	s_cmpk_lt_i32 s13, 0x2000
	s_waitcnt vmcnt(5)
	v_pk_add_f32 v[98:99], v[98:99], 1.0 op_sel_hi:[1,0]
	v_pk_add_f32 v[96:97], v[96:97], 1.0 op_sel_hi:[1,0]
	s_waitcnt vmcnt(4)
	v_pk_add_f32 v[102:103], v[102:103], 1.0 op_sel_hi:[1,0]
	v_pk_add_f32 v[100:101], v[100:101], 1.0 op_sel_hi:[1,0]
	s_waitcnt vmcnt(3)
	v_pk_mul_f32 v[98:99], v[106:107], v[98:99]
	v_pk_mul_f32 v[96:97], v[104:105], v[96:97]
	s_waitcnt vmcnt(2)
	v_pk_mul_f32 v[102:103], v[110:111], v[102:103]
	v_pk_mul_f32 v[100:101], v[108:109], v[100:101]
	s_waitcnt vmcnt(1)
	v_pk_fma_f32 v[90:91], v[90:91], v[98:99], v[114:115]
	v_pk_fma_f32 v[82:83], v[82:83], v[96:97], v[112:113]
	s_waitcnt vmcnt(0)
	v_pk_fma_f32 v[84:85], v[84:85], v[102:103], v[118:119]
	v_pk_fma_f32 v[88:89], v[88:89], v[100:101], v[116:117]
	v_pk_fma_f32 v[72:73], v[72:73], v[98:99], v[114:115]
	v_pk_fma_f32 v[76:77], v[76:77], v[96:97], v[112:113]
	v_pk_fma_f32 v[64:65], v[98:99], v[64:65], v[114:115]
	v_pk_fma_f32 v[68:69], v[96:97], v[68:69], v[112:113]
	v_pk_fma_f32 v[98:99], v[98:99], v[56:57], v[114:115]
	v_pk_fma_f32 v[60:61], v[96:97], v[60:61], v[112:113]
	v_pk_fma_f32 v[96:97], v[102:103], v[54:55], v[118:119]
	v_cvt_pk_bf16_f32 v54, v82, v83
	v_cvt_pk_bf16_f32 v55, v90, v91
	v_cvt_pk_bf16_f32 v56, v88, v89
	v_cvt_pk_bf16_f32 v57, v84, v85
	v_pk_fma_f32 v[92:93], v[92:93], v[102:103], v[118:119]
	v_pk_fma_f32 v[74:75], v[74:75], v[100:101], v[116:117]
	global_store_dwordx4 v[52:53], v[54:57], off nt
	v_pk_fma_f32 v[62:63], v[62:63], v[102:103], v[118:119]
	v_pk_fma_f32 v[66:67], v[66:67], v[100:101], v[116:117]
	v_cvt_pk_bf16_f32 v54, v76, v77
	v_cvt_pk_bf16_f32 v55, v72, v73
	v_cvt_pk_bf16_f32 v56, v74, v75
	v_cvt_pk_bf16_f32 v57, v92, v93
	global_store_dwordx4 v[70:71], v[54:57], off nt
	v_pk_fma_f32 v[58:59], v[100:101], v[58:59], v[116:117]
	s_nop 0
	v_cvt_pk_bf16_f32 v54, v68, v69
	v_cvt_pk_bf16_f32 v55, v64, v65
	v_cvt_pk_bf16_f32 v56, v66, v67
	v_cvt_pk_bf16_f32 v57, v62, v63
	global_store_dwordx4 v[94:95], v[54:57], off nt
	s_nop 1
	v_cvt_pk_bf16_f32 v54, v60, v61
	v_cvt_pk_bf16_f32 v55, v98, v99
	v_cvt_pk_bf16_f32 v56, v58, v59
	v_cvt_pk_bf16_f32 v57, v96, v97
	global_store_dwordx4 v[120:121], v[54:57], off nt
	global_load_dwordx4 v[54:57], v137, s[6:7]
	s_nop 0
	global_load_dwordx4 v[58:61], v137, s[6:7] offset:16
	global_load_dwordx4 v[62:65], v[46:47], off
	global_load_dwordx4 v[66:69], v[46:47], off offset:16
	global_load_dwordx4 v[72:75], v135, s[4:5] offset:2048
	global_load_dwordx4 v[82:85], v135, s[4:5] offset:2064
	s_waitcnt vmcnt(5)
	v_pk_add_f32 v[56:57], v[56:57], 1.0 op_sel_hi:[1,0]
	v_pk_add_f32 v[54:55], v[54:55], 1.0 op_sel_hi:[1,0]
	s_waitcnt vmcnt(4)
	v_pk_add_f32 v[60:61], v[60:61], 1.0 op_sel_hi:[1,0]
	v_pk_add_f32 v[58:59], v[58:59], 1.0 op_sel_hi:[1,0]
	s_waitcnt vmcnt(3)
	v_pk_mul_f32 v[56:57], v[64:65], v[56:57]
	v_pk_mul_f32 v[54:55], v[62:63], v[54:55]
	s_waitcnt vmcnt(2)
	v_pk_mul_f32 v[60:61], v[68:69], v[60:61]
	v_pk_mul_f32 v[58:59], v[66:67], v[58:59]
	s_waitcnt vmcnt(1)
	v_pk_fma_f32 v[14:15], v[14:15], v[56:57], v[74:75]
	v_pk_fma_f32 v[16:17], v[16:17], v[54:55], v[72:73]
	s_waitcnt vmcnt(0)
	v_pk_fma_f32 v[18:19], v[18:19], v[60:61], v[84:85]
	v_pk_fma_f32 v[20:21], v[20:21], v[58:59], v[82:83]
	v_pk_fma_f32 v[62:63], v[2:3], v[56:57], v[74:75]
	v_pk_fma_f32 v[64:65], v[4:5], v[54:55], v[72:73]
	v_cvt_pk_bf16_f32 v2, v16, v17
	v_cvt_pk_bf16_f32 v3, v14, v15
	v_cvt_pk_bf16_f32 v4, v20, v21
	v_cvt_pk_bf16_f32 v5, v18, v19
	v_pk_fma_f32 v[10:11], v[10:11], v[56:57], v[74:75]
	v_pk_fma_f32 v[12:13], v[12:13], v[54:55], v[72:73]
	v_pk_fma_f32 v[22:23], v[22:23], v[60:61], v[84:85]
	v_pk_fma_f32 v[24:25], v[24:25], v[58:59], v[82:83]
	global_store_dwordx4 v[52:53], v[2:5], off offset:1024 nt
	v_pk_fma_f32 v[26:27], v[26:27], v[60:61], v[84:85]
	v_pk_fma_f32 v[28:29], v[28:29], v[58:59], v[82:83]
	v_cvt_pk_bf16_f32 v2, v12, v13
	v_cvt_pk_bf16_f32 v3, v10, v11
	v_cvt_pk_bf16_f32 v4, v24, v25
	v_cvt_pk_bf16_f32 v5, v22, v23
	global_store_dwordx4 v[70:71], v[2:5], off offset:1024 nt
	v_pk_fma_f32 v[6:7], v[6:7], v[56:57], v[74:75]
	v_pk_fma_f32 v[8:9], v[8:9], v[54:55], v[72:73]
	v_cvt_pk_bf16_f32 v2, v64, v65
	v_cvt_pk_bf16_f32 v3, v62, v63
	v_cvt_pk_bf16_f32 v4, v28, v29
	v_cvt_pk_bf16_f32 v5, v26, v27
	v_pk_fma_f32 v[30:31], v[30:31], v[60:61], v[84:85]
	v_pk_fma_f32 v[32:33], v[32:33], v[58:59], v[82:83]
	global_store_dwordx4 v[94:95], v[2:5], off offset:1024 nt
	s_nop 1
	v_cvt_pk_bf16_f32 v2, v8, v9
	v_cvt_pk_bf16_f32 v3, v6, v7
	v_cvt_pk_bf16_f32 v4, v32, v33
	v_cvt_pk_bf16_f32 v5, v30, v31
	global_store_dwordx4 v[120:121], v[2:5], off offset:1024 nt
	s_cbranch_scc1 .LBB0_1195

.LBB0_1507:
	s_ashr_i32 s11, s10, 31
	s_lshl_b64 s[16:17], s[10:11], 11
	v_lshl_add_u64 v[52:53], v[36:37], 0, s[16:17]
	v_add_co_u32_e32 v30, vcc, s46, v52
	s_add_i32 s50, s10, 1
	s_nop 0
	v_addc_co_u32_e32 v31, vcc, 0, v53, vcc
	s_add_i32 s6, s10, 2
	s_add_i32 s4, s10, 3
	global_load_dwordx4 v[2:5], v[52:53], off
	global_load_dwordx4 v[6:9], v[52:53], off offset:1024
	global_load_dwordx4 v[10:13], v[52:53], off offset:2048
	global_load_dwordx4 v[14:17], v[52:53], off offset:3072
	global_load_dwordx4 v[18:21], v[30:31], off
	global_load_dwordx4 v[22:25], v[30:31], off offset:1024
	global_load_dwordx4 v[26:29], v[30:31], off offset:2048
	s_ashr_i32 s51, s50, 31
	s_ashr_i32 s7, s6, 31
	s_ashr_i32 s5, s4, 31
	s_ashr_i32 s24, s13, 10
	s_lshl_b64 s[56:57], s[10:11], 6
	s_lshl_b64 s[22:23], s[50:51], 11
	s_lshl_b64 s[20:21], s[6:7], 11
	s_lshl_b64 s[18:19], s[4:5], 11
	s_add_u32 s56, s28, s56
	s_addc_u32 s57, s29, s57
	global_load_dwordx4 v[30:33], v[30:31], off offset:3072
	s_nop 0
	global_load_dwordx4 v[70:73], v35, s[56:57] offset:48
	global_load_dwordx4 v[74:77], v35, s[56:57] offset:32
	global_load_dwordx4 v[92:95], v35, s[56:57] offset:16
	global_load_dwordx4 v[148:151], v35, s[56:57]
	s_lshl_b64 s[50:51], s[50:51], 6
	s_add_u32 s50, s28, s50
	s_addc_u32 s51, s29, s51
	global_load_dwordx4 v[152:155], v35, s[50:51] offset:48
	global_load_dwordx4 v[156:159], v35, s[50:51] offset:32
	global_load_dwordx4 v[160:163], v35, s[50:51] offset:16
	global_load_dwordx4 v[164:167], v35, s[50:51]
	s_lshl_b64 s[6:7], s[6:7], 6
	s_add_u32 s6, s28, s6
	s_addc_u32 s7, s29, s7
	global_load_dwordx4 v[168:171], v35, s[6:7] offset:16
	global_load_dwordx4 v[172:175], v35, s[6:7]
	s_lshl_b64 s[4:5], s[4:5], 6
	s_add_u32 s4, s28, s4
	s_addc_u32 s5, s29, s5
	s_waitcnt vmcnt(0)
	v_lshlrev_b32_e32 v54, 16, v2
	v_and_b32_e32 v55, 0xffff0000, v2
	v_lshlrev_b32_e32 v58, 16, v3
	v_and_b32_e32 v59, 0xffff0000, v3
	v_lshl_add_u64 v[2:3], v[38:39], 0, s[16:17]
	v_lshlrev_b32_e32 v106, 16, v14
	v_and_b32_e32 v107, 0xffff0000, v14
	v_lshlrev_b32_e32 v108, 16, v15
	v_and_b32_e32 v109, 0xffff0000, v15
	v_lshlrev_b32_e32 v102, 16, v16
	v_and_b32_e32 v103, 0xffff0000, v16
	v_lshlrev_b32_e32 v104, 16, v17
	v_and_b32_e32 v105, 0xffff0000, v17
	v_lshlrev_b32_e32 v126, 16, v26
	v_and_b32_e32 v127, 0xffff0000, v26
	v_lshlrev_b32_e32 v130, 16, v27
	v_and_b32_e32 v131, 0xffff0000, v27
	v_lshlrev_b32_e32 v128, 16, v28
	v_and_b32_e32 v129, 0xffff0000, v28
	v_lshlrev_b32_e32 v132, 16, v29
	v_and_b32_e32 v133, 0xffff0000, v29
	global_load_dwordx4 v[26:29], v[2:3], off
	global_load_dwordx4 v[14:17], v[2:3], off offset:1024
	v_lshl_add_u64 v[2:3], v[38:39], 0, s[22:23]
	v_lshlrev_b32_e32 v62, 16, v10
	v_and_b32_e32 v63, 0xffff0000, v10
	v_lshlrev_b32_e32 v66, 16, v11
	v_and_b32_e32 v67, 0xffff0000, v11
	v_lshlrev_b32_e32 v64, 16, v12
	v_and_b32_e32 v65, 0xffff0000, v12
	v_lshlrev_b32_e32 v68, 16, v13
	v_and_b32_e32 v69, 0xffff0000, v13
	v_lshlrev_b32_e32 v98, 16, v22
	v_and_b32_e32 v99, 0xffff0000, v22
	v_lshlrev_b32_e32 v100, 16, v23
	v_and_b32_e32 v101, 0xffff0000, v23
	v_lshlrev_b32_e32 v90, 16, v24
	v_and_b32_e32 v91, 0xffff0000, v24
	v_lshlrev_b32_e32 v96, 16, v25
	v_and_b32_e32 v97, 0xffff0000, v25
	global_load_dwordx4 v[22:25], v[2:3], off
	global_load_dwordx4 v[10:13], v[2:3], off offset:1024
	v_lshl_add_u64 v[2:3], v[38:39], 0, s[20:21]
	v_lshlrev_b32_e32 v56, 16, v4
	v_and_b32_e32 v57, 0xffff0000, v4
	v_lshlrev_b32_e32 v60, 16, v5
	v_and_b32_e32 v61, 0xffff0000, v5
	v_lshlrev_b32_e32 v118, 16, v18
	v_and_b32_e32 v119, 0xffff0000, v18
	v_lshlrev_b32_e32 v122, 16, v19
	v_and_b32_e32 v123, 0xffff0000, v19
	v_lshlrev_b32_e32 v120, 16, v20
	v_and_b32_e32 v121, 0xffff0000, v20
	v_lshlrev_b32_e32 v124, 16, v21
	v_and_b32_e32 v125, 0xffff0000, v21
	global_load_dwordx4 v[176:179], v35, s[6:7] offset:48
	global_load_dwordx4 v[180:183], v35, s[6:7] offset:32
	global_load_dwordx4 v[18:21], v[2:3], off
	s_nop 0
	global_load_dwordx4 v[2:5], v[2:3], off offset:1024
	v_lshlrev_b32_e32 v114, 16, v6
	v_and_b32_e32 v115, 0xffff0000, v6
	v_lshlrev_b32_e32 v116, 16, v7
	v_and_b32_e32 v117, 0xffff0000, v7
	v_lshl_add_u64 v[6:7], v[38:39], 0, s[18:19]
	v_lshlrev_b32_e32 v110, 16, v8
	v_and_b32_e32 v111, 0xffff0000, v8
	v_lshlrev_b32_e32 v112, 16, v9
	v_and_b32_e32 v113, 0xffff0000, v9
	v_lshlrev_b32_e32 v82, 16, v30
	v_and_b32_e32 v83, 0xffff0000, v30
	v_lshlrev_b32_e32 v86, 16, v31
	v_and_b32_e32 v87, 0xffff0000, v31
	v_lshlrev_b32_e32 v78, 16, v32
	v_and_b32_e32 v79, 0xffff0000, v32
	v_lshlrev_b32_e32 v80, 16, v33
	v_and_b32_e32 v81, 0xffff0000, v33
	global_load_dwordx4 v[184:187], v35, s[4:5] offset:16
	global_load_dwordx4 v[188:191], v35, s[4:5]
	global_load_dwordx4 v[30:33], v[6:7], off
	s_nop 0
	global_load_dwordx4 v[6:9], v[6:7], off offset:1024
	v_mov_b32_e32 v84, v149
	v_mov_b32_e32 v85, v150
	v_mov_b32_e32 v149, v151
	v_pk_add_f32 v[84:85], v[84:85], v[148:149]
	global_load_dwordx4 v[148:151], v35, s[4:5] offset:48
	global_load_dwordx4 v[192:195], v35, s[4:5] offset:32
	v_mov_b32_e32 v88, v93
	v_mov_b32_e32 v89, v94
	v_mov_b32_e32 v93, v95
	v_pk_add_f32 v[88:89], v[88:89], v[92:93]
	v_pk_add_f32 v[84:85], v[84:85], v[84:85] op_sel:[0,1] op_sel_hi:[1,0]
	v_pk_add_f32 v[88:89], v[88:89], v[88:89] op_sel:[0,1] op_sel_hi:[1,0]
	v_add_f32_e32 v74, v74, v75
	v_add_f32_e32 v76, v76, v77
	v_mov_b32_e32 v85, v70
	v_mov_b32_e32 v89, v71
	v_mov_b32_e32 v75, v72
	v_mov_b32_e32 v77, v73
	v_pk_add_f32 v[70:71], v[84:85], v[88:89]
	v_pk_add_f32 v[72:73], v[74:75], v[76:77]
	v_mov_b32_e32 v74, v161
	v_pk_add_f32 v[70:71], v[70:71], v[72:73]
	v_mov_b32_e32 v72, v165
	v_mov_b32_e32 v73, v166
	v_mov_b32_e32 v165, v167
	v_mov_b32_e32 v75, v162
	v_mov_b32_e32 v161, v163
	v_pk_add_f32 v[72:73], v[72:73], v[164:165]
	v_pk_add_f32 v[74:75], v[74:75], v[160:161]
	v_pk_add_f32 v[72:73], v[72:73], v[72:73] op_sel:[0,1] op_sel_hi:[1,0]
	v_pk_add_f32 v[74:75], v[74:75], v[74:75] op_sel:[0,1] op_sel_hi:[1,0]
	v_add_f32_e32 v76, v156, v157
	v_add_f32_e32 v84, v158, v159
	v_mov_b32_e32 v73, v152
	v_mov_b32_e32 v75, v153
	v_mov_b32_e32 v77, v154
	v_mov_b32_e32 v85, v155
	v_pk_add_f32 v[72:73], v[72:73], v[74:75]
	v_pk_add_f32 v[74:75], v[76:77], v[84:85]
	s_waitcnt vmcnt(9)
	v_mov_b32_e32 v77, v179
	v_pk_add_f32 v[72:73], v[72:73], v[74:75]
	v_mov_b32_e32 v75, v70
	v_mov_b32_e32 v74, v72
	v_mov_b32_e32 v70, v73
	v_pk_add_f32 v[70:71], v[74:75], v[70:71]
	v_mov_b32_e32 v73, v170
	v_pk_fma_f32 v[70:71], v[70:71], s[12:13], v[50:51] op_sel_hi:[1,0,0]
	s_waitcnt vmcnt(8)
	v_add_f32_e32 v74, v180, v181
	v_mul_f32_e32 v72, 0x4b800000, v71
	v_cmp_gt_f32_e32 vcc, s47, v71
	v_cmp_gt_f32_e64 s[4:5], s47, v70
	v_add_f32_e32 v76, v182, v183
	v_cndmask_b32_e32 v71, v71, v72, vcc
	v_rsq_f32_e32 v71, v71
	v_mul_f32_e32 v72, 0x4b800000, v70
	v_cndmask_b32_e64 v70, v70, v72, s[4:5]
	v_rsq_f32_e32 v70, v70
	v_mul_f32_e32 v72, 0x45800000, v71
	v_cndmask_b32_e32 v71, v71, v72, vcc
	v_mul_f32_e32 v138, 0.5, v71
	v_mul_f32_e32 v71, 0x45800000, v70
	v_cndmask_b32_e64 v70, v70, v71, s[4:5]
	v_mul_f32_e32 v134, 0.5, v70
	v_mov_b32_e32 v70, v173
	v_mov_b32_e32 v71, v174
	v_mov_b32_e32 v173, v175
	v_mov_b32_e32 v72, v169
	v_mov_b32_e32 v169, v171
	v_pk_add_f32 v[70:71], v[70:71], v[172:173]
	v_pk_add_f32 v[72:73], v[72:73], v[168:169]
	v_pk_add_f32 v[70:71], v[70:71], v[70:71] op_sel:[0,1] op_sel_hi:[1,0]
	v_pk_add_f32 v[72:73], v[72:73], v[72:73] op_sel:[0,1] op_sel_hi:[1,0]
	v_mov_b32_e32 v71, v176
	v_mov_b32_e32 v73, v177
	v_mov_b32_e32 v75, v178
	v_pk_add_f32 v[70:71], v[70:71], v[72:73]
	v_pk_add_f32 v[72:73], v[74:75], v[76:77]
	s_waitcnt vmcnt(5)
	v_mov_b32_e32 v74, v185
	v_pk_add_f32 v[70:71], v[70:71], v[72:73]
	s_waitcnt vmcnt(4)
	v_mov_b32_e32 v72, v189
	v_mov_b32_e32 v73, v190
	v_mov_b32_e32 v189, v191
	v_mov_b32_e32 v75, v186
	v_mov_b32_e32 v185, v187
	v_pk_add_f32 v[72:73], v[72:73], v[188:189]
	v_pk_add_f32 v[74:75], v[74:75], v[184:185]
	v_pk_add_f32 v[72:73], v[72:73], v[72:73] op_sel:[0,1] op_sel_hi:[1,0]
	v_pk_add_f32 v[74:75], v[74:75], v[74:75] op_sel:[0,1] op_sel_hi:[1,0]
	s_waitcnt vmcnt(0)
	v_add_f32_e32 v76, v192, v193
	v_add_f32_e32 v84, v194, v195
	v_mov_b32_e32 v73, v148
	v_mov_b32_e32 v75, v149
	v_mov_b32_e32 v77, v150
	v_mov_b32_e32 v85, v151
	v_pk_add_f32 v[72:73], v[72:73], v[74:75]
	v_pk_add_f32 v[74:75], v[76:77], v[84:85]
	s_nop 0
	v_pk_add_f32 v[72:73], v[72:73], v[74:75]
	v_mov_b32_e32 v75, v70
	v_mov_b32_e32 v74, v72
	v_mov_b32_e32 v70, v73
	v_pk_add_f32 v[70:71], v[74:75], v[70:71]
	s_nop 0
	v_pk_fma_f32 v[70:71], v[70:71], s[12:13], v[50:51] op_sel_hi:[1,0,0]
	s_nop 0
	v_mul_f32_e32 v72, 0x4b800000, v71
	v_cmp_gt_f32_e32 vcc, s47, v71
	v_cmp_gt_f32_e64 s[4:5], s47, v70
	s_nop 0
	v_cndmask_b32_e32 v71, v71, v72, vcc
	v_rsq_f32_e32 v71, v71
	v_mul_f32_e32 v72, 0x4b800000, v70
	v_cndmask_b32_e64 v70, v70, v72, s[4:5]
	v_rsq_f32_e32 v70, v70
	v_mul_f32_e32 v72, 0x45800000, v71
	v_cndmask_b32_e32 v71, v71, v72, vcc
	v_mul_f32_e32 v140, 0.5, v71
	v_mul_f32_e32 v71, 0x45800000, v70
	v_cndmask_b32_e64 v70, v70, v71, s[4:5]
	v_mul_f32_e32 v136, 0.5, v70
	s_mul_i32 s4, s24, 9
	s_ashr_i32 s5, s4, 31
	s_lshl_b64 s[4:5], s[4:5], 12
	s_add_u32 s24, s68, s4
	s_addc_u32 s25, s69, s5
	s_add_u32 s4, s24, 0x2000
	s_addc_u32 s5, s25, 0
	global_load_dwordx4 v[70:73], v[40:41], off
	global_load_dwordx4 v[74:77], v34, s[4:5]
	global_load_dwordx4 v[92:95], v34, s[4:5] offset:16
	global_load_dwordx4 v[148:151], v[40:41], off offset:16
	global_load_dwordx4 v[152:155], v135, s[4:5]
	global_load_dwordx4 v[156:159], v[42:43], off
	global_load_dwordx4 v[160:163], v[42:43], off offset:16
	global_load_dwordx4 v[164:167], v135, s[4:5] offset:16
	v_lshlrev_b32_e32 v170, 16, v24
	v_and_b32_e32 v171, 0xffff0000, v24
	v_lshlrev_b32_e32 v172, 16, v18
	v_and_b32_e32 v173, 0xffff0000, v18
	v_lshlrev_b32_e32 v18, 16, v19
	v_and_b32_e32 v19, 0xffff0000, v19
	v_lshlrev_b32_e32 v168, 16, v22
	v_and_b32_e32 v169, 0xffff0000, v22
	v_lshlrev_b32_e32 v22, 16, v23
	v_and_b32_e32 v23, 0xffff0000, v23
	v_lshlrev_b32_e32 v174, 16, v20
	v_and_b32_e32 v175, 0xffff0000, v20
	v_lshlrev_b32_e32 v20, 16, v21
	v_and_b32_e32 v21, 0xffff0000, v21
	v_pk_mul_f32 v[170:171], v[134:135], v[170:171] op_sel_hi:[0,1]
	v_pk_mul_f32 v[18:19], v[140:141], v[18:19] op_sel_hi:[0,1]
	v_lshlrev_b32_e32 v84, 16, v26
	v_and_b32_e32 v85, 0xffff0000, v26
	v_lshlrev_b32_e32 v26, 16, v27
	v_and_b32_e32 v27, 0xffff0000, v27
	v_lshlrev_b32_e32 v88, 16, v28
	v_and_b32_e32 v89, 0xffff0000, v28
	v_lshlrev_b32_e32 v28, 16, v29
	v_and_b32_e32 v29, 0xffff0000, v29
	v_pk_mul_f32 v[168:169], v[134:135], v[168:169] op_sel_hi:[0,1]
	v_pk_mul_f32 v[22:23], v[134:135], v[22:23] op_sel_hi:[0,1]
	v_pk_mul_f32 v[20:21], v[140:141], v[20:21] op_sel_hi:[0,1]
	v_lshlrev_b32_e32 v24, 16, v25
	v_and_b32_e32 v25, 0xffff0000, v25
	v_lshlrev_b32_e32 v176, 16, v30
	v_and_b32_e32 v177, 0xffff0000, v30
	v_lshlrev_b32_e32 v30, 16, v31
	v_and_b32_e32 v31, 0xffff0000, v31
	v_pk_mul_f32 v[84:85], v[138:139], v[84:85] op_sel_hi:[0,1]
	v_pk_mul_f32 v[26:27], v[138:139], v[26:27] op_sel_hi:[0,1]
	v_pk_mul_f32 v[28:29], v[138:139], v[28:29] op_sel_hi:[0,1]
	v_lshlrev_b32_e32 v178, 16, v32
	v_and_b32_e32 v179, 0xffff0000, v32
	v_lshlrev_b32_e32 v32, 16, v33
	v_and_b32_e32 v33, 0xffff0000, v33
	v_pk_mul_f32 v[88:89], v[138:139], v[88:89] op_sel_hi:[0,1]
	v_pk_mul_f32 v[24:25], v[134:135], v[24:25] op_sel_hi:[0,1]
	v_pk_mul_f32 v[30:31], v[136:137], v[30:31] op_sel_hi:[0,1]
	v_pk_mul_f32 v[32:33], v[136:137], v[32:33] op_sel_hi:[0,1]
	v_lshlrev_b32_e32 v180, 16, v14
	v_and_b32_e32 v181, 0xffff0000, v14
	v_lshlrev_b32_e32 v14, 16, v15
	v_and_b32_e32 v15, 0xffff0000, v15
	v_pk_mul_f32 v[14:15], v[138:139], v[14:15] op_sel_hi:[0,1]
	v_pk_mul_f32 v[172:173], v[140:141], v[172:173] op_sel_hi:[0,1]
	v_pk_mul_f32 v[174:175], v[140:141], v[174:175] op_sel_hi:[0,1]
	v_pk_mul_f32 v[176:177], v[136:137], v[176:177] op_sel_hi:[0,1]
	v_pk_mul_f32 v[178:179], v[136:137], v[178:179] op_sel_hi:[0,1]
	s_waitcnt vmcnt(6)
	v_pk_mul_f32 v[182:183], v[76:77], v[72:73]
	v_pk_mul_f32 v[184:185], v[74:75], v[70:71]
	s_waitcnt vmcnt(4)
	v_pk_mul_f32 v[148:149], v[92:93], v[148:149]
	v_pk_mul_f32 v[150:151], v[94:95], v[150:151]
	v_pk_fma_f32 v[74:75], v[148:149], v[170:171], v[64:65]
	v_pk_fma_f32 v[64:65], v[182:183], v[18:19], v[122:123]
	v_lshlrev_b32_e32 v18, 16, v16
	v_and_b32_e32 v19, 0xffff0000, v16
	s_waitcnt vmcnt(2)
	v_pk_mul_f32 v[154:155], v[154:155], v[158:159]
	s_waitcnt vmcnt(0)
	v_pk_mul_f32 v[158:159], v[164:165], v[160:161]
	v_pk_fma_f32 v[72:73], v[182:183], v[22:23], v[66:67]
	v_pk_fma_f32 v[76:77], v[184:185], v[168:169], v[62:63]
	v_pk_fma_f32 v[62:63], v[150:151], v[20:21], v[124:125]
	v_lshlrev_b32_e32 v20, 16, v17
	v_and_b32_e32 v21, 0xffff0000, v17
	v_pk_mul_f32 v[22:23], v[138:139], v[18:19] op_sel_hi:[0,1]
	v_pk_fma_f32 v[92:93], v[182:183], v[26:27], v[58:59]
	v_pk_fma_f32 v[94:95], v[184:185], v[84:85], v[54:55]
	v_pk_fma_f32 v[84:85], v[28:29], v[150:151], v[60:61]
	v_pk_mul_f32 v[18:19], v[138:139], v[20:21] op_sel_hi:[0,1]
	v_pk_fma_f32 v[20:21], v[22:23], v[158:159], v[110:111]
	v_lshlrev_b32_e32 v22, 16, v10
	v_and_b32_e32 v23, 0xffff0000, v10
	v_lshlrev_b32_e32 v26, 16, v13
	v_and_b32_e32 v27, 0xffff0000, v13
	v_lshlrev_b32_e32 v28, 16, v4
	v_and_b32_e32 v29, 0xffff0000, v4
	v_pk_fma_f32 v[88:89], v[88:89], v[148:149], v[56:57]
	v_pk_fma_f32 v[70:71], v[150:151], v[24:25], v[68:69]
	v_pk_fma_f32 v[56:57], v[182:183], v[30:31], v[130:131]
	v_lshlrev_b32_e32 v24, 16, v12
	v_and_b32_e32 v25, 0xffff0000, v12
	v_pk_mul_f32 v[12:13], v[134:135], v[22:23] op_sel_hi:[0,1]
	v_pk_mul_f32 v[22:23], v[134:135], v[26:27] op_sel_hi:[0,1]
	v_lshlrev_b32_e32 v26, 16, v2
	v_and_b32_e32 v27, 0xffff0000, v2
	v_lshlrev_b32_e32 v30, 16, v5
	v_and_b32_e32 v31, 0xffff0000, v5
	v_pk_mul_f32 v[28:29], v[140:141], v[28:29] op_sel_hi:[0,1]
	v_pk_fma_f32 v[54:55], v[150:151], v[32:33], v[132:133]
	v_pk_mul_f32 v[4:5], v[140:141], v[26:27] op_sel_hi:[0,1]
	v_pk_mul_f32 v[26:27], v[140:141], v[30:31] op_sel_hi:[0,1]
	v_pk_fma_f32 v[28:29], v[158:159], v[28:29], v[90:91]
	v_lshlrev_b32_e32 v30, 16, v6
	v_and_b32_e32 v31, 0xffff0000, v6
	v_lshlrev_b32_e32 v32, 16, v8
	v_and_b32_e32 v33, 0xffff0000, v8
	v_lshlrev_b32_e32 v90, 16, v9
	v_and_b32_e32 v91, 0xffff0000, v9
	v_pk_mul_f32 v[152:153], v[152:153], v[156:157]
	v_pk_mul_f32 v[156:157], v[166:167], v[162:163]
	v_pk_mul_f32 v[8:9], v[136:137], v[30:31] op_sel_hi:[0,1]
	v_pk_mul_f32 v[32:33], v[136:137], v[32:33] op_sel_hi:[0,1]
	v_pk_mul_f32 v[30:31], v[136:137], v[90:91] op_sel_hi:[0,1]
	v_pk_mul_f32 v[16:17], v[138:139], v[180:181] op_sel_hi:[0,1]
	v_pk_fma_f32 v[30:31], v[156:157], v[30:31], v[80:81]
	v_pk_fma_f32 v[32:33], v[158:159], v[32:33], v[78:79]
	v_cvt_pk_bf16_f32 v78, v94, v95
	v_cvt_pk_bf16_f32 v79, v92, v93
	v_cvt_pk_bf16_f32 v80, v88, v89
	v_cvt_pk_bf16_f32 v81, v84, v85
	v_pk_fma_f32 v[14:15], v[14:15], v[154:155], v[116:117]
	v_pk_fma_f32 v[16:17], v[16:17], v[152:153], v[114:115]
	v_pk_fma_f32 v[18:19], v[18:19], v[156:157], v[112:113]
	v_lshlrev_b32_e32 v10, 16, v11
	v_and_b32_e32 v11, 0xffff0000, v11
	global_store_dwordx4 v[52:53], v[78:81], off nt
	v_pk_mul_f32 v[10:11], v[134:135], v[10:11] op_sel_hi:[0,1]
	v_pk_mul_f32 v[24:25], v[134:135], v[24:25] op_sel_hi:[0,1]
	v_cvt_pk_bf16_f32 v78, v16, v17
	v_cvt_pk_bf16_f32 v79, v14, v15
	v_cvt_pk_bf16_f32 v80, v20, v21
	v_cvt_pk_bf16_f32 v81, v18, v19
	global_store_dwordx4 v[52:53], v[78:81], off offset:1024 nt
	v_lshl_add_u64 v[52:53], v[36:37], 0, s[22:23]
	v_pk_fma_f32 v[10:11], v[154:155], v[10:11], v[108:109]
	v_cvt_pk_bf16_f32 v78, v76, v77
	v_cvt_pk_bf16_f32 v79, v72, v73
	v_cvt_pk_bf16_f32 v80, v74, v75
	v_cvt_pk_bf16_f32 v81, v70, v71
	v_pk_fma_f32 v[12:13], v[152:153], v[12:13], v[106:107]
	v_pk_fma_f32 v[22:23], v[22:23], v[156:157], v[104:105]
	v_pk_fma_f32 v[24:25], v[24:25], v[158:159], v[102:103]
	v_lshlrev_b32_e32 v2, 16, v3
	v_and_b32_e32 v3, 0xffff0000, v3
	global_store_dwordx4 v[52:53], v[78:81], off nt
	v_pk_fma_f32 v[68:69], v[184:185], v[172:173], v[118:119]
	v_pk_fma_f32 v[66:67], v[148:149], v[174:175], v[120:121]
	v_cvt_pk_bf16_f32 v78, v12, v13
	v_cvt_pk_bf16_f32 v79, v10, v11
	v_cvt_pk_bf16_f32 v80, v24, v25
	v_cvt_pk_bf16_f32 v81, v22, v23
	v_pk_mul_f32 v[2:3], v[140:141], v[2:3] op_sel_hi:[0,1]
	global_store_dwordx4 v[52:53], v[78:81], off offset:1024 nt
	v_lshl_add_u64 v[52:53], v[36:37], 0, s[20:21]
	v_pk_fma_f32 v[2:3], v[154:155], v[2:3], v[100:101]
	v_cvt_pk_bf16_f32 v78, v68, v69
	v_cvt_pk_bf16_f32 v79, v64, v65
	v_cvt_pk_bf16_f32 v80, v66, v67
	v_cvt_pk_bf16_f32 v81, v62, v63
	v_pk_fma_f32 v[4:5], v[152:153], v[4:5], v[98:99]
	v_pk_fma_f32 v[26:27], v[156:157], v[26:27], v[96:97]
	v_lshlrev_b32_e32 v6, 16, v7
	v_and_b32_e32 v7, 0xffff0000, v7
	global_store_dwordx4 v[52:53], v[78:81], off nt
	v_pk_fma_f32 v[60:61], v[184:185], v[176:177], v[126:127]
	v_pk_fma_f32 v[58:59], v[148:149], v[178:179], v[128:129]
	v_cvt_pk_bf16_f32 v78, v4, v5
	v_cvt_pk_bf16_f32 v79, v2, v3
	v_cvt_pk_bf16_f32 v80, v28, v29
	v_cvt_pk_bf16_f32 v81, v26, v27
	v_pk_mul_f32 v[6:7], v[136:137], v[6:7] op_sel_hi:[0,1]
	global_store_dwordx4 v[52:53], v[78:81], off offset:1024 nt
	v_lshl_add_u64 v[52:53], v[36:37], 0, s[18:19]
	v_pk_fma_f32 v[6:7], v[154:155], v[6:7], v[86:87]
	v_cvt_pk_bf16_f32 v78, v60, v61
	v_cvt_pk_bf16_f32 v79, v56, v57
	v_cvt_pk_bf16_f32 v80, v58, v59
	v_cvt_pk_bf16_f32 v81, v54, v55
	v_pk_fma_f32 v[8:9], v[152:153], v[8:9], v[82:83]
	global_store_dwordx4 v[52:53], v[78:81], off nt
	s_nop 1
	v_cvt_pk_bf16_f32 v78, v8, v9
	v_cvt_pk_bf16_f32 v79, v6, v7
	v_cvt_pk_bf16_f32 v80, v32, v33
	v_cvt_pk_bf16_f32 v81, v30, v31
	global_store_dwordx4 v[52:53], v[78:81], off offset:1024 nt
	v_pk_mul_f32 v[52:53], v[92:93], v[92:93]
	s_nop 0
	v_pk_mul_f32 v[78:79], v[94:95], v[94:95]
	v_cmp_lt_i32_e32 vcc, v141, v139
	v_pk_mov_b32 v[80:81], v[78:79], v[52:53] op_sel:[1,0]
	v_mov_b32_e32 v79, v53
	v_pk_add_f32 v[52:53], v[80:81], v[78:79]
	v_pk_mul_f32 v[78:79], v[84:85], v[84:85]
	v_pk_mul_f32 v[80:81], v[88:89], v[88:89]
	v_pk_add_f32 v[52:53], v[52:53], v[52:53] op_sel:[0,1] op_sel_hi:[1,0]
	v_pk_mov_b32 v[82:83], v[80:81], v[78:79] op_sel:[1,0]
	v_mov_b32_e32 v81, v79
	v_pk_add_f32 v[78:79], v[82:83], v[80:81]
	v_mul_f32_e32 v80, v20, v20
	v_mul_f32_e32 v81, v21, v21
	v_pk_add_f32 v[78:79], v[78:79], v[78:79] op_sel:[0,1] op_sel_hi:[1,0]
	v_mov_b32_e32 v53, v80
	v_mov_b32_e32 v79, v81
	v_pk_add_f32 v[52:53], v[52:53], v[78:79]
	v_mul_f32_e32 v78, v17, v17
	v_mul_f32_e32 v80, v15, v15
	v_mul_f32_e32 v82, v18, v18
	v_mul_f32_e32 v83, v19, v19
	v_pk_fma_f32 v[78:79], v[16:17], v[16:17], v[78:79] op_sel_hi:[1,1,0]
	v_pk_fma_f32 v[80:81], v[14:15], v[14:15], v[80:81] op_sel_hi:[1,1,0]
	v_mov_b32_e32 v79, v82
	v_mov_b32_e32 v81, v83
	v_pk_add_f32 v[78:79], v[78:79], v[80:81]
	v_pk_mul_f32 v[80:81], v[76:77], v[76:77]
	v_pk_add_f32 v[52:53], v[52:53], v[78:79]
	v_cndmask_b32_e32 v78, v137, v141, vcc
	v_lshlrev_b32_e32 v98, 2, v78
	v_pk_mul_f32 v[78:79], v[72:73], v[72:73]
	v_mul_f32_e32 v90, v25, v25
	v_pk_mov_b32 v[82:83], v[80:81], v[78:79] op_sel:[1,0]
	v_mov_b32_e32 v81, v79
	v_pk_add_f32 v[78:79], v[82:83], v[80:81]
	v_pk_mul_f32 v[80:81], v[70:71], v[70:71]
	v_pk_mul_f32 v[82:83], v[74:75], v[74:75]
	v_mul_f32_e32 v91, v22, v22
	v_pk_mov_b32 v[86:87], v[82:83], v[80:81] op_sel:[1,0]
	v_mov_b32_e32 v83, v81
	v_pk_add_f32 v[80:81], v[86:87], v[82:83]
	v_mul_f32_e32 v82, v13, v13
	v_mul_f32_e32 v86, v24, v24
	v_pk_fma_f32 v[82:83], v[12:13], v[12:13], v[82:83] op_sel_hi:[1,1,0]
	v_mul_f32_e32 v96, v23, v23
	v_mov_b32_e32 v83, v86
	v_mul_f32_e32 v86, v11, v11
	v_pk_fma_f32 v[86:87], v[10:11], v[10:11], v[86:87] op_sel_hi:[1,1,0]
	v_pk_add_f32 v[78:79], v[78:79], v[78:79] op_sel:[0,1] op_sel_hi:[1,0]
	v_pk_add_f32 v[80:81], v[80:81], v[80:81] op_sel:[0,1] op_sel_hi:[1,0]
	v_mov_b32_e32 v87, v90
	v_mov_b32_e32 v79, v91
	v_mov_b32_e32 v81, v96
	v_pk_add_f32 v[82:83], v[82:83], v[86:87]
	v_pk_add_f32 v[78:79], v[78:79], v[80:81]
	v_mov_b32_e32 v81, v52
	v_pk_add_f32 v[78:79], v[82:83], v[78:79]
	v_cmp_lt_i32_e32 vcc, v142, v139
	v_mov_b32_e32 v80, v78
	v_mov_b32_e32 v52, v79
	v_pk_add_f32 v[52:53], v[80:81], v[52:53]
	v_cndmask_b32_e32 v80, v137, v142, vcc
	v_cmp_lt_i32_e32 vcc, v143, v139
	v_lshlrev_b32_e32 v99, 2, v80
	v_pk_mul_f32 v[82:83], v[68:69], v[68:69]
	v_cndmask_b32_e32 v80, v137, v143, vcc
	v_cmp_lt_i32_e32 vcc, v144, v139
	v_lshlrev_b32_e32 v100, 2, v80
	ds_bpermute_b32 v79, v98, v53
	v_cndmask_b32_e32 v80, v137, v144, vcc
	v_cmp_lt_i32_e32 vcc, v145, v139
	v_lshlrev_b32_e32 v101, 2, v80
	ds_bpermute_b32 v78, v98, v52
	v_cndmask_b32_e32 v80, v137, v145, vcc
	v_lshlrev_b32_e32 v102, 2, v80
	v_pk_mul_f32 v[80:81], v[64:65], v[64:65]
	v_cmp_lt_i32_e32 vcc, v146, v139
	v_pk_mov_b32 v[86:87], v[82:83], v[80:81] op_sel:[1,0]
	v_mov_b32_e32 v83, v81
	v_pk_add_f32 v[80:81], v[86:87], v[82:83]
	v_pk_mul_f32 v[82:83], v[62:63], v[62:63]
	v_pk_add_f32 v[80:81], v[80:81], v[80:81] op_sel_hi:[0,1]
	v_pk_mul_f32 v[86:87], v[66:67], v[66:67]
	v_mul_f32_e32 v80, v4, v4
	v_pk_mov_b32 v[90:91], v[86:87], v[82:83] op_sel:[1,0]
	v_mov_b32_e32 v87, v83
	v_pk_add_f32 v[82:83], v[90:91], v[86:87]
	v_pk_fma_f32 v[86:87], v[4:5], v[4:5], v[80:81] op_sel_hi:[1,1,0]
	v_mul_f32_e32 v80, v2, v2
	v_pk_add_f32 v[82:83], v[82:83], v[82:83] op_sel_hi:[0,1]
	v_pk_fma_f32 v[90:91], v[2:3], v[2:3], v[80:81] op_sel_hi:[1,1,0]
	v_mul_f32_e32 v86, v28, v28
	v_mul_f32_e32 v90, v29, v29
	v_mul_f32_e32 v80, v26, v26
	v_mul_f32_e32 v82, v27, v27
	s_waitcnt lgkmcnt(0)
	v_pk_add_f32 v[52:53], v[52:53], v[78:79]
	v_pk_add_f32 v[86:87], v[86:87], v[90:91]
	v_pk_add_f32 v[80:81], v[80:81], v[82:83]
	ds_bpermute_b32 v79, v99, v53
	ds_bpermute_b32 v78, v99, v52
	v_pk_add_f32 v[80:81], v[86:87], v[80:81]
	v_pk_mul_f32 v[82:83], v[56:57], v[56:57]
	v_pk_mul_f32 v[86:87], v[60:61], v[60:61]
	s_waitcnt lgkmcnt(0)
	v_pk_add_f32 v[52:53], v[52:53], v[78:79]
	v_pk_mov_b32 v[90:91], v[86:87], v[82:83] op_sel:[1,0]
	v_mov_b32_e32 v87, v83
	v_pk_add_f32 v[82:83], v[90:91], v[86:87]
	v_pk_mul_f32 v[86:87], v[54:55], v[54:55]
	v_pk_add_f32 v[82:83], v[82:83], v[82:83] op_sel_hi:[0,1]
	v_pk_mul_f32 v[90:91], v[58:59], v[58:59]
	v_mul_f32_e32 v82, v8, v8
	v_pk_mov_b32 v[96:97], v[90:91], v[86:87] op_sel:[1,0]
	v_mov_b32_e32 v91, v87
	v_pk_add_f32 v[86:87], v[96:97], v[90:91]
	v_pk_fma_f32 v[90:91], v[8:9], v[8:9], v[82:83] op_sel_hi:[1,1,0]
	v_mul_f32_e32 v82, v6, v6
	ds_bpermute_b32 v79, v100, v53
	ds_bpermute_b32 v78, v100, v52
	v_pk_add_f32 v[86:87], v[86:87], v[86:87] op_sel_hi:[0,1]
	v_pk_fma_f32 v[96:97], v[6:7], v[6:7], v[82:83] op_sel_hi:[1,1,0]
	v_mul_f32_e32 v90, v32, v32
	v_mul_f32_e32 v96, v33, v33
	v_mul_f32_e32 v82, v30, v30
	v_mul_f32_e32 v86, v31, v31
	v_pk_add_f32 v[90:91], v[90:91], v[96:97]
	v_pk_add_f32 v[82:83], v[82:83], v[86:87]
	v_mov_b32_e32 v87, v80
	v_pk_add_f32 v[82:83], v[90:91], v[82:83]
	s_waitcnt lgkmcnt(0)
	v_pk_add_f32 v[52:53], v[52:53], v[78:79]
	v_mov_b32_e32 v86, v82
	v_mov_b32_e32 v80, v83
	v_pk_add_f32 v[80:81], v[86:87], v[80:81]
	ds_bpermute_b32 v79, v101, v53
	ds_bpermute_b32 v78, v101, v52
	ds_bpermute_b32 v83, v98, v81
	ds_bpermute_b32 v82, v98, v80
	v_cndmask_b32_e32 v86, v137, v146, vcc
	v_lshlrev_b32_e32 v86, 2, v86
	s_waitcnt lgkmcnt(2)
	v_pk_add_f32 v[52:53], v[52:53], v[78:79]
	ds_bpermute_b32 v79, v102, v53
	s_waitcnt lgkmcnt(1)
	v_pk_add_f32 v[80:81], v[80:81], v[82:83]
	ds_bpermute_b32 v78, v102, v52
	ds_bpermute_b32 v83, v99, v81
	ds_bpermute_b32 v82, v99, v80
	s_waitcnt lgkmcnt(2)
	v_pk_add_f32 v[52:53], v[52:53], v[78:79]
	ds_bpermute_b32 v79, v86, v53
	s_waitcnt lgkmcnt(1)
	v_pk_add_f32 v[80:81], v[80:81], v[82:83]
	ds_bpermute_b32 v78, v86, v52
	ds_bpermute_b32 v83, v100, v81
	ds_bpermute_b32 v82, v100, v80
	s_waitcnt lgkmcnt(2)
	v_pk_add_f32 v[52:53], v[52:53], v[78:79]
	s_nop 0
	v_pk_fma_f32 v[52:53], v[52:53], s[12:13], v[50:51] op_sel_hi:[1,0,0]
	s_waitcnt lgkmcnt(0)
	v_pk_add_f32 v[78:79], v[80:81], v[82:83]
	ds_bpermute_b32 v81, v101, v79
	ds_bpermute_b32 v80, v101, v78
	v_mul_f32_e32 v82, 0x4b800000, v53
	v_cmp_gt_f32_e32 vcc, s47, v53
	v_cmp_gt_f32_e64 s[4:5], s47, v52
	s_waitcnt lgkmcnt(0)
	v_pk_add_f32 v[78:79], v[78:79], v[80:81]
	ds_bpermute_b32 v81, v102, v79
	ds_bpermute_b32 v80, v102, v78
	v_cndmask_b32_e32 v53, v53, v82, vcc
	v_rsq_f32_e32 v82, v53
	v_mul_f32_e32 v53, 0x4b800000, v52
	v_cndmask_b32_e64 v52, v52, v53, s[4:5]
	v_rsq_f32_e32 v83, v52
	s_waitcnt lgkmcnt(0)
	v_pk_add_f32 v[52:53], v[78:79], v[80:81]
	ds_bpermute_b32 v79, v86, v53
	ds_bpermute_b32 v78, v86, v52
	v_mul_f32_e32 v80, 0x45800000, v82
	v_cndmask_b32_e32 v90, v82, v80, vcc
	v_mul_f32_e32 v80, 0x45800000, v83
	v_cndmask_b32_e64 v82, v83, v80, s[4:5]
	s_waitcnt lgkmcnt(0)
	v_pk_add_f32 v[52:53], v[52:53], v[78:79]
	s_add_u32 s4, s24, 0x4000
	v_pk_fma_f32 v[52:53], v[52:53], s[12:13], v[50:51] op_sel_hi:[1,0,0]
	s_addc_u32 s5, s25, 0
	v_mul_f32_e32 v78, 0x4b800000, v53
	v_cmp_gt_f32_e32 vcc, s47, v53
	v_cmp_gt_f32_e64 s[6:7], s47, v52
	s_nop 0
	v_cndmask_b32_e32 v53, v53, v78, vcc
	v_mul_f32_e32 v78, 0x4b800000, v52
	v_rsq_f32_e32 v53, v53
	v_cndmask_b32_e64 v52, v52, v78, s[6:7]
	v_rsq_f32_e32 v52, v52
	v_mul_f32_e32 v78, 0x45800000, v53
	v_cndmask_b32_e32 v80, v53, v78, vcc
	v_mul_f32_e32 v53, 0x45800000, v52
	v_cndmask_b32_e64 v52, v52, v53, s[6:7]
	v_lshl_add_u64 v[78:79], s[24:25], 0, v[34:35]
	v_add_co_u32_e32 v86, vcc, s48, v78
	global_load_dwordx4 v[96:99], v34, s[4:5] offset:16
	global_load_dwordx4 v[100:103], v34, s[4:5]
	global_load_dwordx4 v[104:107], v[44:45], off offset:16
	global_load_dwordx4 v[108:111], v[44:45], off
	v_addc_co_u32_e32 v87, vcc, 0, v79, vcc
	v_lshl_add_u64 v[120:121], v[78:79], 0, s[14:15]
	global_load_dwordx4 v[112:115], v[86:87], off
	global_load_dwordx4 v[116:119], v[120:121], off offset:16
	v_pk_mul_f32 v[86:87], v[94:95], v[90:91] op_sel_hi:[1,0]
	v_pk_mul_f32 v[92:93], v[92:93], v[90:91] op_sel_hi:[1,0]
	v_pk_mul_f32 v[88:89], v[88:89], v[90:91] op_sel_hi:[1,0]
	v_pk_mul_f32 v[84:85], v[84:85], v[90:91] op_sel_hi:[1,0]
	v_pk_mul_f32 v[72:73], v[72:73], v[82:83] op_sel_hi:[1,0]
	v_pk_mul_f32 v[94:95], v[70:71], v[82:83] op_sel_hi:[1,0]
	v_pk_mul_f32 v[64:65], v[64:65], v[80:81] op_sel_hi:[1,0]
	v_pk_mul_f32 v[62:63], v[62:63], v[80:81] op_sel_hi:[1,0]
	v_pk_mul_f32 v[56:57], v[56:57], v[52:53] op_sel_hi:[1,0]
	v_pk_mul_f32 v[54:55], v[54:55], v[52:53] op_sel_hi:[1,0]
	v_lshl_add_u64 v[78:79], v[48:49], 0, s[16:17]
	v_pk_mul_f32 v[76:77], v[76:77], v[82:83] op_sel_hi:[1,0]
	v_pk_mul_f32 v[74:75], v[74:75], v[82:83] op_sel_hi:[1,0]
	v_lshl_add_u64 v[70:71], v[48:49], 0, s[22:23]
	v_pk_mul_f32 v[68:69], v[68:69], v[80:81] op_sel_hi:[1,0]
	v_pk_mul_f32 v[66:67], v[66:67], v[80:81] op_sel_hi:[1,0]
	v_lshl_add_u64 v[122:123], v[48:49], 0, s[20:21]
	v_pk_mul_f32 v[60:61], v[60:61], v[52:53] op_sel_hi:[1,0]
	v_pk_mul_f32 v[58:59], v[58:59], v[52:53] op_sel_hi:[1,0]
	v_lshl_add_u64 v[124:125], v[48:49], 0, s[18:19]
	v_pk_mul_f32 v[8:9], v[8:9], v[52:53] op_sel_hi:[1,0]
	v_pk_mul_f32 v[6:7], v[6:7], v[52:53] op_sel_hi:[1,0]
	v_pk_mul_f32 v[32:33], v[32:33], v[52:53] op_sel_hi:[1,0]
	v_pk_mul_f32 v[30:31], v[30:31], v[52:53] op_sel_hi:[1,0]
	v_pk_mul_f32 v[16:17], v[16:17], v[90:91] op_sel_hi:[1,0]
	v_pk_mul_f32 v[14:15], v[14:15], v[90:91] op_sel_hi:[1,0]
	v_pk_mul_f32 v[20:21], v[20:21], v[90:91] op_sel_hi:[1,0]
	v_pk_mul_f32 v[18:19], v[18:19], v[90:91] op_sel_hi:[1,0]
	v_pk_mul_f32 v[4:5], v[4:5], v[80:81] op_sel_hi:[1,0]
	v_pk_mul_f32 v[2:3], v[2:3], v[80:81] op_sel_hi:[1,0]
	v_pk_mul_f32 v[12:13], v[12:13], v[82:83] op_sel_hi:[1,0]
	v_pk_mul_f32 v[10:11], v[10:11], v[82:83] op_sel_hi:[1,0]
	v_pk_mul_f32 v[24:25], v[24:25], v[82:83] op_sel_hi:[1,0]
	v_pk_mul_f32 v[22:23], v[22:23], v[82:83] op_sel_hi:[1,0]
	v_pk_mul_f32 v[28:29], v[28:29], v[80:81] op_sel_hi:[1,0]
	v_pk_mul_f32 v[26:27], v[26:27], v[80:81] op_sel_hi:[1,0]
	s_add_i32 s13, s13, s44
	s_add_i32 s10, s10, s45
	s_cmpk_lt_i32 s13, 0x2000
	s_waitcnt vmcnt(5)
	v_pk_add_f32 v[98:99], v[98:99], 1.0 op_sel_hi:[1,0]
	s_waitcnt vmcnt(4)
	v_pk_add_f32 v[102:103], v[102:103], 1.0 op_sel_hi:[1,0]
	v_pk_add_f32 v[100:101], v[100:101], 1.0 op_sel_hi:[1,0]
	v_pk_add_f32 v[96:97], v[96:97], 1.0 op_sel_hi:[1,0]
	s_waitcnt vmcnt(2)
	v_pk_mul_f32 v[102:103], v[110:111], v[102:103]
	v_pk_mul_f32 v[100:101], v[108:109], v[100:101]
	v_pk_mul_f32 v[98:99], v[106:107], v[98:99]
	v_pk_mul_f32 v[96:97], v[104:105], v[96:97]
	s_waitcnt vmcnt(1)
	v_pk_fma_f32 v[92:93], v[92:93], v[102:103], v[114:115]
	v_pk_fma_f32 v[86:87], v[86:87], v[100:101], v[112:113]
	s_waitcnt vmcnt(0)
	v_pk_fma_f32 v[84:85], v[84:85], v[98:99], v[118:119]
	v_pk_fma_f32 v[88:89], v[88:89], v[96:97], v[116:117]
	v_pk_fma_f32 v[72:73], v[72:73], v[102:103], v[114:115]
	v_pk_fma_f32 v[94:95], v[94:95], v[98:99], v[118:119]
	v_pk_fma_f32 v[64:65], v[102:103], v[64:65], v[114:115]
	v_pk_fma_f32 v[62:63], v[62:63], v[98:99], v[118:119]
	v_pk_fma_f32 v[102:103], v[102:103], v[56:57], v[114:115]
	v_pk_fma_f32 v[98:99], v[98:99], v[54:55], v[118:119]
	v_cvt_pk_bf16_f32 v54, v86, v87
	v_cvt_pk_bf16_f32 v55, v92, v93
	v_cvt_pk_bf16_f32 v56, v88, v89
	v_cvt_pk_bf16_f32 v57, v84, v85
	v_pk_fma_f32 v[76:77], v[76:77], v[100:101], v[112:113]
	v_pk_fma_f32 v[74:75], v[74:75], v[96:97], v[116:117]
	global_store_dwordx4 v[78:79], v[54:57], off nt
	v_pk_fma_f32 v[68:69], v[100:101], v[68:69], v[112:113]
	v_pk_fma_f32 v[66:67], v[66:67], v[96:97], v[116:117]
	v_cvt_pk_bf16_f32 v54, v76, v77
	v_cvt_pk_bf16_f32 v55, v72, v73
	v_cvt_pk_bf16_f32 v56, v74, v75
	v_cvt_pk_bf16_f32 v57, v94, v95
	global_store_dwordx4 v[70:71], v[54:57], off nt
	v_pk_fma_f32 v[60:61], v[100:101], v[60:61], v[112:113]
	v_pk_fma_f32 v[58:59], v[96:97], v[58:59], v[116:117]
	v_cvt_pk_bf16_f32 v54, v68, v69
	v_cvt_pk_bf16_f32 v55, v64, v65
	v_cvt_pk_bf16_f32 v56, v66, v67
	v_cvt_pk_bf16_f32 v57, v62, v63
	global_store_dwordx4 v[122:123], v[54:57], off nt
	s_nop 1
	v_cvt_pk_bf16_f32 v54, v60, v61
	v_cvt_pk_bf16_f32 v55, v102, v103
	v_cvt_pk_bf16_f32 v56, v58, v59
	v_cvt_pk_bf16_f32 v57, v98, v99
	global_store_dwordx4 v[124:125], v[54:57], off nt
	global_load_dwordx4 v[54:57], v135, s[4:5]
	s_nop 0
	global_load_dwordx4 v[58:61], v135, s[4:5] offset:16
	global_load_dwordx4 v[62:65], v[46:47], off
	global_load_dwordx4 v[66:69], v[46:47], off offset:16
	global_load_dwordx4 v[72:75], v[120:121], off offset:2048
	global_load_dwordx4 v[84:87], v[120:121], off offset:2064
	s_waitcnt vmcnt(5)
	v_pk_add_f32 v[52:53], v[56:57], 1.0 op_sel_hi:[1,0]
	v_pk_add_f32 v[54:55], v[54:55], 1.0 op_sel_hi:[1,0]
	s_waitcnt vmcnt(4)
	v_pk_add_f32 v[56:57], v[60:61], 1.0 op_sel_hi:[1,0]
	v_pk_add_f32 v[58:59], v[58:59], 1.0 op_sel_hi:[1,0]
	s_waitcnt vmcnt(3)
	v_pk_mul_f32 v[52:53], v[64:65], v[52:53]
	v_pk_mul_f32 v[54:55], v[62:63], v[54:55]
	s_waitcnt vmcnt(2)
	v_pk_mul_f32 v[56:57], v[68:69], v[56:57]
	v_pk_mul_f32 v[58:59], v[66:67], v[58:59]
	s_waitcnt vmcnt(1)
	v_pk_fma_f32 v[14:15], v[14:15], v[52:53], v[74:75]
	v_pk_fma_f32 v[16:17], v[16:17], v[54:55], v[72:73]
	s_waitcnt vmcnt(0)
	v_pk_fma_f32 v[18:19], v[18:19], v[56:57], v[86:87]
	v_pk_fma_f32 v[20:21], v[20:21], v[58:59], v[84:85]
	v_pk_fma_f32 v[60:61], v[2:3], v[52:53], v[74:75]
	v_pk_fma_f32 v[62:63], v[4:5], v[54:55], v[72:73]
	v_cvt_pk_bf16_f32 v2, v16, v17
	v_cvt_pk_bf16_f32 v3, v14, v15
	v_cvt_pk_bf16_f32 v4, v20, v21
	v_cvt_pk_bf16_f32 v5, v18, v19
	v_pk_fma_f32 v[10:11], v[10:11], v[52:53], v[74:75]
	v_pk_fma_f32 v[12:13], v[12:13], v[54:55], v[72:73]
	v_pk_fma_f32 v[22:23], v[22:23], v[56:57], v[86:87]
	v_pk_fma_f32 v[24:25], v[24:25], v[58:59], v[84:85]
	global_store_dwordx4 v[78:79], v[2:5], off offset:1024 nt
	v_pk_fma_f32 v[26:27], v[26:27], v[56:57], v[86:87]
	v_pk_fma_f32 v[28:29], v[28:29], v[58:59], v[84:85]
	v_cvt_pk_bf16_f32 v2, v12, v13
	v_cvt_pk_bf16_f32 v3, v10, v11
	v_cvt_pk_bf16_f32 v4, v24, v25
	v_cvt_pk_bf16_f32 v5, v22, v23
	global_store_dwordx4 v[70:71], v[2:5], off offset:1024 nt
	v_pk_fma_f32 v[6:7], v[6:7], v[52:53], v[74:75]
	v_pk_fma_f32 v[8:9], v[8:9], v[54:55], v[72:73]
	v_cvt_pk_bf16_f32 v2, v62, v63
	v_cvt_pk_bf16_f32 v3, v60, v61
	v_cvt_pk_bf16_f32 v4, v28, v29
	v_cvt_pk_bf16_f32 v5, v26, v27
	v_pk_fma_f32 v[30:31], v[30:31], v[56:57], v[86:87]
	v_pk_fma_f32 v[32:33], v[32:33], v[58:59], v[84:85]
	global_store_dwordx4 v[122:123], v[2:5], off offset:1024 nt
	s_nop 1
	v_cvt_pk_bf16_f32 v2, v8, v9
	v_cvt_pk_bf16_f32 v3, v6, v7
	v_cvt_pk_bf16_f32 v4, v32, v33
	v_cvt_pk_bf16_f32 v5, v30, v31
	global_store_dwordx4 v[124:125], v[2:5], off offset:1024 nt
	s_cbranch_scc1 .LBB0_1507

.LBB0_1878:
	s_ashr_i32 s9, s8, 31
	s_lshl_b64 s[14:15], s[8:9], 11
	v_lshl_add_u64 v[54:55], v[38:39], 0, s[14:15]
	v_add_co_u32_e32 v30, vcc, s44, v54
	s_add_i32 s48, s8, 1
	s_nop 0
	v_addc_co_u32_e32 v31, vcc, 0, v55, vcc
	s_add_i32 s4, s8, 2
	s_add_i32 s0, s8, 3
	global_load_dwordx4 v[2:5], v[54:55], off
	global_load_dwordx4 v[6:9], v[54:55], off offset:1024
	global_load_dwordx4 v[10:13], v[54:55], off offset:2048
	global_load_dwordx4 v[14:17], v[54:55], off offset:3072
	global_load_dwordx4 v[18:21], v[30:31], off
	global_load_dwordx4 v[22:25], v[30:31], off offset:1024
	global_load_dwordx4 v[26:29], v[30:31], off offset:2048
	s_ashr_i32 s49, s48, 31
	s_ashr_i32 s5, s4, 31
	s_ashr_i32 s1, s0, 31
	s_ashr_i32 s22, s11, 10
	s_lshl_b64 s[50:51], s[8:9], 6
	s_lshl_b64 s[20:21], s[48:49], 11
	s_lshl_b64 s[18:19], s[4:5], 11
	s_lshl_b64 s[16:17], s[0:1], 11
	s_add_u32 s50, s24, s50
	s_addc_u32 s51, s25, s51
	global_load_dwordx4 v[32:35], v[30:31], off offset:3072
	global_load_dwordx4 v[72:75], v37, s[50:51] offset:48
	global_load_dwordx4 v[76:79], v37, s[50:51] offset:32
	global_load_dwordx4 v[84:87], v37, s[50:51] offset:16
	global_load_dwordx4 v[148:151], v37, s[50:51]
	s_lshl_b64 s[48:49], s[48:49], 6
	s_add_u32 s48, s24, s48
	s_addc_u32 s49, s25, s49
	global_load_dwordx4 v[152:155], v37, s[48:49] offset:48
	global_load_dwordx4 v[156:159], v37, s[48:49] offset:32
	global_load_dwordx4 v[160:163], v37, s[48:49] offset:16
	global_load_dwordx4 v[164:167], v37, s[48:49]
	s_lshl_b64 s[4:5], s[4:5], 6
	s_add_u32 s4, s24, s4
	s_addc_u32 s5, s25, s5
	global_load_dwordx4 v[168:171], v37, s[4:5] offset:16
	global_load_dwordx4 v[172:175], v37, s[4:5]
	s_lshl_b64 s[0:1], s[0:1], 6
	s_add_u32 s0, s24, s0
	s_addc_u32 s1, s25, s1
	s_waitcnt vmcnt(0)
	v_lshlrev_b32_e32 v56, 16, v2
	v_and_b32_e32 v57, 0xffff0000, v2
	v_lshlrev_b32_e32 v60, 16, v3
	v_and_b32_e32 v61, 0xffff0000, v3
	v_lshl_add_u64 v[2:3], v[40:41], 0, s[14:15]
	v_lshlrev_b32_e32 v102, 16, v14
	v_and_b32_e32 v103, 0xffff0000, v14
	v_lshlrev_b32_e32 v104, 16, v15
	v_and_b32_e32 v105, 0xffff0000, v15
	v_lshlrev_b32_e32 v98, 16, v16
	v_and_b32_e32 v99, 0xffff0000, v16
	v_lshlrev_b32_e32 v100, 16, v17
	v_and_b32_e32 v101, 0xffff0000, v17
	v_lshlrev_b32_e32 v126, 16, v26
	v_and_b32_e32 v127, 0xffff0000, v26
	v_lshlrev_b32_e32 v130, 16, v27
	v_and_b32_e32 v131, 0xffff0000, v27
	v_lshlrev_b32_e32 v128, 16, v28
	v_and_b32_e32 v129, 0xffff0000, v28
	v_lshlrev_b32_e32 v132, 16, v29
	v_and_b32_e32 v133, 0xffff0000, v29
	global_load_dwordx4 v[26:29], v[2:3], off
	global_load_dwordx4 v[14:17], v[2:3], off offset:1024
	v_lshl_add_u64 v[2:3], v[40:41], 0, s[20:21]
	v_lshlrev_b32_e32 v64, 16, v10
	v_and_b32_e32 v65, 0xffff0000, v10
	v_lshlrev_b32_e32 v68, 16, v11
	v_and_b32_e32 v69, 0xffff0000, v11
	v_lshlrev_b32_e32 v66, 16, v12
	v_and_b32_e32 v67, 0xffff0000, v12
	v_lshlrev_b32_e32 v70, 16, v13
	v_and_b32_e32 v71, 0xffff0000, v13
	v_lshlrev_b32_e32 v94, 16, v22
	v_and_b32_e32 v95, 0xffff0000, v22
	v_lshlrev_b32_e32 v96, 16, v23
	v_and_b32_e32 v97, 0xffff0000, v23
	v_lshlrev_b32_e32 v90, 16, v24
	v_and_b32_e32 v91, 0xffff0000, v24
	v_lshlrev_b32_e32 v92, 16, v25
	v_and_b32_e32 v93, 0xffff0000, v25
	global_load_dwordx4 v[176:179], v37, s[4:5] offset:48
	global_load_dwordx4 v[180:183], v37, s[4:5] offset:32
	global_load_dwordx4 v[22:25], v[2:3], off
	global_load_dwordx4 v[10:13], v[2:3], off offset:1024
	v_lshl_add_u64 v[2:3], v[40:41], 0, s[18:19]
	v_lshlrev_b32_e32 v58, 16, v4
	v_and_b32_e32 v59, 0xffff0000, v4
	v_lshlrev_b32_e32 v62, 16, v5
	v_and_b32_e32 v63, 0xffff0000, v5
	v_lshlrev_b32_e32 v118, 16, v18
	v_and_b32_e32 v119, 0xffff0000, v18
	v_lshlrev_b32_e32 v122, 16, v19
	v_and_b32_e32 v123, 0xffff0000, v19
	v_lshlrev_b32_e32 v120, 16, v20
	v_and_b32_e32 v121, 0xffff0000, v20
	v_lshlrev_b32_e32 v124, 16, v21
	v_and_b32_e32 v125, 0xffff0000, v21
	global_load_dwordx4 v[18:21], v[2:3], off
	s_nop 0
	global_load_dwordx4 v[2:5], v[2:3], off offset:1024
	s_nop 0
	global_load_dwordx4 v[184:187], v37, s[0:1] offset:16
	global_load_dwordx4 v[188:191], v37, s[0:1]
	v_lshlrev_b32_e32 v110, 16, v6
	v_and_b32_e32 v111, 0xffff0000, v6
	v_lshlrev_b32_e32 v114, 16, v7
	v_and_b32_e32 v115, 0xffff0000, v7
	v_lshl_add_u64 v[6:7], v[40:41], 0, s[16:17]
	v_mov_b32_e32 v80, v149
	v_mov_b32_e32 v81, v150
	v_mov_b32_e32 v149, v151
	v_lshlrev_b32_e32 v106, 16, v8
	v_and_b32_e32 v107, 0xffff0000, v8
	v_lshlrev_b32_e32 v108, 16, v9
	v_and_b32_e32 v109, 0xffff0000, v9
	v_lshlrev_b32_e32 v82, 16, v32
	v_and_b32_e32 v83, 0xffff0000, v32
	v_lshlrev_b32_e32 v88, 16, v33
	v_and_b32_e32 v89, 0xffff0000, v33
	global_load_dwordx4 v[30:33], v[6:7], off
	s_nop 0
	global_load_dwordx4 v[6:9], v[6:7], off offset:1024
	v_pk_add_f32 v[80:81], v[80:81], v[148:149]
	global_load_dwordx4 v[148:151], v37, s[0:1] offset:48
	global_load_dwordx4 v[192:195], v37, s[0:1] offset:32
	v_mov_b32_e32 v196, v85
	v_mov_b32_e32 v197, v86
	v_mov_b32_e32 v85, v87
	v_pk_add_f32 v[84:85], v[196:197], v[84:85]
	v_pk_add_f32 v[80:81], v[80:81], v[80:81] op_sel:[0,1] op_sel_hi:[1,0]
	v_pk_add_f32 v[84:85], v[84:85], v[84:85] op_sel:[0,1] op_sel_hi:[1,0]
	v_add_f32_e32 v76, v76, v77
	v_add_f32_e32 v78, v78, v79
	v_mov_b32_e32 v81, v72
	v_mov_b32_e32 v85, v73
	v_mov_b32_e32 v77, v74
	v_mov_b32_e32 v79, v75
	v_pk_add_f32 v[72:73], v[80:81], v[84:85]
	v_pk_add_f32 v[74:75], v[76:77], v[78:79]
	v_mov_b32_e32 v76, v161
	v_pk_add_f32 v[72:73], v[72:73], v[74:75]
	v_mov_b32_e32 v74, v165
	v_mov_b32_e32 v75, v166
	v_mov_b32_e32 v165, v167
	v_mov_b32_e32 v77, v162
	v_mov_b32_e32 v161, v163
	v_pk_add_f32 v[74:75], v[74:75], v[164:165]
	v_pk_add_f32 v[76:77], v[76:77], v[160:161]
	v_pk_add_f32 v[74:75], v[74:75], v[74:75] op_sel:[0,1] op_sel_hi:[1,0]
	v_pk_add_f32 v[76:77], v[76:77], v[76:77] op_sel:[0,1] op_sel_hi:[1,0]
	v_add_f32_e32 v78, v156, v157
	v_add_f32_e32 v80, v158, v159
	v_mov_b32_e32 v75, v152
	v_mov_b32_e32 v77, v153
	v_mov_b32_e32 v79, v154
	v_mov_b32_e32 v81, v155
	v_pk_add_f32 v[74:75], v[74:75], v[76:77]
	v_pk_add_f32 v[76:77], v[78:79], v[80:81]
	v_lshlrev_b32_e32 v112, 16, v34
	v_pk_add_f32 v[74:75], v[74:75], v[76:77]
	v_mov_b32_e32 v77, v72
	v_mov_b32_e32 v76, v74
	v_mov_b32_e32 v72, v75
	v_pk_add_f32 v[72:73], v[76:77], v[72:73]
	v_and_b32_e32 v113, 0xffff0000, v34
	v_pk_fma_f32 v[72:73], v[72:73], s[10:11], v[52:53] op_sel_hi:[1,0,0]
	v_lshlrev_b32_e32 v116, 16, v35
	v_mul_f32_e32 v34, 0x4b800000, v73
	v_cmp_gt_f32_e32 vcc, s45, v73
	v_cmp_gt_f32_e64 s[0:1], s45, v72
	v_and_b32_e32 v117, 0xffff0000, v35
	v_cndmask_b32_e32 v34, v73, v34, vcc
	v_rsq_f32_e32 v34, v34
	v_mul_f32_e32 v73, 0x4b800000, v72
	v_cndmask_b32_e64 v72, v72, v73, s[0:1]
	v_rsq_f32_e32 v80, v72
	v_mul_f32_e32 v35, 0x45800000, v34
	v_cndmask_b32_e32 v136, v34, v35, vcc
	v_mov_b32_e32 v34, v173
	v_mov_b32_e32 v35, v174
	v_mov_b32_e32 v173, v175
	v_mov_b32_e32 v72, v169
	v_mov_b32_e32 v73, v170
	v_mov_b32_e32 v169, v171
	v_pk_add_f32 v[34:35], v[34:35], v[172:173]
	v_pk_add_f32 v[72:73], v[72:73], v[168:169]
	v_pk_add_f32 v[34:35], v[34:35], v[34:35] op_sel:[0,1] op_sel_hi:[1,0]
	v_pk_add_f32 v[72:73], v[72:73], v[72:73] op_sel:[0,1] op_sel_hi:[1,0]
	s_waitcnt vmcnt(10)
	v_add_f32_e32 v74, v180, v181
	v_add_f32_e32 v76, v182, v183
	v_mov_b32_e32 v35, v176
	v_mov_b32_e32 v73, v177
	v_mov_b32_e32 v75, v178
	v_mov_b32_e32 v77, v179
	v_pk_add_f32 v[34:35], v[34:35], v[72:73]
	v_pk_add_f32 v[72:73], v[74:75], v[76:77]
	s_waitcnt vmcnt(5)
	v_mov_b32_e32 v74, v185
	v_pk_add_f32 v[34:35], v[34:35], v[72:73]
	s_waitcnt vmcnt(4)
	v_mov_b32_e32 v72, v189
	v_mov_b32_e32 v73, v190
	v_mov_b32_e32 v189, v191
	v_mov_b32_e32 v75, v186
	v_mov_b32_e32 v185, v187
	v_pk_add_f32 v[72:73], v[72:73], v[188:189]
	v_pk_add_f32 v[74:75], v[74:75], v[184:185]
	v_pk_add_f32 v[72:73], v[72:73], v[72:73] op_sel:[0,1] op_sel_hi:[1,0]
	v_pk_add_f32 v[74:75], v[74:75], v[74:75] op_sel:[0,1] op_sel_hi:[1,0]
	s_waitcnt vmcnt(0)
	v_add_f32_e32 v76, v192, v193
	v_add_f32_e32 v78, v194, v195
	v_mov_b32_e32 v73, v148
	v_mov_b32_e32 v75, v149
	v_mov_b32_e32 v77, v150
	v_mov_b32_e32 v79, v151
	v_pk_add_f32 v[72:73], v[72:73], v[74:75]
	v_pk_add_f32 v[74:75], v[76:77], v[78:79]
	v_mul_f32_e32 v81, 0x45800000, v80
	v_pk_add_f32 v[72:73], v[72:73], v[74:75]
	v_mov_b32_e32 v75, v34
	v_mov_b32_e32 v74, v72
	v_mov_b32_e32 v34, v73
	v_pk_add_f32 v[34:35], v[74:75], v[34:35]
	v_cndmask_b32_e64 v140, v80, v81, s[0:1]
	v_pk_fma_f32 v[34:35], v[34:35], s[10:11], v[52:53] op_sel_hi:[1,0,0]
	s_nop 0
	v_mul_f32_e32 v72, 0x4b800000, v35
	v_cmp_gt_f32_e32 vcc, s45, v35
	v_cmp_gt_f32_e64 s[4:5], s45, v34
	s_nop 0
	v_cndmask_b32_e32 v35, v35, v72, vcc
	v_mul_f32_e32 v72, 0x4b800000, v34
	v_rsq_f32_e32 v35, v35
	v_cndmask_b32_e64 v34, v34, v72, s[4:5]
	v_rsq_f32_e32 v34, v34
	v_mul_f32_e32 v72, 0x45800000, v35
	v_cndmask_b32_e32 v138, v35, v72, vcc
	v_mul_f32_e32 v35, 0x45800000, v34
	v_cndmask_b32_e64 v134, v34, v35, s[4:5]
	s_mul_i32 s0, s22, 9
	s_ashr_i32 s1, s0, 31
	s_lshl_b64 s[0:1], s[0:1], 12
	s_add_u32 s22, s68, s0
	s_addc_u32 s23, s69, s1
	s_add_u32 s0, s22, 0x5000
	s_addc_u32 s1, s23, 0
	global_load_dwordx4 v[72:75], v[42:43], off
	global_load_dwordx4 v[76:79], v36, s[0:1]
	global_load_dwordx4 v[84:87], v36, s[0:1] offset:16
	global_load_dwordx4 v[148:151], v[42:43], off offset:16
	global_load_dwordx4 v[152:155], v135, s[0:1]
	global_load_dwordx4 v[156:159], v[44:45], off
	global_load_dwordx4 v[160:163], v[44:45], off offset:16
	global_load_dwordx4 v[164:167], v135, s[0:1] offset:16
	v_lshlrev_b32_e32 v168, 16, v22
	v_and_b32_e32 v169, 0xffff0000, v22
	v_lshlrev_b32_e32 v172, 16, v18
	v_and_b32_e32 v173, 0xffff0000, v18
	v_lshlrev_b32_e32 v18, 16, v19
	v_and_b32_e32 v19, 0xffff0000, v19
	v_lshlrev_b32_e32 v80, 16, v28
	v_and_b32_e32 v81, 0xffff0000, v28
	v_lshlrev_b32_e32 v28, 16, v29
	v_and_b32_e32 v29, 0xffff0000, v29
	v_lshlrev_b32_e32 v22, 16, v23
	v_and_b32_e32 v23, 0xffff0000, v23
	v_lshlrev_b32_e32 v174, 16, v20
	v_and_b32_e32 v175, 0xffff0000, v20
	v_lshlrev_b32_e32 v20, 16, v21
	v_and_b32_e32 v21, 0xffff0000, v21
	v_pk_mul_f32 v[168:169], v[140:141], v[168:169] op_sel_hi:[0,1]
	v_pk_mul_f32 v[18:19], v[138:139], v[18:19] op_sel_hi:[0,1]
	v_lshlrev_b32_e32 v34, 16, v26
	v_and_b32_e32 v35, 0xffff0000, v26
	v_lshlrev_b32_e32 v26, 16, v27
	v_and_b32_e32 v27, 0xffff0000, v27
	v_pk_mul_f32 v[28:29], v[136:137], v[28:29] op_sel_hi:[0,1]
	v_pk_mul_f32 v[22:23], v[140:141], v[22:23] op_sel_hi:[0,1]
	v_pk_mul_f32 v[20:21], v[138:139], v[20:21] op_sel_hi:[0,1]
	v_lshlrev_b32_e32 v170, 16, v24
	v_and_b32_e32 v171, 0xffff0000, v24
	v_lshlrev_b32_e32 v24, 16, v25
	v_and_b32_e32 v25, 0xffff0000, v25
	v_lshlrev_b32_e32 v176, 16, v30
	v_and_b32_e32 v177, 0xffff0000, v30
	v_lshlrev_b32_e32 v30, 16, v31
	v_and_b32_e32 v31, 0xffff0000, v31
	v_pk_mul_f32 v[26:27], v[136:137], v[26:27] op_sel_hi:[0,1]
	v_pk_mul_f32 v[34:35], v[136:137], v[34:35] op_sel_hi:[0,1]
	v_pk_mul_f32 v[24:25], v[140:141], v[24:25] op_sel_hi:[0,1]
	v_pk_mul_f32 v[30:31], v[134:135], v[30:31] op_sel_hi:[0,1]
	v_lshlrev_b32_e32 v178, 16, v32
	v_and_b32_e32 v179, 0xffff0000, v32
	v_lshlrev_b32_e32 v32, 16, v33
	v_and_b32_e32 v33, 0xffff0000, v33
	v_lshlrev_b32_e32 v180, 16, v14
	v_and_b32_e32 v181, 0xffff0000, v14
	v_pk_mul_f32 v[80:81], v[136:137], v[80:81] op_sel_hi:[0,1]
	v_pk_mul_f32 v[32:33], v[134:135], v[32:33] op_sel_hi:[0,1]
	v_lshlrev_b32_e32 v14, 16, v15
	v_and_b32_e32 v15, 0xffff0000, v15
	v_pk_mul_f32 v[14:15], v[136:137], v[14:15] op_sel_hi:[0,1]
	v_pk_mul_f32 v[170:171], v[140:141], v[170:171] op_sel_hi:[0,1]
	v_pk_mul_f32 v[172:173], v[138:139], v[172:173] op_sel_hi:[0,1]
	v_pk_mul_f32 v[174:175], v[138:139], v[174:175] op_sel_hi:[0,1]
	v_pk_mul_f32 v[176:177], v[134:135], v[176:177] op_sel_hi:[0,1]
	v_pk_mul_f32 v[178:179], v[134:135], v[178:179] op_sel_hi:[0,1]
	s_waitcnt vmcnt(6)
	v_pk_mul_f32 v[182:183], v[78:79], v[74:75]
	v_pk_mul_f32 v[184:185], v[76:77], v[72:73]
	s_waitcnt vmcnt(4)
	v_pk_mul_f32 v[150:151], v[86:87], v[150:151]
	v_pk_fma_f32 v[76:77], v[184:185], v[168:169], v[64:65]
	v_pk_fma_f32 v[64:65], v[182:183], v[18:19], v[122:123]
	v_lshlrev_b32_e32 v18, 16, v16
	v_and_b32_e32 v19, 0xffff0000, v16
	s_waitcnt vmcnt(2)
	v_pk_mul_f32 v[154:155], v[154:155], v[158:159]
	s_waitcnt vmcnt(0)
	v_pk_mul_f32 v[158:159], v[164:165], v[160:161]
	v_pk_fma_f32 v[78:79], v[28:29], v[150:151], v[62:63]
	v_pk_fma_f32 v[72:73], v[182:183], v[22:23], v[68:69]
	v_pk_fma_f32 v[62:63], v[150:151], v[20:21], v[124:125]
	v_lshlrev_b32_e32 v20, 16, v17
	v_and_b32_e32 v21, 0xffff0000, v17
	v_pk_mul_f32 v[22:23], v[136:137], v[18:19] op_sel_hi:[0,1]
	v_pk_mul_f32 v[148:149], v[84:85], v[148:149]
	v_pk_fma_f32 v[84:85], v[26:27], v[182:183], v[60:61]
	v_pk_mul_f32 v[18:19], v[136:137], v[20:21] op_sel_hi:[0,1]
	v_pk_fma_f32 v[20:21], v[22:23], v[158:159], v[106:107]
	v_lshlrev_b32_e32 v22, 16, v10
	v_and_b32_e32 v23, 0xffff0000, v10
	v_lshlrev_b32_e32 v26, 16, v13
	v_and_b32_e32 v27, 0xffff0000, v13
	v_pk_fma_f32 v[86:87], v[34:35], v[184:185], v[56:57]
	v_pk_fma_f32 v[70:71], v[150:151], v[24:25], v[70:71]
	v_pk_fma_f32 v[56:57], v[182:183], v[30:31], v[130:131]
	v_lshlrev_b32_e32 v24, 16, v12
	v_and_b32_e32 v25, 0xffff0000, v12
	v_pk_mul_f32 v[12:13], v[140:141], v[22:23] op_sel_hi:[0,1]
	v_pk_mul_f32 v[22:23], v[140:141], v[26:27] op_sel_hi:[0,1]
	v_lshlrev_b32_e32 v26, 16, v2
	v_and_b32_e32 v27, 0xffff0000, v2
	v_lshlrev_b32_e32 v28, 16, v4
	v_and_b32_e32 v29, 0xffff0000, v4
	v_lshlrev_b32_e32 v30, 16, v5
	v_and_b32_e32 v31, 0xffff0000, v5
	v_pk_mul_f32 v[4:5], v[138:139], v[26:27] op_sel_hi:[0,1]
	v_pk_mul_f32 v[28:29], v[138:139], v[28:29] op_sel_hi:[0,1]
	v_pk_mul_f32 v[26:27], v[138:139], v[30:31] op_sel_hi:[0,1]
	v_lshlrev_b32_e32 v30, 16, v6
	v_and_b32_e32 v31, 0xffff0000, v6
	v_lshlrev_b32_e32 v6, 16, v7
	v_and_b32_e32 v7, 0xffff0000, v7
	v_pk_fma_f32 v[28:29], v[158:159], v[28:29], v[90:91]
	v_lshlrev_b32_e32 v90, 16, v9
	v_and_b32_e32 v91, 0xffff0000, v9
	v_pk_mul_f32 v[6:7], v[134:135], v[6:7] op_sel_hi:[0,1]
	v_pk_mul_f32 v[152:153], v[152:153], v[156:157]
	v_pk_mul_f32 v[156:157], v[166:167], v[162:163]
	v_pk_fma_f32 v[80:81], v[80:81], v[148:149], v[58:59]
	v_pk_fma_f32 v[34:35], v[150:151], v[32:33], v[132:133]
	v_pk_mul_f32 v[16:17], v[136:137], v[180:181] op_sel_hi:[0,1]
	v_lshlrev_b32_e32 v32, 16, v8
	v_and_b32_e32 v33, 0xffff0000, v8
	v_pk_mul_f32 v[8:9], v[134:135], v[30:31] op_sel_hi:[0,1]
	v_pk_fma_f32 v[6:7], v[154:155], v[6:7], v[88:89]
	v_pk_mul_f32 v[30:31], v[134:135], v[90:91] op_sel_hi:[0,1]
	v_cvt_pk_bf16_f32 v88, v86, v87
	v_cvt_pk_bf16_f32 v89, v84, v85
	v_cvt_pk_bf16_f32 v90, v80, v81
	v_cvt_pk_bf16_f32 v91, v78, v79
	v_pk_fma_f32 v[14:15], v[14:15], v[154:155], v[114:115]
	v_pk_fma_f32 v[16:17], v[16:17], v[152:153], v[110:111]
	v_pk_fma_f32 v[18:19], v[18:19], v[156:157], v[108:109]
	v_lshlrev_b32_e32 v10, 16, v11
	v_and_b32_e32 v11, 0xffff0000, v11
	global_store_dwordx4 v[54:55], v[88:91], off nt
	v_pk_fma_f32 v[74:75], v[148:149], v[170:171], v[66:67]
	v_pk_mul_f32 v[10:11], v[140:141], v[10:11] op_sel_hi:[0,1]
	v_cvt_pk_bf16_f32 v88, v16, v17
	v_cvt_pk_bf16_f32 v89, v14, v15
	v_cvt_pk_bf16_f32 v90, v20, v21
	v_cvt_pk_bf16_f32 v91, v18, v19
	v_pk_mul_f32 v[24:25], v[140:141], v[24:25] op_sel_hi:[0,1]
	global_store_dwordx4 v[54:55], v[88:91], off offset:1024 nt
	v_lshl_add_u64 v[54:55], v[38:39], 0, s[20:21]
	v_pk_fma_f32 v[10:11], v[10:11], v[154:155], v[104:105]
	v_cvt_pk_bf16_f32 v88, v76, v77
	v_cvt_pk_bf16_f32 v89, v72, v73
	v_cvt_pk_bf16_f32 v90, v74, v75
	v_cvt_pk_bf16_f32 v91, v70, v71
	v_pk_fma_f32 v[12:13], v[12:13], v[152:153], v[102:103]
	v_pk_fma_f32 v[22:23], v[22:23], v[156:157], v[100:101]
	v_pk_fma_f32 v[24:25], v[24:25], v[158:159], v[98:99]
	v_lshlrev_b32_e32 v2, 16, v3
	v_and_b32_e32 v3, 0xffff0000, v3
	global_store_dwordx4 v[54:55], v[88:91], off nt
	v_pk_fma_f32 v[68:69], v[184:185], v[172:173], v[118:119]
	v_pk_fma_f32 v[66:67], v[148:149], v[174:175], v[120:121]
	v_cvt_pk_bf16_f32 v88, v12, v13
	v_cvt_pk_bf16_f32 v89, v10, v11
	v_cvt_pk_bf16_f32 v90, v24, v25
	v_cvt_pk_bf16_f32 v91, v22, v23
	v_pk_mul_f32 v[2:3], v[138:139], v[2:3] op_sel_hi:[0,1]
	global_store_dwordx4 v[54:55], v[88:91], off offset:1024 nt
	v_lshl_add_u64 v[54:55], v[38:39], 0, s[18:19]
	v_pk_fma_f32 v[2:3], v[154:155], v[2:3], v[96:97]
	v_cvt_pk_bf16_f32 v88, v68, v69
	v_cvt_pk_bf16_f32 v89, v64, v65
	v_cvt_pk_bf16_f32 v90, v66, v67
	v_cvt_pk_bf16_f32 v91, v62, v63
	v_pk_fma_f32 v[4:5], v[152:153], v[4:5], v[94:95]
	v_pk_fma_f32 v[26:27], v[156:157], v[26:27], v[92:93]
	global_store_dwordx4 v[54:55], v[88:91], off nt
	v_pk_fma_f32 v[60:61], v[184:185], v[176:177], v[126:127]
	v_pk_fma_f32 v[58:59], v[148:149], v[178:179], v[128:129]
	v_cvt_pk_bf16_f32 v88, v4, v5
	v_cvt_pk_bf16_f32 v89, v2, v3
	v_cvt_pk_bf16_f32 v90, v28, v29
	v_cvt_pk_bf16_f32 v91, v26, v27
	v_pk_mul_f32 v[32:33], v[134:135], v[32:33] op_sel_hi:[0,1]
	global_store_dwordx4 v[54:55], v[88:91], off offset:1024 nt
	v_lshl_add_u64 v[54:55], v[38:39], 0, s[16:17]
	v_pk_fma_f32 v[8:9], v[152:153], v[8:9], v[82:83]
	v_cvt_pk_bf16_f32 v88, v60, v61
	v_cvt_pk_bf16_f32 v89, v56, v57
	v_cvt_pk_bf16_f32 v90, v58, v59
	v_cvt_pk_bf16_f32 v91, v34, v35
	v_pk_fma_f32 v[30:31], v[156:157], v[30:31], v[116:117]
	v_pk_fma_f32 v[32:33], v[158:159], v[32:33], v[112:113]
	global_store_dwordx4 v[54:55], v[88:91], off nt
	s_nop 1
	v_cvt_pk_bf16_f32 v88, v8, v9
	v_cvt_pk_bf16_f32 v89, v6, v7
	v_cvt_pk_bf16_f32 v90, v32, v33
	v_cvt_pk_bf16_f32 v91, v30, v31
	global_store_dwordx4 v[54:55], v[88:91], off offset:1024 nt
	v_pk_mul_f32 v[54:55], v[84:85], v[84:85]
	v_pk_mul_f32 v[82:83], v[86:87], v[86:87]
	v_cmp_lt_i32_e32 vcc, v141, v139
	v_pk_mov_b32 v[88:89], v[82:83], v[54:55] op_sel:[1,0]
	v_mov_b32_e32 v83, v55
	v_pk_add_f32 v[54:55], v[88:89], v[82:83]
	v_pk_mul_f32 v[82:83], v[78:79], v[78:79]
	v_pk_mul_f32 v[88:89], v[80:81], v[80:81]
	v_pk_add_f32 v[54:55], v[54:55], v[54:55] op_sel:[0,1] op_sel_hi:[1,0]
	v_pk_mov_b32 v[90:91], v[88:89], v[82:83] op_sel:[1,0]
	v_mov_b32_e32 v89, v83
	v_pk_add_f32 v[82:83], v[90:91], v[88:89]
	v_mul_f32_e32 v88, v20, v20
	v_mul_f32_e32 v89, v21, v21
	v_pk_add_f32 v[82:83], v[82:83], v[82:83] op_sel:[0,1] op_sel_hi:[1,0]
	v_mov_b32_e32 v55, v88
	v_mov_b32_e32 v83, v89
	v_pk_add_f32 v[54:55], v[54:55], v[82:83]
	v_mul_f32_e32 v82, v17, v17
	v_mul_f32_e32 v88, v15, v15
	v_mul_f32_e32 v90, v18, v18
	v_mul_f32_e32 v91, v19, v19
	v_pk_fma_f32 v[82:83], v[16:17], v[16:17], v[82:83] op_sel_hi:[1,1,0]
	v_pk_fma_f32 v[88:89], v[14:15], v[14:15], v[88:89] op_sel_hi:[1,1,0]
	v_mov_b32_e32 v83, v90
	v_mov_b32_e32 v89, v91
	v_pk_add_f32 v[82:83], v[82:83], v[88:89]
	v_pk_mul_f32 v[88:89], v[76:77], v[76:77]
	v_pk_add_f32 v[54:55], v[54:55], v[82:83]
	v_cndmask_b32_e32 v82, v137, v141, vcc
	v_lshlrev_b32_e32 v98, 2, v82
	v_pk_mul_f32 v[82:83], v[72:73], v[72:73]
	v_cmp_lt_i32_e32 vcc, v142, v139
	v_pk_mov_b32 v[90:91], v[88:89], v[82:83] op_sel:[1,0]
	v_mov_b32_e32 v89, v83
	v_pk_add_f32 v[82:83], v[90:91], v[88:89]
	v_pk_mul_f32 v[88:89], v[70:71], v[70:71]
	v_pk_mul_f32 v[90:91], v[74:75], v[74:75]
	v_pk_add_f32 v[82:83], v[82:83], v[82:83] op_sel:[0,1] op_sel_hi:[1,0]
	v_pk_mov_b32 v[92:93], v[90:91], v[88:89] op_sel:[1,0]
	v_mov_b32_e32 v91, v89
	v_pk_add_f32 v[88:89], v[92:93], v[90:91]
	v_mul_f32_e32 v90, v24, v24
	v_mul_f32_e32 v91, v25, v25
	v_pk_add_f32 v[88:89], v[88:89], v[88:89] op_sel:[0,1] op_sel_hi:[1,0]
	v_mov_b32_e32 v83, v90
	v_mov_b32_e32 v89, v91
	v_pk_add_f32 v[82:83], v[82:83], v[88:89]
	v_mul_f32_e32 v88, v13, v13
	v_mul_f32_e32 v90, v11, v11
	v_mul_f32_e32 v92, v22, v22
	v_mul_f32_e32 v93, v23, v23
	v_pk_fma_f32 v[88:89], v[12:13], v[12:13], v[88:89] op_sel_hi:[1,1,0]
	v_pk_fma_f32 v[90:91], v[10:11], v[10:11], v[90:91] op_sel_hi:[1,1,0]
	v_mov_b32_e32 v89, v92
	v_mov_b32_e32 v91, v93
	v_pk_add_f32 v[88:89], v[88:89], v[90:91]
	v_pk_mul_f32 v[90:91], v[68:69], v[68:69]
	v_pk_add_f32 v[82:83], v[82:83], v[88:89]
	v_mov_b32_e32 v89, v54
	v_mov_b32_e32 v88, v82
	v_mov_b32_e32 v54, v83
	v_pk_add_f32 v[54:55], v[88:89], v[54:55]
	v_cndmask_b32_e32 v88, v137, v142, vcc
	v_cmp_lt_i32_e32 vcc, v143, v139
	v_lshlrev_b32_e32 v99, 2, v88
	ds_bpermute_b32 v83, v98, v55
	v_cndmask_b32_e32 v88, v137, v143, vcc
	v_cmp_lt_i32_e32 vcc, v144, v139
	v_lshlrev_b32_e32 v100, 2, v88
	ds_bpermute_b32 v82, v98, v54
	v_cndmask_b32_e32 v88, v137, v144, vcc
	v_cmp_lt_i32_e32 vcc, v145, v139
	v_lshlrev_b32_e32 v101, 2, v88
	s_waitcnt lgkmcnt(0)
	v_pk_add_f32 v[54:55], v[54:55], v[82:83]
	v_cndmask_b32_e32 v88, v137, v145, vcc
	v_lshlrev_b32_e32 v102, 2, v88
	v_pk_mul_f32 v[88:89], v[64:65], v[64:65]
	ds_bpermute_b32 v83, v99, v55
	v_pk_mov_b32 v[92:93], v[90:91], v[88:89] op_sel:[1,0]
	v_mov_b32_e32 v91, v89
	v_pk_add_f32 v[88:89], v[92:93], v[90:91]
	v_pk_mul_f32 v[90:91], v[62:63], v[62:63]
	v_pk_add_f32 v[88:89], v[88:89], v[88:89] op_sel_hi:[0,1]
	v_pk_mul_f32 v[92:93], v[66:67], v[66:67]
	v_mul_f32_e32 v88, v4, v4
	v_pk_mov_b32 v[94:95], v[92:93], v[90:91] op_sel:[1,0]
	v_mov_b32_e32 v93, v91
	v_pk_add_f32 v[90:91], v[94:95], v[92:93]
	v_pk_fma_f32 v[92:93], v[4:5], v[4:5], v[88:89] op_sel_hi:[1,1,0]
	v_mul_f32_e32 v88, v2, v2
	v_pk_add_f32 v[90:91], v[90:91], v[90:91] op_sel_hi:[0,1]
	v_pk_fma_f32 v[94:95], v[2:3], v[2:3], v[88:89] op_sel_hi:[1,1,0]
	v_mul_f32_e32 v92, v28, v28
	v_mul_f32_e32 v94, v29, v29
	v_mul_f32_e32 v88, v26, v26
	v_mul_f32_e32 v90, v27, v27
	v_pk_add_f32 v[92:93], v[92:93], v[94:95]
	v_pk_add_f32 v[88:89], v[88:89], v[90:91]
	ds_bpermute_b32 v82, v99, v54
	v_pk_add_f32 v[88:89], v[92:93], v[88:89]
	v_pk_mul_f32 v[90:91], v[56:57], v[56:57]
	v_pk_mul_f32 v[92:93], v[60:61], v[60:61]
	v_cmp_lt_i32_e32 vcc, v146, v139
	v_pk_mov_b32 v[94:95], v[92:93], v[90:91] op_sel:[1,0]
	v_mov_b32_e32 v93, v91
	v_pk_add_f32 v[90:91], v[94:95], v[92:93]
	v_pk_mul_f32 v[92:93], v[34:35], v[34:35]
	v_pk_add_f32 v[90:91], v[90:91], v[90:91] op_sel_hi:[0,1]
	v_pk_mul_f32 v[94:95], v[58:59], v[58:59]
	v_mul_f32_e32 v90, v8, v8
	v_pk_mov_b32 v[96:97], v[94:95], v[92:93] op_sel:[1,0]
	v_mov_b32_e32 v95, v93
	s_waitcnt lgkmcnt(0)
	v_pk_add_f32 v[54:55], v[54:55], v[82:83]
	v_pk_add_f32 v[92:93], v[96:97], v[94:95]
	v_pk_fma_f32 v[94:95], v[8:9], v[8:9], v[90:91] op_sel_hi:[1,1,0]
	v_mul_f32_e32 v90, v6, v6
	ds_bpermute_b32 v83, v100, v55
	ds_bpermute_b32 v82, v100, v54
	v_pk_add_f32 v[92:93], v[92:93], v[92:93] op_sel_hi:[0,1]
	v_pk_fma_f32 v[96:97], v[6:7], v[6:7], v[90:91] op_sel_hi:[1,1,0]
	v_mul_f32_e32 v94, v32, v32
	v_mul_f32_e32 v96, v33, v33
	v_mul_f32_e32 v90, v30, v30
	v_mul_f32_e32 v92, v31, v31
	v_pk_add_f32 v[94:95], v[94:95], v[96:97]
	v_pk_add_f32 v[90:91], v[90:91], v[92:93]
	v_mov_b32_e32 v93, v88
	v_pk_add_f32 v[90:91], v[94:95], v[90:91]
	s_waitcnt lgkmcnt(0)
	v_pk_add_f32 v[54:55], v[54:55], v[82:83]
	v_mov_b32_e32 v92, v90
	v_mov_b32_e32 v88, v91
	v_pk_add_f32 v[88:89], v[92:93], v[88:89]
	ds_bpermute_b32 v83, v101, v55
	ds_bpermute_b32 v82, v101, v54
	ds_bpermute_b32 v91, v98, v89
	ds_bpermute_b32 v90, v98, v88
	v_cndmask_b32_e32 v92, v137, v146, vcc
	v_lshlrev_b32_e32 v92, 2, v92
	s_waitcnt lgkmcnt(2)
	v_pk_add_f32 v[54:55], v[54:55], v[82:83]
	ds_bpermute_b32 v83, v102, v55
	s_waitcnt lgkmcnt(1)
	v_pk_add_f32 v[88:89], v[88:89], v[90:91]
	ds_bpermute_b32 v82, v102, v54
	ds_bpermute_b32 v91, v99, v89
	ds_bpermute_b32 v90, v99, v88
	s_waitcnt lgkmcnt(2)
	v_pk_add_f32 v[54:55], v[54:55], v[82:83]
	ds_bpermute_b32 v83, v92, v55
	s_waitcnt lgkmcnt(1)
	v_pk_add_f32 v[88:89], v[88:89], v[90:91]
	ds_bpermute_b32 v82, v92, v54
	ds_bpermute_b32 v91, v100, v89
	ds_bpermute_b32 v90, v100, v88
	s_waitcnt lgkmcnt(2)
	v_pk_add_f32 v[54:55], v[54:55], v[82:83]
	s_nop 0
	v_pk_fma_f32 v[54:55], v[54:55], s[10:11], v[52:53] op_sel_hi:[1,0,0]
	s_waitcnt lgkmcnt(0)
	v_pk_add_f32 v[82:83], v[88:89], v[90:91]
	ds_bpermute_b32 v89, v101, v83
	ds_bpermute_b32 v88, v101, v82
	v_mul_f32_e32 v90, 0x4b800000, v55
	v_cmp_gt_f32_e32 vcc, s45, v55
	v_cmp_gt_f32_e64 s[0:1], s45, v54
	s_waitcnt lgkmcnt(0)
	v_pk_add_f32 v[82:83], v[82:83], v[88:89]
	ds_bpermute_b32 v89, v102, v83
	ds_bpermute_b32 v88, v102, v82
	v_cndmask_b32_e32 v55, v55, v90, vcc
	v_rsq_f32_e32 v90, v55
	v_mul_f32_e32 v55, 0x4b800000, v54
	v_cndmask_b32_e64 v54, v54, v55, s[0:1]
	v_rsq_f32_e32 v91, v54
	s_waitcnt lgkmcnt(0)
	v_pk_add_f32 v[54:55], v[82:83], v[88:89]
	ds_bpermute_b32 v83, v92, v55
	ds_bpermute_b32 v82, v92, v54
	v_mul_f32_e32 v88, 0x45800000, v90
	v_cndmask_b32_e32 v114, v90, v88, vcc
	v_mul_f32_e32 v88, 0x45800000, v91
	v_cndmask_b32_e64 v88, v91, v88, s[0:1]
	s_waitcnt lgkmcnt(0)
	v_pk_add_f32 v[54:55], v[54:55], v[82:83]
	s_add_u32 s0, s22, 0x7000
	v_pk_fma_f32 v[54:55], v[54:55], s[10:11], v[52:53] op_sel_hi:[1,0,0]
	s_addc_u32 s1, s23, 0
	v_mul_f32_e32 v82, 0x4b800000, v55
	v_cmp_gt_f32_e32 vcc, s45, v55
	v_cmp_gt_f32_e64 s[4:5], s45, v54
	s_nop 0
	v_cndmask_b32_e32 v55, v55, v82, vcc
	v_mul_f32_e32 v82, 0x4b800000, v54
	v_rsq_f32_e32 v55, v55
	v_cndmask_b32_e64 v54, v54, v82, s[4:5]
	v_rsq_f32_e32 v54, v54
	v_mul_f32_e32 v82, 0x45800000, v55
	v_cndmask_b32_e32 v82, v55, v82, vcc
	v_mul_f32_e32 v55, 0x45800000, v54
	v_cndmask_b32_e64 v54, v54, v55, s[4:5]
	v_lshl_add_u64 v[110:111], s[22:23], 0, v[36:37]
	v_add_co_u32_e32 v106, vcc, s46, v110
	global_load_dwordx4 v[90:93], v36, s[0:1] offset:16
	global_load_dwordx4 v[94:97], v36, s[0:1]
	global_load_dwordx4 v[98:101], v[46:47], off offset:16
	global_load_dwordx4 v[102:105], v[46:47], off
	v_addc_co_u32_e32 v107, vcc, 0, v111, vcc
	v_lshl_add_u64 v[116:117], v[110:111], 0, s[12:13]
	global_load_dwordx4 v[106:109], v[106:107], off
	v_pk_mul_f32 v[86:87], v[86:87], v[114:115] op_sel_hi:[1,0]
	global_load_dwordx4 v[110:113], v[116:117], off offset:16
	v_pk_mul_f32 v[84:85], v[84:85], v[114:115] op_sel_hi:[1,0]
	v_pk_mul_f32 v[80:81], v[80:81], v[114:115] op_sel_hi:[1,0]
	v_pk_mul_f32 v[118:119], v[78:79], v[114:115] op_sel_hi:[1,0]
	v_pk_mul_f32 v[72:73], v[72:73], v[88:89] op_sel_hi:[1,0]
	v_pk_mul_f32 v[74:75], v[74:75], v[88:89] op_sel_hi:[1,0]
	v_pk_mul_f32 v[64:65], v[64:65], v[82:83] op_sel_hi:[1,0]
	v_pk_mul_f32 v[66:67], v[66:67], v[82:83] op_sel_hi:[1,0]
	v_pk_mul_f32 v[56:57], v[56:57], v[54:55] op_sel_hi:[1,0]
	v_pk_mul_f32 v[58:59], v[58:59], v[54:55] op_sel_hi:[1,0]
	v_lshl_add_u64 v[78:79], v[50:51], 0, s[14:15]
	v_pk_mul_f32 v[76:77], v[76:77], v[88:89] op_sel_hi:[1,0]
	v_pk_mul_f32 v[120:121], v[70:71], v[88:89] op_sel_hi:[1,0]
	v_lshl_add_u64 v[70:71], v[50:51], 0, s[20:21]
	v_pk_mul_f32 v[68:69], v[68:69], v[82:83] op_sel_hi:[1,0]
	v_pk_mul_f32 v[62:63], v[62:63], v[82:83] op_sel_hi:[1,0]
	v_lshl_add_u64 v[122:123], v[50:51], 0, s[18:19]
	v_pk_mul_f32 v[60:61], v[60:61], v[54:55] op_sel_hi:[1,0]
	v_pk_mul_f32 v[34:35], v[34:35], v[54:55] op_sel_hi:[1,0]
	v_lshl_add_u64 v[124:125], v[50:51], 0, s[16:17]
	v_pk_mul_f32 v[8:9], v[8:9], v[54:55] op_sel_hi:[1,0]
	v_pk_mul_f32 v[6:7], v[6:7], v[54:55] op_sel_hi:[1,0]
	v_pk_mul_f32 v[32:33], v[32:33], v[54:55] op_sel_hi:[1,0]
	v_pk_mul_f32 v[30:31], v[30:31], v[54:55] op_sel_hi:[1,0]
	v_pk_mul_f32 v[16:17], v[16:17], v[114:115] op_sel_hi:[1,0]
	v_pk_mul_f32 v[14:15], v[14:15], v[114:115] op_sel_hi:[1,0]
	v_pk_mul_f32 v[20:21], v[20:21], v[114:115] op_sel_hi:[1,0]
	v_pk_mul_f32 v[18:19], v[18:19], v[114:115] op_sel_hi:[1,0]
	v_pk_mul_f32 v[4:5], v[4:5], v[82:83] op_sel_hi:[1,0]
	v_pk_mul_f32 v[2:3], v[2:3], v[82:83] op_sel_hi:[1,0]
	v_pk_mul_f32 v[12:13], v[12:13], v[88:89] op_sel_hi:[1,0]
	v_pk_mul_f32 v[10:11], v[10:11], v[88:89] op_sel_hi:[1,0]
	v_pk_mul_f32 v[24:25], v[24:25], v[88:89] op_sel_hi:[1,0]
	v_pk_mul_f32 v[22:23], v[22:23], v[88:89] op_sel_hi:[1,0]
	v_pk_mul_f32 v[28:29], v[28:29], v[82:83] op_sel_hi:[1,0]
	v_pk_mul_f32 v[26:27], v[26:27], v[82:83] op_sel_hi:[1,0]
	s_add_i32 s11, s11, s28
	s_add_i32 s8, s8, s29
	s_cmpk_lt_i32 s11, 0x2000
	s_waitcnt vmcnt(5)
	v_pk_add_f32 v[92:93], v[92:93], 1.0 op_sel_hi:[1,0]
	s_waitcnt vmcnt(4)
	v_pk_add_f32 v[96:97], v[96:97], 1.0 op_sel_hi:[1,0]
	v_pk_add_f32 v[94:95], v[94:95], 1.0 op_sel_hi:[1,0]
	v_pk_add_f32 v[90:91], v[90:91], 1.0 op_sel_hi:[1,0]
	s_waitcnt vmcnt(2)
	v_pk_mul_f32 v[96:97], v[104:105], v[96:97]
	v_pk_mul_f32 v[94:95], v[102:103], v[94:95]
	v_pk_mul_f32 v[92:93], v[100:101], v[92:93]
	v_pk_mul_f32 v[90:91], v[98:99], v[90:91]
	s_waitcnt vmcnt(1)
	v_pk_fma_f32 v[84:85], v[84:85], v[96:97], v[108:109]
	v_pk_fma_f32 v[86:87], v[86:87], v[94:95], v[106:107]
	s_waitcnt vmcnt(0)
	v_pk_fma_f32 v[98:99], v[118:119], v[92:93], v[112:113]
	v_pk_fma_f32 v[80:81], v[80:81], v[90:91], v[110:111]
	v_pk_fma_f32 v[72:73], v[72:73], v[96:97], v[108:109]
	v_pk_fma_f32 v[74:75], v[74:75], v[90:91], v[110:111]
	v_pk_fma_f32 v[64:65], v[96:97], v[64:65], v[108:109]
	v_pk_fma_f32 v[66:67], v[66:67], v[90:91], v[110:111]
	v_pk_fma_f32 v[96:97], v[96:97], v[56:57], v[108:109]
	v_pk_fma_f32 v[90:91], v[90:91], v[58:59], v[110:111]
	v_cvt_pk_bf16_f32 v56, v86, v87
	v_cvt_pk_bf16_f32 v57, v84, v85
	v_cvt_pk_bf16_f32 v58, v80, v81
	v_cvt_pk_bf16_f32 v59, v98, v99
	v_pk_fma_f32 v[76:77], v[76:77], v[94:95], v[106:107]
	v_pk_fma_f32 v[100:101], v[120:121], v[92:93], v[112:113]
	global_store_dwordx4 v[78:79], v[56:59], off nt
	v_pk_fma_f32 v[68:69], v[94:95], v[68:69], v[106:107]
	v_pk_fma_f32 v[62:63], v[62:63], v[92:93], v[112:113]
	v_cvt_pk_bf16_f32 v56, v76, v77
	v_cvt_pk_bf16_f32 v57, v72, v73
	v_cvt_pk_bf16_f32 v58, v74, v75
	v_cvt_pk_bf16_f32 v59, v100, v101
	global_store_dwordx4 v[70:71], v[56:59], off nt
	v_pk_fma_f32 v[60:61], v[94:95], v[60:61], v[106:107]
	v_pk_fma_f32 v[34:35], v[92:93], v[34:35], v[112:113]
	v_cvt_pk_bf16_f32 v56, v68, v69
	v_cvt_pk_bf16_f32 v57, v64, v65
	v_cvt_pk_bf16_f32 v58, v66, v67
	v_cvt_pk_bf16_f32 v59, v62, v63
	global_store_dwordx4 v[122:123], v[56:59], off nt
	s_nop 1
	v_cvt_pk_bf16_f32 v56, v60, v61
	v_cvt_pk_bf16_f32 v57, v96, v97
	v_cvt_pk_bf16_f32 v58, v90, v91
	v_cvt_pk_bf16_f32 v59, v34, v35
	global_store_dwordx4 v[124:125], v[56:59], off nt
	global_load_dwordx4 v[56:59], v135, s[0:1]
	s_nop 0
	global_load_dwordx4 v[60:63], v135, s[0:1] offset:16
	global_load_dwordx4 v[64:67], v[48:49], off
	global_load_dwordx4 v[72:75], v[48:49], off offset:16
	global_load_dwordx4 v[84:87], v[116:117], off offset:2048
	global_load_dwordx4 v[90:93], v[116:117], off offset:2064
	s_waitcnt vmcnt(5)
	v_pk_add_f32 v[34:35], v[58:59], 1.0 op_sel_hi:[1,0]
	v_pk_add_f32 v[54:55], v[56:57], 1.0 op_sel_hi:[1,0]
	s_waitcnt vmcnt(4)
	v_pk_add_f32 v[56:57], v[62:63], 1.0 op_sel_hi:[1,0]
	v_pk_add_f32 v[58:59], v[60:61], 1.0 op_sel_hi:[1,0]
	s_waitcnt vmcnt(3)
	v_pk_mul_f32 v[34:35], v[66:67], v[34:35]
	v_pk_mul_f32 v[54:55], v[64:65], v[54:55]
	s_waitcnt vmcnt(2)
	v_pk_mul_f32 v[56:57], v[74:75], v[56:57]
	v_pk_mul_f32 v[58:59], v[72:73], v[58:59]
	s_waitcnt vmcnt(1)
	v_pk_fma_f32 v[14:15], v[14:15], v[34:35], v[86:87]
	v_pk_fma_f32 v[16:17], v[16:17], v[54:55], v[84:85]
	s_waitcnt vmcnt(0)
	v_pk_fma_f32 v[18:19], v[18:19], v[56:57], v[92:93]
	v_pk_fma_f32 v[20:21], v[20:21], v[58:59], v[90:91]
	v_pk_fma_f32 v[60:61], v[2:3], v[34:35], v[86:87]
	v_pk_fma_f32 v[62:63], v[4:5], v[54:55], v[84:85]
	v_cvt_pk_bf16_f32 v2, v16, v17
	v_cvt_pk_bf16_f32 v3, v14, v15
	v_cvt_pk_bf16_f32 v4, v20, v21
	v_cvt_pk_bf16_f32 v5, v18, v19
	v_pk_fma_f32 v[10:11], v[10:11], v[34:35], v[86:87]
	v_pk_fma_f32 v[12:13], v[12:13], v[54:55], v[84:85]
	v_pk_fma_f32 v[22:23], v[22:23], v[56:57], v[92:93]
	v_pk_fma_f32 v[24:25], v[24:25], v[58:59], v[90:91]
	global_store_dwordx4 v[78:79], v[2:5], off offset:1024 nt
	v_pk_fma_f32 v[26:27], v[26:27], v[56:57], v[92:93]
	v_pk_fma_f32 v[28:29], v[28:29], v[58:59], v[90:91]
	v_cvt_pk_bf16_f32 v2, v12, v13
	v_cvt_pk_bf16_f32 v3, v10, v11
	v_cvt_pk_bf16_f32 v4, v24, v25
	v_cvt_pk_bf16_f32 v5, v22, v23
	global_store_dwordx4 v[70:71], v[2:5], off offset:1024 nt
	v_pk_fma_f32 v[6:7], v[6:7], v[34:35], v[86:87]
	v_pk_fma_f32 v[8:9], v[8:9], v[54:55], v[84:85]
	v_cvt_pk_bf16_f32 v2, v62, v63
	v_cvt_pk_bf16_f32 v3, v60, v61
	v_cvt_pk_bf16_f32 v4, v28, v29
	v_cvt_pk_bf16_f32 v5, v26, v27
	v_pk_fma_f32 v[30:31], v[30:31], v[56:57], v[92:93]
	v_pk_fma_f32 v[32:33], v[32:33], v[58:59], v[90:91]
	global_store_dwordx4 v[122:123], v[2:5], off offset:1024 nt
	s_nop 1
	v_cvt_pk_bf16_f32 v2, v8, v9
	v_cvt_pk_bf16_f32 v3, v6, v7
	v_cvt_pk_bf16_f32 v4, v32, v33
	v_cvt_pk_bf16_f32 v5, v30, v31
	global_store_dwordx4 v[124:125], v[2:5], off offset:1024 nt
	s_cbranch_scc1 .LBB0_1878

.LBB0_2190:
	s_ashr_i32 s3, s2, 31
	s_lshl_b64 s[0:1], s[2:3], 11
	v_lshl_add_u64 v[18:19], v[36:37], 0, s[0:1]
	v_add_co_u32_e32 v30, vcc, s22, v18
	s_add_i32 s10, s2, 1
	s_add_i32 s8, s2, 2
	s_add_i32 s6, s2, 3
	v_addc_co_u32_e32 v31, vcc, 0, v19, vcc
	s_ashr_i32 s11, s10, 31
	s_ashr_i32 s9, s8, 31
	s_ashr_i32 s7, s6, 31
	global_load_dwordx4 v[2:5], v[18:19], off
	global_load_dwordx4 v[6:9], v[18:19], off offset:1024
	global_load_dwordx4 v[10:13], v[18:19], off offset:2048
	global_load_dwordx4 v[14:17], v[18:19], off offset:3072
	s_nop 0
	global_load_dwordx4 v[18:21], v[30:31], off
	global_load_dwordx4 v[22:25], v[30:31], off offset:1024
	global_load_dwordx4 v[26:29], v[30:31], off offset:2048
	s_ashr_i32 s24, s5, 10
	s_lshl_b64 s[26:27], s[2:3], 6
	s_lshl_b64 s[16:17], s[10:11], 11
	s_lshl_b64 s[14:15], s[8:9], 11
	s_lshl_b64 s[12:13], s[6:7], 11
	s_add_u32 s26, s18, s26
	s_addc_u32 s27, s19, s27
	global_load_dwordx4 v[30:33], v[30:31], off offset:3072
	s_nop 0
	global_load_dwordx4 v[116:119], v35, s[26:27] offset:48
	global_load_dwordx4 v[120:123], v35, s[26:27] offset:32
	global_load_dwordx4 v[124:127], v35, s[26:27] offset:16
	global_load_dwordx4 v[128:131], v35, s[26:27]
	s_lshl_b64 s[28:29], s[10:11], 6
	s_add_u32 s26, s18, s28
	s_addc_u32 s27, s19, s29
	global_load_dwordx4 v[132:135], v35, s[26:27] offset:48
	global_load_dwordx4 v[136:139], v35, s[26:27] offset:32
	global_load_dwordx4 v[140:143], v35, s[26:27] offset:16
	global_load_dwordx4 v[144:147], v35, s[26:27]
	s_lshl_b64 s[26:27], s[8:9], 6
	s_add_u32 s26, s18, s26
	s_addc_u32 s27, s19, s27
	global_load_dwordx4 v[148:151], v35, s[26:27] offset:16
	global_load_dwordx4 v[152:155], v35, s[26:27]
	s_waitcnt vmcnt(0)
	v_lshlrev_b32_e32 v80, 16, v2
	v_and_b32_e32 v81, 0xffff0000, v2
	v_lshlrev_b32_e32 v84, 16, v3
	v_and_b32_e32 v85, 0xffff0000, v3
	v_lshl_add_u64 v[2:3], v[38:39], 0, s[0:1]
	v_lshlrev_b32_e32 v68, 16, v14
	v_and_b32_e32 v69, 0xffff0000, v14
	v_lshlrev_b32_e32 v70, 16, v15
	v_and_b32_e32 v71, 0xffff0000, v15
	v_lshlrev_b32_e32 v64, 16, v16
	v_and_b32_e32 v65, 0xffff0000, v16
	v_lshlrev_b32_e32 v66, 16, v17
	v_and_b32_e32 v67, 0xffff0000, v17
	v_lshlrev_b32_e32 v104, 16, v26
	v_and_b32_e32 v105, 0xffff0000, v26
	v_lshlrev_b32_e32 v108, 16, v27
	v_and_b32_e32 v109, 0xffff0000, v27
	v_lshlrev_b32_e32 v106, 16, v28
	v_and_b32_e32 v107, 0xffff0000, v28
	v_lshlrev_b32_e32 v110, 16, v29
	v_and_b32_e32 v111, 0xffff0000, v29
	global_load_dwordx4 v[26:29], v[2:3], off
	global_load_dwordx4 v[14:17], v[2:3], off offset:1024
	v_lshl_add_u64 v[2:3], v[38:39], 0, s[16:17]
	v_lshlrev_b32_e32 v88, 16, v10
	v_and_b32_e32 v89, 0xffff0000, v10
	v_lshlrev_b32_e32 v92, 16, v11
	v_and_b32_e32 v93, 0xffff0000, v11
	v_lshlrev_b32_e32 v90, 16, v12
	v_and_b32_e32 v91, 0xffff0000, v12
	v_lshlrev_b32_e32 v94, 16, v13
	v_and_b32_e32 v95, 0xffff0000, v13
	v_lshlrev_b32_e32 v60, 16, v22
	v_and_b32_e32 v61, 0xffff0000, v22
	v_lshlrev_b32_e32 v62, 16, v23
	v_and_b32_e32 v63, 0xffff0000, v23
	v_lshlrev_b32_e32 v56, 16, v24
	v_and_b32_e32 v57, 0xffff0000, v24
	v_lshlrev_b32_e32 v58, 16, v25
	v_and_b32_e32 v59, 0xffff0000, v25
	global_load_dwordx4 v[22:25], v[2:3], off
	global_load_dwordx4 v[10:13], v[2:3], off offset:1024
	v_lshl_add_u64 v[2:3], v[38:39], 0, s[14:15]
	s_lshl_b64 s[0:1], s[6:7], 6
	v_lshlrev_b32_e32 v82, 16, v4
	v_and_b32_e32 v83, 0xffff0000, v4
	v_lshlrev_b32_e32 v86, 16, v5
	v_and_b32_e32 v87, 0xffff0000, v5
	v_lshlrev_b32_e32 v96, 16, v18
	v_and_b32_e32 v97, 0xffff0000, v18
	v_lshlrev_b32_e32 v100, 16, v19
	v_and_b32_e32 v101, 0xffff0000, v19
	v_lshlrev_b32_e32 v98, 16, v20
	v_and_b32_e32 v99, 0xffff0000, v20
	v_lshlrev_b32_e32 v102, 16, v21
	v_and_b32_e32 v103, 0xffff0000, v21
	global_load_dwordx4 v[156:159], v35, s[26:27] offset:48
	global_load_dwordx4 v[160:163], v35, s[26:27] offset:32
	global_load_dwordx4 v[18:21], v[2:3], off
	s_nop 0
	global_load_dwordx4 v[2:5], v[2:3], off offset:1024
	s_add_u32 s0, s18, s0
	v_lshlrev_b32_e32 v76, 16, v6
	v_and_b32_e32 v77, 0xffff0000, v6
	v_lshlrev_b32_e32 v78, 16, v7
	v_and_b32_e32 v79, 0xffff0000, v7
	v_lshl_add_u64 v[6:7], v[38:39], 0, s[12:13]
	s_addc_u32 s1, s19, s1
	v_mov_b32_e32 v172, v129
	v_mov_b32_e32 v173, v130
	v_mov_b32_e32 v129, v131
	v_lshlrev_b32_e32 v72, 16, v8
	v_and_b32_e32 v73, 0xffff0000, v8
	v_lshlrev_b32_e32 v74, 16, v9
	v_and_b32_e32 v75, 0xffff0000, v9
	v_lshlrev_b32_e32 v52, 16, v30
	v_and_b32_e32 v53, 0xffff0000, v30
	v_lshlrev_b32_e32 v54, 16, v31
	v_and_b32_e32 v55, 0xffff0000, v31
	v_lshlrev_b32_e32 v48, 16, v32
	v_and_b32_e32 v49, 0xffff0000, v32
	v_lshlrev_b32_e32 v50, 16, v33
	v_and_b32_e32 v51, 0xffff0000, v33
	global_load_dwordx4 v[164:167], v35, s[0:1] offset:16
	global_load_dwordx4 v[168:171], v35, s[0:1]
	global_load_dwordx4 v[30:33], v[6:7], off
	s_nop 0
	global_load_dwordx4 v[6:9], v[6:7], off offset:1024
	v_pk_add_f32 v[128:129], v[172:173], v[128:129]
	v_mov_b32_e32 v178, v125
	v_pk_add_f32 v[176:177], v[128:129], v[128:129] op_sel:[0,1] op_sel_hi:[1,0]
	global_load_dwordx4 v[128:131], v35, s[0:1] offset:48
	global_load_dwordx4 v[172:175], v35, s[0:1] offset:32
	v_mov_b32_e32 v179, v126
	v_mov_b32_e32 v125, v127
	v_pk_add_f32 v[124:125], v[178:179], v[124:125]
	v_add_f32_e32 v120, v120, v121
	v_pk_add_f32 v[124:125], v[124:125], v[124:125] op_sel:[0,1] op_sel_hi:[1,0]
	v_add_f32_e32 v122, v122, v123
	v_mov_b32_e32 v177, v116
	v_mov_b32_e32 v125, v117
	v_mov_b32_e32 v121, v118
	v_mov_b32_e32 v123, v119
	v_pk_add_f32 v[116:117], v[176:177], v[124:125]
	v_pk_add_f32 v[118:119], v[120:121], v[122:123]
	v_mov_b32_e32 v120, v141
	v_pk_add_f32 v[116:117], v[116:117], v[118:119]
	v_mov_b32_e32 v118, v145
	v_mov_b32_e32 v119, v146
	v_mov_b32_e32 v145, v147
	v_mov_b32_e32 v121, v142
	v_mov_b32_e32 v141, v143
	v_pk_add_f32 v[118:119], v[118:119], v[144:145]
	v_pk_add_f32 v[120:121], v[120:121], v[140:141]
	v_pk_add_f32 v[118:119], v[118:119], v[118:119] op_sel:[0,1] op_sel_hi:[1,0]
	v_pk_add_f32 v[120:121], v[120:121], v[120:121] op_sel:[0,1] op_sel_hi:[1,0]
	v_add_f32_e32 v122, v136, v137
	v_add_f32_e32 v124, v138, v139
	v_mov_b32_e32 v119, v132
	v_mov_b32_e32 v121, v133
	v_mov_b32_e32 v123, v134
	v_mov_b32_e32 v125, v135
	v_pk_add_f32 v[118:119], v[118:119], v[120:121]
	v_pk_add_f32 v[120:121], v[122:123], v[124:125]
	s_waitcnt vmcnt(9)
	v_mov_b32_e32 v123, v159
	v_pk_add_f32 v[118:119], v[118:119], v[120:121]
	v_mov_b32_e32 v121, v116
	v_mov_b32_e32 v120, v118
	v_mov_b32_e32 v116, v119
	v_pk_add_f32 v[116:117], v[120:121], v[116:117]
	v_mov_b32_e32 v118, v149
	v_pk_fma_f32 v[116:117], v[116:117], s[4:5], v[46:47] op_sel_hi:[1,0,0]
	v_mov_b32_e32 v119, v150
	v_mul_f32_e32 v34, 0x4b800000, v117
	v_cmp_gt_f32_e32 vcc, s23, v117
	v_mul_f32_e32 v112, 0x4b800000, v116
	v_cmp_gt_f32_e64 s[0:1], s23, v116
	v_cndmask_b32_e32 v34, v117, v34, vcc
	v_mov_b32_e32 v117, v154
	v_cndmask_b32_e64 v112, v116, v112, s[0:1]
	v_mov_b32_e32 v116, v153
	v_mov_b32_e32 v153, v155
	v_mov_b32_e32 v149, v151
	v_pk_add_f32 v[116:117], v[116:117], v[152:153]
	v_pk_add_f32 v[118:119], v[118:119], v[148:149]
	v_pk_add_f32 v[116:117], v[116:117], v[116:117] op_sel:[0,1] op_sel_hi:[1,0]
	v_pk_add_f32 v[118:119], v[118:119], v[118:119] op_sel:[0,1] op_sel_hi:[1,0]
	s_waitcnt vmcnt(8)
	v_add_f32_e32 v120, v160, v161
	v_add_f32_e32 v122, v162, v163
	v_mov_b32_e32 v117, v156
	v_mov_b32_e32 v119, v157
	v_mov_b32_e32 v121, v158
	v_pk_add_f32 v[116:117], v[116:117], v[118:119]
	v_pk_add_f32 v[118:119], v[120:121], v[122:123]
	s_waitcnt vmcnt(5)
	v_mov_b32_e32 v120, v165
	v_pk_add_f32 v[116:117], v[116:117], v[118:119]
	s_waitcnt vmcnt(4)
	v_mov_b32_e32 v118, v169
	v_mov_b32_e32 v119, v170
	v_mov_b32_e32 v169, v171
	v_mov_b32_e32 v121, v166
	v_mov_b32_e32 v165, v167
	v_pk_add_f32 v[118:119], v[118:119], v[168:169]
	v_pk_add_f32 v[120:121], v[120:121], v[164:165]
	v_rsq_f32_e32 v34, v34
	v_pk_add_f32 v[118:119], v[118:119], v[118:119] op_sel:[0,1] op_sel_hi:[1,0]
	v_pk_add_f32 v[120:121], v[120:121], v[120:121] op_sel:[0,1] op_sel_hi:[1,0]
	s_waitcnt vmcnt(0)
	v_add_f32_e32 v122, v172, v173
	v_add_f32_e32 v124, v174, v175
	v_mov_b32_e32 v119, v128
	v_mov_b32_e32 v121, v129
	v_mov_b32_e32 v123, v130
	v_mov_b32_e32 v125, v131
	v_rsq_f32_e32 v112, v112
	v_pk_add_f32 v[118:119], v[118:119], v[120:121]
	v_pk_add_f32 v[120:121], v[122:123], v[124:125]
	v_mul_f32_e32 v114, 0x45800000, v34
	v_pk_add_f32 v[118:119], v[118:119], v[120:121]
	v_mov_b32_e32 v121, v116
	v_mov_b32_e32 v120, v118
	v_mov_b32_e32 v116, v119
	v_cndmask_b32_e32 v34, v34, v114, vcc
	v_pk_add_f32 v[116:117], v[120:121], v[116:117]
	v_mul_f32_e32 v114, 0.5, v34
	v_mul_f32_e32 v34, 0x45800000, v112
	v_pk_fma_f32 v[116:117], v[116:117], s[4:5], v[46:47] op_sel_hi:[1,0,0]
	v_cndmask_b32_e64 v34, v112, v34, s[0:1]
	v_mul_f32_e32 v112, 0x4b800000, v117
	v_cmp_gt_f32_e32 vcc, s23, v117
	v_cmp_gt_f32_e64 s[0:1], s23, v116
	v_mul_f32_e32 v34, 0.5, v34
	v_cndmask_b32_e32 v112, v117, v112, vcc
	v_rsq_f32_e32 v112, v112
	v_mul_f32_e32 v117, 0x4b800000, v116
	v_cndmask_b32_e64 v116, v116, v117, s[0:1]
	v_rsq_f32_e32 v117, v116
	v_mul_f32_e32 v116, 0x45800000, v112
	v_cndmask_b32_e32 v112, v112, v116, vcc
	v_mul_f32_e32 v116, 0.5, v112
	v_mul_f32_e32 v112, 0x45800000, v117
	v_cndmask_b32_e64 v112, v117, v112, s[0:1]
	v_mul_f32_e32 v112, 0.5, v112
	s_mul_i32 s0, s24, 9
	s_ashr_i32 s1, s0, 31
	s_lshl_b64 s[0:1], s[0:1], 12
	s_add_u32 s0, s68, s0
	s_addc_u32 s1, s69, s1
	s_add_u32 s0, s0, 0x8000
	s_addc_u32 s1, s1, 0
	global_load_dwordx4 v[118:121], v[40:41], off
	global_load_dwordx4 v[122:125], v113, s[0:1]
	global_load_dwordx4 v[126:129], v113, s[0:1] offset:16
	global_load_dwordx4 v[130:133], v[40:41], off offset:16
	global_load_dwordx4 v[134:137], v115, s[0:1]
	global_load_dwordx4 v[138:141], v[42:43], off
	global_load_dwordx4 v[142:145], v[42:43], off offset:16
	global_load_dwordx4 v[146:149], v115, s[0:1] offset:16
	v_lshlrev_b32_e32 v150, 16, v26
	v_and_b32_e32 v151, 0xffff0000, v26
	v_lshlrev_b32_e32 v152, 16, v28
	v_and_b32_e32 v153, 0xffff0000, v28
	v_lshlrev_b32_e32 v158, 16, v18
	v_and_b32_e32 v159, 0xffff0000, v18
	v_lshlrev_b32_e32 v18, 16, v19
	v_and_b32_e32 v19, 0xffff0000, v19
	v_lshlrev_b32_e32 v26, 16, v27
	v_and_b32_e32 v27, 0xffff0000, v27
	v_lshlrev_b32_e32 v154, 16, v22
	v_and_b32_e32 v155, 0xffff0000, v22
	v_lshlrev_b32_e32 v22, 16, v23
	v_and_b32_e32 v23, 0xffff0000, v23
	v_lshlrev_b32_e32 v160, 16, v20
	v_and_b32_e32 v161, 0xffff0000, v20
	v_lshlrev_b32_e32 v166, 16, v14
	v_and_b32_e32 v167, 0xffff0000, v14
	v_pk_mul_f32 v[150:151], v[114:115], v[150:151] op_sel_hi:[0,1]
	v_pk_mul_f32 v[152:153], v[114:115], v[152:153] op_sel_hi:[0,1]
	v_pk_mul_f32 v[158:159], v[116:117], v[158:159] op_sel_hi:[0,1]
	v_pk_mul_f32 v[172:173], v[116:117], v[18:19] op_sel_hi:[0,1]
	v_lshlrev_b32_e32 v14, 16, v15
	v_and_b32_e32 v15, 0xffff0000, v15
	v_lshlrev_b32_e32 v20, 16, v21
	v_and_b32_e32 v21, 0xffff0000, v21
	v_pk_mul_f32 v[26:27], v[114:115], v[26:27] op_sel_hi:[0,1]
	v_pk_mul_f32 v[168:169], v[34:35], v[22:23] op_sel_hi:[0,1]
	v_pk_mul_f32 v[160:161], v[116:117], v[160:161] op_sel_hi:[0,1]
	v_pk_mul_f32 v[14:15], v[114:115], v[14:15] op_sel_hi:[0,1]
	v_pk_mul_f32 v[174:175], v[116:117], v[20:21] op_sel_hi:[0,1]
	v_lshlrev_b32_e32 v28, 16, v29
	v_and_b32_e32 v29, 0xffff0000, v29
	s_lshl_b64 s[0:1], s[2:3], 12
	v_lshlrev_b32_e32 v156, 16, v24
	v_and_b32_e32 v157, 0xffff0000, v24
	v_lshlrev_b32_e32 v24, 16, v25
	v_and_b32_e32 v25, 0xffff0000, v25
	v_pk_mul_f32 v[28:29], v[114:115], v[28:29] op_sel_hi:[0,1]
	v_pk_mul_f32 v[154:155], v[34:35], v[154:155] op_sel_hi:[0,1]
	v_lshlrev_b32_e32 v162, 16, v30
	v_and_b32_e32 v163, 0xffff0000, v30
	v_lshlrev_b32_e32 v30, 16, v31
	v_and_b32_e32 v31, 0xffff0000, v31
	v_lshlrev_b32_e32 v164, 16, v32
	v_and_b32_e32 v165, 0xffff0000, v32
	v_lshlrev_b32_e32 v32, 16, v33
	v_and_b32_e32 v33, 0xffff0000, v33
	v_pk_mul_f32 v[156:157], v[34:35], v[156:157] op_sel_hi:[0,1]
	v_pk_mul_f32 v[170:171], v[34:35], v[24:25] op_sel_hi:[0,1]
	v_pk_mul_f32 v[162:163], v[112:113], v[162:163] op_sel_hi:[0,1]
	v_pk_mul_f32 v[176:177], v[112:113], v[30:31] op_sel_hi:[0,1]
	v_pk_mul_f32 v[178:179], v[112:113], v[32:33] op_sel_hi:[0,1]
	v_pk_mul_f32 v[164:165], v[112:113], v[164:165] op_sel_hi:[0,1]
	s_waitcnt vmcnt(6)
	v_pk_mul_f32 v[120:121], v[124:125], v[120:121]
	v_pk_mul_f32 v[118:119], v[122:123], v[118:119]
	s_waitcnt vmcnt(4)
	v_pk_mul_f32 v[124:125], v[126:127], v[130:131]
	v_pk_mul_f32 v[122:123], v[128:129], v[132:133]
	s_waitcnt vmcnt(2)
	v_pk_mul_f32 v[126:127], v[136:137], v[140:141]
	v_pk_mul_f32 v[128:129], v[134:135], v[138:139]
	v_pk_fma_f32 v[18:19], v[150:151], v[118:119], v[80:81]
	v_pk_fma_f32 v[22:23], v[152:153], v[124:125], v[82:83]
	v_pk_fma_f32 v[82:83], v[120:121], v[172:173], v[100:101]
	v_pk_fma_f32 v[80:81], v[118:119], v[158:159], v[96:97]
	v_lshlrev_b32_e32 v96, 16, v16
	v_and_b32_e32 v97, 0xffff0000, v16
	v_pk_mul_f32 v[100:101], v[114:115], v[166:167] op_sel_hi:[0,1]
	s_waitcnt vmcnt(0)
	v_pk_mul_f32 v[132:133], v[146:147], v[142:143]
	v_pk_fma_f32 v[20:21], v[26:27], v[120:121], v[84:85]
	v_pk_fma_f32 v[84:85], v[124:125], v[160:161], v[98:99]
	v_lshlrev_b32_e32 v98, 16, v17
	v_and_b32_e32 v99, 0xffff0000, v17
	v_pk_fma_f32 v[16:17], v[14:15], v[126:127], v[78:79]
	v_pk_fma_f32 v[14:15], v[100:101], v[128:129], v[76:77]
	v_pk_mul_f32 v[76:77], v[114:115], v[96:97] op_sel_hi:[0,1]
	v_pk_mul_f32 v[130:131], v[148:149], v[144:145]
	v_pk_mul_f32 v[78:79], v[114:115], v[98:99] op_sel_hi:[0,1]
	v_pk_fma_f32 v[72:73], v[76:77], v[132:133], v[72:73]
	v_lshlrev_b32_e32 v76, 16, v10
	v_and_b32_e32 v77, 0xffff0000, v10
	v_lshlrev_b32_e32 v10, 16, v11
	v_and_b32_e32 v11, 0xffff0000, v11
	v_pk_fma_f32 v[74:75], v[78:79], v[130:131], v[74:75]
	v_lshlrev_b32_e32 v78, 16, v12
	v_and_b32_e32 v79, 0xffff0000, v12
	v_pk_mul_f32 v[76:77], v[34:35], v[76:77] op_sel_hi:[0,1]
	v_pk_mul_f32 v[10:11], v[34:35], v[10:11] op_sel_hi:[0,1]
	v_lshlrev_b32_e32 v96, 16, v13
	v_and_b32_e32 v97, 0xffff0000, v13
	v_pk_fma_f32 v[12:13], v[10:11], v[126:127], v[70:71]
	v_pk_fma_f32 v[10:11], v[76:77], v[128:129], v[68:69]
	v_pk_mul_f32 v[68:69], v[34:35], v[78:79] op_sel_hi:[0,1]
	v_pk_mul_f32 v[70:71], v[34:35], v[96:97] op_sel_hi:[0,1]
	v_pk_fma_f32 v[64:65], v[68:69], v[132:133], v[64:65]
	v_lshlrev_b32_e32 v68, 16, v2
	v_and_b32_e32 v69, 0xffff0000, v2
	v_lshlrev_b32_e32 v2, 16, v3
	v_and_b32_e32 v3, 0xffff0000, v3
	v_pk_fma_f32 v[66:67], v[70:71], v[130:131], v[66:67]
	v_lshlrev_b32_e32 v70, 16, v4
	v_and_b32_e32 v71, 0xffff0000, v4
	v_pk_mul_f32 v[68:69], v[116:117], v[68:69] op_sel_hi:[0,1]
	v_pk_mul_f32 v[2:3], v[116:117], v[2:3] op_sel_hi:[0,1]
	v_lshlrev_b32_e32 v76, 16, v5
	v_and_b32_e32 v77, 0xffff0000, v5
	v_pk_fma_f32 v[4:5], v[126:127], v[2:3], v[62:63]
	v_pk_fma_f32 v[2:3], v[128:129], v[68:69], v[60:61]
	v_pk_mul_f32 v[60:61], v[116:117], v[70:71] op_sel_hi:[0,1]
	v_pk_mul_f32 v[62:63], v[116:117], v[76:77] op_sel_hi:[0,1]
	v_pk_fma_f32 v[56:57], v[132:133], v[60:61], v[56:57]
	v_lshlrev_b32_e32 v60, 16, v6
	v_and_b32_e32 v61, 0xffff0000, v6
	v_lshlrev_b32_e32 v6, 16, v7
	v_and_b32_e32 v7, 0xffff0000, v7
	v_pk_fma_f32 v[58:59], v[130:131], v[62:63], v[58:59]
	v_lshlrev_b32_e32 v62, 16, v8
	v_and_b32_e32 v63, 0xffff0000, v8
	v_pk_mul_f32 v[60:61], v[112:113], v[60:61] op_sel_hi:[0,1]
	v_pk_mul_f32 v[6:7], v[112:113], v[6:7] op_sel_hi:[0,1]
	v_lshlrev_b32_e32 v68, 16, v9
	v_and_b32_e32 v69, 0xffff0000, v9
	v_pk_fma_f32 v[8:9], v[126:127], v[6:7], v[54:55]
	v_pk_fma_f32 v[6:7], v[128:129], v[60:61], v[52:53]
	v_pk_mul_f32 v[52:53], v[112:113], v[62:63] op_sel_hi:[0,1]
	v_pk_fma_f32 v[48:49], v[132:133], v[52:53], v[48:49]
	v_lshl_add_u64 v[52:53], v[44:45], 0, s[0:1]
	s_lshl_b64 s[0:1], s[10:11], 12
	v_pk_fma_f32 v[24:25], v[28:29], v[122:123], v[86:87]
	v_pk_fma_f32 v[28:29], v[120:121], v[168:169], v[92:93]
	v_pk_fma_f32 v[26:27], v[118:119], v[154:155], v[88:89]
	global_store_dwordx4 v[52:53], v[18:21], off nt
	global_store_dwordx4 v[52:53], v[22:25], off offset:16 nt
	global_store_dwordx4 v[52:53], v[14:17], off offset:2048 nt
	global_store_dwordx4 v[52:53], v[72:75], off offset:2064 nt
	v_pk_fma_f32 v[32:33], v[122:123], v[170:171], v[94:95]
	v_lshl_add_u64 v[14:15], v[44:45], 0, s[0:1]
	s_lshl_b64 s[0:1], s[8:9], 12
	v_pk_fma_f32 v[30:31], v[124:125], v[156:157], v[90:91]
	global_store_dwordx4 v[14:15], v[26:29], off nt
	global_store_dwordx4 v[14:15], v[30:33], off offset:16 nt
	global_store_dwordx4 v[14:15], v[10:13], off offset:2048 nt
	global_store_dwordx4 v[14:15], v[64:67], off offset:2064 nt
	v_pk_fma_f32 v[86:87], v[122:123], v[174:175], v[102:103]
	v_lshl_add_u64 v[10:11], v[44:45], 0, s[0:1]
	s_lshl_b64 s[0:1], s[6:7], 12
	v_pk_fma_f32 v[90:91], v[120:121], v[176:177], v[108:109]
	v_pk_fma_f32 v[88:89], v[118:119], v[162:163], v[104:105]
	v_pk_mul_f32 v[54:55], v[112:113], v[68:69] op_sel_hi:[0,1]
	global_store_dwordx4 v[10:11], v[80:83], off nt
	global_store_dwordx4 v[10:11], v[84:87], off offset:16 nt
	global_store_dwordx4 v[10:11], v[2:5], off offset:2048 nt
	global_store_dwordx4 v[10:11], v[56:59], off offset:2064 nt
	v_pk_fma_f32 v[94:95], v[122:123], v[178:179], v[110:111]
	v_lshl_add_u64 v[2:3], v[44:45], 0, s[0:1]
	v_pk_fma_f32 v[92:93], v[124:125], v[164:165], v[106:107]
	v_pk_fma_f32 v[50:51], v[130:131], v[54:55], v[50:51]
	global_store_dwordx4 v[2:3], v[88:91], off nt
	global_store_dwordx4 v[2:3], v[92:95], off offset:16 nt
	global_store_dwordx4 v[2:3], v[6:9], off offset:2048 nt
	global_store_dwordx4 v[2:3], v[48:51], off offset:2064 nt
	s_add_i32 s5, s5, s20
	s_add_i32 s2, s2, s21
	s_cmpk_lt_i32 s5, 0x2000
	s_cbranch_scc1 .LBB0_2190
